# pairing + peel + epilogue edits, early barrier with 2-MFMA tail
# speedup vs baseline: 1.0106x; 1.0106x over previous
;     __device__ bool next(int i, Unit& u) const { if (i >= 2) return false; const int x = c & 7, j = c >> 3; u.pm = 32 * i + 4 * x + (j & 3); u.pn = j >> 2; return true; }
; #define PG8_STAGE(bufoff, gbase, voff) do { _Pragma("unroll") for (int _i = 0; _i < 2; ++_i) \
;         __builtin_amdgcn_global_load_lds((const unsigned*)((const char*)(gbase) + (voff)[_i]), (LAS unsigned*)(lds + (bufoff) + ldsw + _i * 8192), 16, 0, 0); } while (0)
; #define PG8_LDA(dst, b, h) do { _Pragma("unroll") for (int m = 0; m < 4; ++m) _Pragma("unroll") for (int k = 0; k < 2; ++k) dst[m][k] = *(const LAS bf16x8*)(lds + PG8_SA(b, h) + aoff + m * 2048 + k * 1024); } while (0)
; #define PG8_LDB(dst, b, h) do { _Pragma("unroll") for (int n = 0; n < 2; ++n) _Pragma("unroll") for (int k = 0; k < 2; ++k) dst[n][k] = *(const LAS bf16x8*)(lds + PG8_SB(b, h) + boff + n * 2048 + k * 1024); } while (0)
; #define PG8_WAIT_V(n) asm volatile("s_waitcnt vmcnt(" #n ")" ::: "memory")
; #define PG8_WAIT_L(n) asm volatile("s_waitcnt lgkmcnt(" #n ")" ::: "memory")
; #define PG8_BAR __builtin_amdgcn_s_barrier()
; #define PG8_SCHED __builtin_amdgcn_sched_barrier(0)
; template <class Epi, class Sched, bool ALIGN_EPI = true>
; __device__ __forceinline__ void gemm_phase(LAS unsigned char* lds, const Gemm g, const Sched& S, const Epi& E) {
;     ...
;         const bool has_next = S.next(ui + 1, nxt);
;         const char* nA = has_next ? (const char*)g.A + ((size_t)nxt.pm * BM * g.lda + (size_t)nxt.pn * g.a_pn_off) * 2 : cA; const char* nB = has_next ? (const char*)g.Bt + (size_t)nxt.pn * BM * g.ldb * 2 : cB;
;         for (int t = 0; t < nt; t += 2) {
;             const bool last = (t == nt - 2);
;             const char* a1 = cA + (size_t)(t + 1) * kstep;
;             const char* a2 = last ? nA : cA + (size_t)(t + 2) * kstep; const char* b2 = last ? nB : cB + (size_t)(t + 2) * kstep;
;             const char* a3 = a2 + kstep; const char* b3 = b2 + kstep;
;             PG8_LDB(B0, 0, 0); PG8_LDB(B1, 0, 1); PG8_SCHED; PG8_LDA(At, 0, 0); PG8_STAGE(PG8_SA(1, 1), a1 + hA, voffA);
;             PG8_WAIT_V(8); PG8_WAIT_L(0); PG8_BAR; PG8_MMA(0, 0, At, B0); PG8_MMA(0, 1, At, B1); PG8_BAR; PG8_SCHED;
;             PG8_LDA(At, 0, 1); PG8_STAGE(PG8_SB(0, 0), b2, voffB); PG8_STAGE(PG8_SB(0, 1), b2 + hB, voffB); PG8_STAGE(PG8_SA(0, 0), a2, voffA);
.LBB0_76:
	s_ashr_i32 s15, s14, 31
	s_lshl_b64 s[18:19], s[14:15], 20
	s_add_u32 s38, s46, s18
	s_addc_u32 s39, s47, s19
	s_and_b64 s[18:19], s[4:5], exec
	s_cselect_b32 s15, s39, s7
	s_cselect_b32 s17, s38, s6
	s_ashr_i32 s13, s12, 31
	s_lshl_b64 s[18:19], s[12:13], 20
	s_add_u32 s40, s53, s18
	s_addc_u32 s41, s58, s19
	s_and_b64 s[18:19], s[4:5], exec
	s_cselect_b32 s13, s41, s43
	s_cselect_b32 s18, s40, s42
	s_add_u32 s6, s6, 0x80080
	s_addc_u32 s7, s7, 0
	s_add_u32 s19, s42, 0x100
	s_addc_u32 s24, s43, 0
	s_mov_b32 s25, -2
	s_add_u32 s26, s6, 0xfff80080
	s_addc_u32 s27, s7, -1
	s_add_i32 s30, 0, 0x10000
	s_cmp_eq_u32 s25, 28
	s_cselect_b32 s45, s15, s27
	s_cselect_b32 s44, s17, s26
	s_cselect_b32 s43, s13, s24
	s_cselect_b32 s42, s18, s19
	s_add_i32 s31, 0, 0x14000
	v_add_u32_e32 v144, s30, v166
	v_add_u32_e32 v156, s31, v166
	ds_read_b128 v[132:135], v144
	ds_read_b128 v[136:139], v144 offset:1024
	ds_read_b128 v[140:143], v144 offset:2048
	ds_read_b128 v[144:147], v144 offset:3072
	ds_read_b128 v[170:173], v156
	ds_read_b128 v[174:177], v156 offset:1024
	ds_read_b128 v[178:181], v156 offset:2048
	ds_read_b128 v[182:185], v156 offset:3072
	v_lshl_add_u64 v[156:157], s[6:7], 0, v[152:153]
	s_add_i32 m0, s60, 0xc000
	ds_read_b128 v[186:189], v168
	ds_read_b128 v[190:193], v168 offset:1024
	ds_read_b128 v[194:197], v168 offset:2048
	ds_read_b128 v[204:207], v168 offset:3072
	ds_read_b128 v[208:211], v168 offset:4096
	ds_read_b128 v[212:215], v168 offset:5120
	ds_read_b128 v[216:219], v168 offset:6144
	ds_read_b128 v[220:223], v168 offset:7168
	global_load_lds_dwordx4 v[156:157], off
	v_lshl_add_u64 v[156:157], s[6:7], 0, v[154:155]
	s_add_i32 m0, s60, 0xe000
	s_nop 0
	global_load_lds_dwordx4 v[156:157], off
	s_waitcnt vmcnt(8)
	s_waitcnt lgkmcnt(0)
	s_barrier
	s_setprio 1
	s_waitcnt lgkmcnt(0)
	v_mfma_f32_16x16x32_bf16 v[128:131], v[132:135], v[186:189], 0
	v_mfma_f32_16x16x32_bf16 v[128:131], v[136:139], v[190:193], v[128:131]
	v_mfma_f32_16x16x32_bf16 v[124:127], v[140:143], v[186:189], 0
	v_mfma_f32_16x16x32_bf16 v[124:127], v[144:147], v[190:193], v[124:127]
	v_mfma_f32_16x16x32_bf16 v[116:119], v[132:135], v[194:197], 0
	v_mfma_f32_16x16x32_bf16 v[116:119], v[136:139], v[204:207], v[116:119]
	v_mfma_f32_16x16x32_bf16 v[112:115], v[140:143], v[194:197], 0
	v_mfma_f32_16x16x32_bf16 v[112:115], v[144:147], v[204:207], v[112:115]
	v_mfma_f32_16x16x32_bf16 v[104:107], v[132:135], v[208:211], 0
	v_mfma_f32_16x16x32_bf16 v[104:107], v[136:139], v[212:215], v[104:107]
	v_mfma_f32_16x16x32_bf16 v[96:99], v[140:143], v[208:211], 0
	v_mfma_f32_16x16x32_bf16 v[96:99], v[144:147], v[212:215], v[96:99]
	v_mfma_f32_16x16x32_bf16 v[88:91], v[132:135], v[216:219], 0
	v_mfma_f32_16x16x32_bf16 v[88:91], v[136:139], v[220:223], v[88:91]
	v_mfma_f32_16x16x32_bf16 v[80:83], v[140:143], v[216:219], 0
	v_mfma_f32_16x16x32_bf16 v[80:83], v[144:147], v[220:223], v[80:83]
	s_setprio 0
	s_setprio 1
	v_mfma_f32_16x16x32_bf16 v[120:123], v[170:173], v[186:189], 0
	v_mfma_f32_16x16x32_bf16 v[120:123], v[174:177], v[190:193], v[120:123]
	v_mfma_f32_16x16x32_bf16 v[108:111], v[178:181], v[186:189], 0
	v_mfma_f32_16x16x32_bf16 v[108:111], v[182:185], v[190:193], v[108:111]
	v_mfma_f32_16x16x32_bf16 v[100:103], v[170:173], v[194:197], 0
	v_mfma_f32_16x16x32_bf16 v[100:103], v[174:177], v[204:207], v[100:103]
	v_mfma_f32_16x16x32_bf16 v[92:95], v[178:181], v[194:197], 0
	v_mfma_f32_16x16x32_bf16 v[92:95], v[182:185], v[204:207], v[92:95]
	v_mfma_f32_16x16x32_bf16 v[84:87], v[170:173], v[208:211], 0
	v_mfma_f32_16x16x32_bf16 v[84:87], v[174:177], v[212:215], v[84:87]
	v_mfma_f32_16x16x32_bf16 v[76:79], v[178:181], v[208:211], 0
	v_mfma_f32_16x16x32_bf16 v[76:79], v[182:185], v[212:215], v[76:79]
	v_mfma_f32_16x16x32_bf16 v[72:75], v[170:173], v[216:219], 0
	v_mfma_f32_16x16x32_bf16 v[72:75], v[174:177], v[220:223], v[72:75]
	s_setprio 2
	s_barrier
	v_mfma_f32_16x16x32_bf16 v[68:71], v[178:181], v[216:219], 0
	v_mfma_f32_16x16x32_bf16 v[68:71], v[182:185], v[220:223], v[68:71]
	s_setprio 0
	s_add_i32 s26, s30, s59
	v_lshl_add_u64 v[156:157], s[42:43], 0, v[2:3]
	s_mov_b32 m0, s26
	ds_read_b128 v[186:189], v168 offset:16384
	ds_read_b128 v[190:193], v168 offset:17408
	ds_read_b128 v[194:197], v168 offset:18432
	ds_read_b128 v[204:207], v168 offset:19456
	ds_read_b128 v[208:211], v168 offset:20480
	ds_read_b128 v[212:215], v168 offset:21504
	ds_read_b128 v[216:219], v168 offset:22528
	ds_read_b128 v[220:223], v168 offset:23552
	global_load_lds_dwordx4 v[156:157], off
	s_add_i32 m0, s26, 0x2000
	s_add_u32 s26, s42, 0x80000
	v_lshl_add_u64 v[164:165], s[42:43], 0, v[0:1]
	s_addc_u32 s27, s43, 0
	s_add_i32 s30, s31, s59
	global_load_lds_dwordx4 v[164:165], off
	v_lshl_add_u64 v[224:225], s[26:27], 0, v[2:3]
	s_mov_b32 m0, s30
	v_lshl_add_u64 v[226:227], s[44:45], 0, v[148:149]
	global_load_lds_dwordx4 v[224:225], off
	v_lshl_add_u64 v[224:225], s[26:27], 0, v[0:1]
	s_add_i32 m0, s30, 0x2000
	s_nop 0
	global_load_lds_dwordx4 v[224:225], off
	v_lshl_add_u64 v[224:225], s[44:45], 0, v[150:151]
	s_mov_b32 m0, s60
	s_nop 0
	global_load_lds_dwordx4 v[224:225], off
	s_mov_b32 m0, s61
	s_nop 0
	global_load_lds_dwordx4 v[226:227], off
	s_waitcnt vmcnt(8)
	s_waitcnt lgkmcnt(0)
	s_barrier
; #define PG8_STAGE(bufoff, gbase, voff) do { _Pragma("unroll") for (int _i = 0; _i < 2; ++_i) \
;         __builtin_amdgcn_global_load_lds((const unsigned*)((const char*)(gbase) + (voff)[_i]), (LAS unsigned*)(lds + (bufoff) + ldsw + _i * 8192), 16, 0, 0); } while (0)
; #define PG8_LDA(dst, b, h) do { _Pragma("unroll") for (int m = 0; m < 4; ++m) _Pragma("unroll") for (int k = 0; k < 2; ++k) dst[m][k] = *(const LAS bf16x8*)(lds + PG8_SA(b, h) + aoff + m * 2048 + k * 1024); } while (0)
; #define PG8_LDB(dst, b, h) do { _Pragma("unroll") for (int n = 0; n < 2; ++n) _Pragma("unroll") for (int k = 0; k < 2; ++k) dst[n][k] = *(const LAS bf16x8*)(lds + PG8_SB(b, h) + boff + n * 2048 + k * 1024); } while (0)
; #define PG8_MMA(ai, bj, At, Bt) do { __builtin_amdgcn_s_setprio(1); _Pragma("unroll") for (int m = 0; m < 4; ++m) _Pragma("unroll") for (int n = 0; n < 2; ++n) _Pragma("unroll") for (int k = 0; k < 2; ++k) \
;         acc[ai][bj][m][n] = __builtin_amdgcn_mfma_f32_16x16x32_bf16(Bt[n][k], At[m][k], acc[ai][bj][m][n], 0, 0, 0); __builtin_amdgcn_s_setprio(0); } while (0)
; #define PG8_WAIT_V(n) asm volatile("s_waitcnt vmcnt(" #n ")" ::: "memory")
; #define PG8_WAIT_L(n) asm volatile("s_waitcnt lgkmcnt(" #n ")" ::: "memory")
; #define PG8_BAR __builtin_amdgcn_s_barrier()
; #define PG8_SCHED __builtin_amdgcn_sched_barrier(0)
; template <class Epi, class Sched, bool ALIGN_EPI = true>
; __device__ __forceinline__ void gemm_phase(LAS unsigned char* lds, const Gemm g, const Sched& S, const Epi& E) {
;     ...
;             PG8_WAIT_V(8); PG8_WAIT_L(0); PG8_BAR; PG8_MMA(1, 0, At, B0); PG8_MMA(1, 1, At, B1); PG8_BAR; PG8_SCHED;
;             PG8_LDB(B0, 1, 0); PG8_LDB(B1, 1, 1); PG8_SCHED; PG8_LDA(At, 1, 0); PG8_STAGE(PG8_SA(0, 1), a2 + hA, voffA);
;             PG8_WAIT_V(8); PG8_WAIT_L(0); PG8_BAR; PG8_MMA(0, 0, At, B0); PG8_MMA(0, 1, At, B1); PG8_BAR; PG8_SCHED;
	s_setprio 1
	s_waitcnt lgkmcnt(0)
	v_mfma_f32_16x16x32_bf16 v[64:67], v[132:135], v[186:189], 0
	v_mfma_f32_16x16x32_bf16 v[64:67], v[136:139], v[190:193], v[64:67]
	v_mfma_f32_16x16x32_bf16 v[60:63], v[140:143], v[186:189], 0
	v_mfma_f32_16x16x32_bf16 v[60:63], v[144:147], v[190:193], v[60:63]
	v_mfma_f32_16x16x32_bf16 v[56:59], v[132:135], v[194:197], 0
	v_mfma_f32_16x16x32_bf16 v[56:59], v[136:139], v[204:207], v[56:59]
	v_mfma_f32_16x16x32_bf16 v[48:51], v[140:143], v[194:197], 0
	v_mfma_f32_16x16x32_bf16 v[48:51], v[144:147], v[204:207], v[48:51]
	v_mfma_f32_16x16x32_bf16 v[40:43], v[132:135], v[208:211], 0
	v_mfma_f32_16x16x32_bf16 v[40:43], v[136:139], v[212:215], v[40:43]
	v_mfma_f32_16x16x32_bf16 v[32:35], v[140:143], v[208:211], 0
	v_mfma_f32_16x16x32_bf16 v[32:35], v[144:147], v[212:215], v[32:35]
	v_mfma_f32_16x16x32_bf16 v[24:27], v[132:135], v[216:219], 0
	v_mfma_f32_16x16x32_bf16 v[24:27], v[136:139], v[220:223], v[24:27]
	v_mfma_f32_16x16x32_bf16 v[16:19], v[140:143], v[216:219], 0
	v_mfma_f32_16x16x32_bf16 v[16:19], v[144:147], v[220:223], v[16:19]
	s_setprio 0
	s_setprio 1
	v_mfma_f32_16x16x32_bf16 v[52:55], v[170:173], v[186:189], 0
	v_mfma_f32_16x16x32_bf16 v[52:55], v[174:177], v[190:193], v[52:55]
	v_mfma_f32_16x16x32_bf16 v[44:47], v[178:181], v[186:189], 0
	v_mfma_f32_16x16x32_bf16 v[44:47], v[182:185], v[190:193], v[44:47]
	v_mfma_f32_16x16x32_bf16 v[36:39], v[170:173], v[194:197], 0
	v_mfma_f32_16x16x32_bf16 v[36:39], v[174:177], v[204:207], v[36:39]
	v_mfma_f32_16x16x32_bf16 v[28:31], v[178:181], v[194:197], 0
	v_mfma_f32_16x16x32_bf16 v[28:31], v[182:185], v[204:207], v[28:31]
	v_mfma_f32_16x16x32_bf16 v[20:23], v[170:173], v[208:211], 0
	v_mfma_f32_16x16x32_bf16 v[20:23], v[174:177], v[212:215], v[20:23]
	v_mfma_f32_16x16x32_bf16 v[12:15], v[178:181], v[208:211], 0
	v_mfma_f32_16x16x32_bf16 v[12:15], v[182:185], v[212:215], v[12:15]
	v_mfma_f32_16x16x32_bf16 v[8:11], v[170:173], v[216:219], 0
	v_mfma_f32_16x16x32_bf16 v[8:11], v[174:177], v[220:223], v[8:11]
	s_setprio 2
	s_barrier
	v_mfma_f32_16x16x32_bf16 v[4:7], v[178:181], v[216:219], 0
	v_mfma_f32_16x16x32_bf16 v[4:7], v[182:185], v[220:223], v[4:7]
	s_setprio 0
	s_add_i32 s30, 0, 0x18000
	s_add_i32 s31, 0, 0x1c000
	v_add_u32_e32 v144, s30, v166
	v_add_u32_e32 v160, s31, v166
	ds_read_b128 v[132:135], v144
	ds_read_b128 v[136:139], v144 offset:1024
	ds_read_b128 v[140:143], v144 offset:2048
	ds_read_b128 v[144:147], v144 offset:3072
	ds_read_b128 v[170:173], v160
	ds_read_b128 v[174:177], v160 offset:1024
	ds_read_b128 v[178:181], v160 offset:2048
	ds_read_b128 v[182:185], v160 offset:3072
	s_add_u32 s26, s44, 0x80000
	s_addc_u32 s27, s45, 0
	s_mov_b32 m0, s62
	v_lshl_add_u64 v[228:229], s[26:27], 0, v[150:151]
	ds_read_b128 v[186:189], v168 offset:32768
	ds_read_b128 v[190:193], v168 offset:33792
	ds_read_b128 v[194:197], v168 offset:34816
	ds_read_b128 v[204:207], v168 offset:35840
	ds_read_b128 v[208:211], v168 offset:36864
	ds_read_b128 v[212:215], v168 offset:37888
	ds_read_b128 v[216:219], v168 offset:38912
	ds_read_b128 v[220:223], v168 offset:39936
	global_load_lds_dwordx4 v[228:229], off
	v_lshl_add_u64 v[228:229], s[26:27], 0, v[148:149]
	s_mov_b32 m0, s63
	s_nop 0
	global_load_lds_dwordx4 v[228:229], off
	s_waitcnt vmcnt(8)
	s_waitcnt lgkmcnt(0)
	s_barrier
	s_setprio 1
	s_waitcnt lgkmcnt(0)
	v_mfma_f32_16x16x32_bf16 v[128:131], v[132:135], v[186:189], v[128:131]
	v_mfma_f32_16x16x32_bf16 v[128:131], v[136:139], v[190:193], v[128:131]
	v_mfma_f32_16x16x32_bf16 v[124:127], v[140:143], v[186:189], v[124:127]
	v_mfma_f32_16x16x32_bf16 v[124:127], v[144:147], v[190:193], v[124:127]
	v_mfma_f32_16x16x32_bf16 v[116:119], v[132:135], v[194:197], v[116:119]
	v_mfma_f32_16x16x32_bf16 v[116:119], v[136:139], v[204:207], v[116:119]
	v_mfma_f32_16x16x32_bf16 v[112:115], v[140:143], v[194:197], v[112:115]
	v_mfma_f32_16x16x32_bf16 v[112:115], v[144:147], v[204:207], v[112:115]
	v_mfma_f32_16x16x32_bf16 v[104:107], v[132:135], v[208:211], v[104:107]
	v_mfma_f32_16x16x32_bf16 v[104:107], v[136:139], v[212:215], v[104:107]
	v_mfma_f32_16x16x32_bf16 v[96:99], v[140:143], v[208:211], v[96:99]
	v_mfma_f32_16x16x32_bf16 v[96:99], v[144:147], v[212:215], v[96:99]
	v_mfma_f32_16x16x32_bf16 v[88:91], v[132:135], v[216:219], v[88:91]
	v_mfma_f32_16x16x32_bf16 v[88:91], v[136:139], v[220:223], v[88:91]
	v_mfma_f32_16x16x32_bf16 v[80:83], v[140:143], v[216:219], v[80:83]
	v_mfma_f32_16x16x32_bf16 v[80:83], v[144:147], v[220:223], v[80:83]
	s_setprio 0
	s_setprio 1
	v_mfma_f32_16x16x32_bf16 v[120:123], v[170:173], v[186:189], v[120:123]
	v_mfma_f32_16x16x32_bf16 v[120:123], v[174:177], v[190:193], v[120:123]
	v_mfma_f32_16x16x32_bf16 v[108:111], v[178:181], v[186:189], v[108:111]
	v_mfma_f32_16x16x32_bf16 v[108:111], v[182:185], v[190:193], v[108:111]
	v_mfma_f32_16x16x32_bf16 v[100:103], v[170:173], v[194:197], v[100:103]
	v_mfma_f32_16x16x32_bf16 v[100:103], v[174:177], v[204:207], v[100:103]
	v_mfma_f32_16x16x32_bf16 v[92:95], v[178:181], v[194:197], v[92:95]
	v_mfma_f32_16x16x32_bf16 v[92:95], v[182:185], v[204:207], v[92:95]
	v_mfma_f32_16x16x32_bf16 v[84:87], v[170:173], v[208:211], v[84:87]
	v_mfma_f32_16x16x32_bf16 v[84:87], v[174:177], v[212:215], v[84:87]
	v_mfma_f32_16x16x32_bf16 v[76:79], v[178:181], v[208:211], v[76:79]
	v_mfma_f32_16x16x32_bf16 v[76:79], v[182:185], v[212:215], v[76:79]
	v_mfma_f32_16x16x32_bf16 v[72:75], v[170:173], v[216:219], v[72:75]
	v_mfma_f32_16x16x32_bf16 v[72:75], v[174:177], v[220:223], v[72:75]
	s_setprio 2
	s_barrier
; #define PG8_STAGE(bufoff, gbase, voff) do { _Pragma("unroll") for (int _i = 0; _i < 2; ++_i) \
;         __builtin_amdgcn_global_load_lds((const unsigned*)((const char*)(gbase) + (voff)[_i]), (LAS unsigned*)(lds + (bufoff) + ldsw + _i * 8192), 16, 0, 0); } while (0)
; #define PG8_LDA(dst, b, h) do { _Pragma("unroll") for (int m = 0; m < 4; ++m) _Pragma("unroll") for (int k = 0; k < 2; ++k) dst[m][k] = *(const LAS bf16x8*)(lds + PG8_SA(b, h) + aoff + m * 2048 + k * 1024); } while (0)
; #define PG8_LDB(dst, b, h) do { _Pragma("unroll") for (int n = 0; n < 2; ++n) _Pragma("unroll") for (int k = 0; k < 2; ++k) dst[n][k] = *(const LAS bf16x8*)(lds + PG8_SB(b, h) + boff + n * 2048 + k * 1024); } while (0)
; #define PG8_MMA(ai, bj, At, Bt) do { __builtin_amdgcn_s_setprio(1); _Pragma("unroll") for (int m = 0; m < 4; ++m) _Pragma("unroll") for (int n = 0; n < 2; ++n) _Pragma("unroll") for (int k = 0; k < 2; ++k) \
;         acc[ai][bj][m][n] = __builtin_amdgcn_mfma_f32_16x16x32_bf16(Bt[n][k], At[m][k], acc[ai][bj][m][n], 0, 0, 0); __builtin_amdgcn_s_setprio(0); } while (0)
; #define PG8_WAIT_V(n) asm volatile("s_waitcnt vmcnt(" #n ")" ::: "memory")
; #define PG8_BAR __builtin_amdgcn_s_barrier()
; template <class Epi, class Sched, bool ALIGN_EPI = true>
; __device__ __forceinline__ void gemm_phase(LAS unsigned char* lds, const Gemm g, const Sched& S, const Epi& E) {
;     ...
;             PG8_LDB(B0, 0, 0); PG8_LDB(B1, 0, 1); PG8_SCHED; PG8_LDA(At, 0, 0); PG8_STAGE(PG8_SA(1, 1), a1 + hA, voffA);
;             PG8_WAIT_V(8); PG8_WAIT_L(0); PG8_BAR; PG8_MMA(0, 0, At, B0); PG8_MMA(0, 1, At, B1); PG8_BAR; PG8_SCHED;
;             PG8_LDA(At, 0, 1); PG8_STAGE(PG8_SB(0, 0), b2, voffB); PG8_STAGE(PG8_SB(0, 1), b2 + hB, voffB); PG8_STAGE(PG8_SA(0, 0), a2, voffA);
;             PG8_WAIT_V(8); PG8_WAIT_L(0); PG8_BAR; PG8_MMA(1, 0, At, B0); PG8_MMA(1, 1, At, B1); PG8_BAR; PG8_SCHED;
;             PG8_LDB(B0, 1, 0); PG8_LDB(B1, 1, 1); PG8_SCHED; PG8_LDA(At, 1, 0); PG8_STAGE(PG8_SA(0, 1), a2 + hA, voffA);
;             PG8_WAIT_V(8); PG8_WAIT_L(0); PG8_BAR; PG8_MMA(0, 0, At, B0); PG8_MMA(0, 1, At, B1); PG8_BAR; PG8_SCHED;
;             PG8_LDA(At, 1, 1); PG8_STAGE(PG8_SB(1, 0), b3, voffB); PG8_STAGE(PG8_SB(1, 1), b3 + hB, voffB); PG8_STAGE(PG8_SA(1, 0), a3, voffA);
;             PG8_WAIT_V(8); PG8_WAIT_L(0); PG8_BAR; PG8_MMA(1, 0, At, B0); PG8_MMA(1, 1, At, B1); PG8_BAR; PG8_SCHED;
	v_mfma_f32_16x16x32_bf16 v[68:71], v[178:181], v[216:219], v[68:71]
	v_mfma_f32_16x16x32_bf16 v[68:71], v[182:185], v[220:223], v[68:71]
	s_setprio 0
	s_add_i32 s26, s30, s59
	v_lshl_add_u64 v[156:157], v[156:157], 0, s[86:87]
	s_mov_b32 m0, s26
	ds_read_b128 v[186:189], v168 offset:49152
	ds_read_b128 v[190:193], v168 offset:50176
	ds_read_b128 v[194:197], v168 offset:51200
	ds_read_b128 v[204:207], v168 offset:52224
	ds_read_b128 v[208:211], v168 offset:53248
	ds_read_b128 v[212:215], v168 offset:54272
	ds_read_b128 v[216:219], v168 offset:55296
	ds_read_b128 v[220:223], v168 offset:56320
	global_load_lds_dwordx4 v[156:157], off
	s_add_i32 m0, s26, 0x2000
	s_add_u32 s26, s42, 0x80080
	v_lshl_add_u64 v[156:157], v[164:165], 0, s[86:87]
	s_addc_u32 s27, s43, 0
	s_add_i32 s30, s31, s59
	global_load_lds_dwordx4 v[156:157], off
	v_lshl_add_u64 v[156:157], s[26:27], 0, v[2:3]
	s_mov_b32 m0, s30
	s_nop 0
	global_load_lds_dwordx4 v[156:157], off
	v_lshl_add_u64 v[156:157], s[26:27], 0, v[0:1]
	s_add_i32 m0, s30, 0x2000
	s_nop 0
	global_load_lds_dwordx4 v[156:157], off
	v_lshl_add_u64 v[156:157], v[224:225], 0, s[86:87]
	s_mov_b32 m0, s64
	s_nop 0
	global_load_lds_dwordx4 v[156:157], off
	v_lshl_add_u64 v[156:157], v[226:227], 0, s[86:87]
	s_mov_b32 m0, s65
	s_nop 0
	global_load_lds_dwordx4 v[156:157], off
	s_waitcnt vmcnt(8)
	s_waitcnt lgkmcnt(0)
	s_barrier
	s_setprio 1
	s_waitcnt lgkmcnt(0)
	v_mfma_f32_16x16x32_bf16 v[64:67], v[132:135], v[186:189], v[64:67]
	v_mfma_f32_16x16x32_bf16 v[64:67], v[136:139], v[190:193], v[64:67]
	v_mfma_f32_16x16x32_bf16 v[60:63], v[140:143], v[186:189], v[60:63]
	v_mfma_f32_16x16x32_bf16 v[60:63], v[144:147], v[190:193], v[60:63]
	v_mfma_f32_16x16x32_bf16 v[56:59], v[132:135], v[194:197], v[56:59]
	v_mfma_f32_16x16x32_bf16 v[56:59], v[136:139], v[204:207], v[56:59]
	v_mfma_f32_16x16x32_bf16 v[48:51], v[140:143], v[194:197], v[48:51]
	v_mfma_f32_16x16x32_bf16 v[48:51], v[144:147], v[204:207], v[48:51]
	v_mfma_f32_16x16x32_bf16 v[40:43], v[132:135], v[208:211], v[40:43]
	v_mfma_f32_16x16x32_bf16 v[40:43], v[136:139], v[212:215], v[40:43]
	v_mfma_f32_16x16x32_bf16 v[32:35], v[140:143], v[208:211], v[32:35]
	v_mfma_f32_16x16x32_bf16 v[32:35], v[144:147], v[212:215], v[32:35]
	v_mfma_f32_16x16x32_bf16 v[24:27], v[132:135], v[216:219], v[24:27]
	v_mfma_f32_16x16x32_bf16 v[24:27], v[136:139], v[220:223], v[24:27]
	v_mfma_f32_16x16x32_bf16 v[16:19], v[140:143], v[216:219], v[16:19]
	v_mfma_f32_16x16x32_bf16 v[16:19], v[144:147], v[220:223], v[16:19]
	s_setprio 0
	s_setprio 1
	v_mfma_f32_16x16x32_bf16 v[52:55], v[170:173], v[186:189], v[52:55]
	v_mfma_f32_16x16x32_bf16 v[52:55], v[174:177], v[190:193], v[52:55]
	v_mfma_f32_16x16x32_bf16 v[44:47], v[178:181], v[186:189], v[44:47]
	v_mfma_f32_16x16x32_bf16 v[44:47], v[182:185], v[190:193], v[44:47]
	v_mfma_f32_16x16x32_bf16 v[36:39], v[170:173], v[194:197], v[36:39]
	v_mfma_f32_16x16x32_bf16 v[36:39], v[174:177], v[204:207], v[36:39]
	v_mfma_f32_16x16x32_bf16 v[28:31], v[178:181], v[194:197], v[28:31]
	v_mfma_f32_16x16x32_bf16 v[28:31], v[182:185], v[204:207], v[28:31]
	v_mfma_f32_16x16x32_bf16 v[20:23], v[170:173], v[208:211], v[20:23]
	v_mfma_f32_16x16x32_bf16 v[20:23], v[174:177], v[212:215], v[20:23]
	v_mfma_f32_16x16x32_bf16 v[12:15], v[178:181], v[208:211], v[12:15]
	v_mfma_f32_16x16x32_bf16 v[12:15], v[182:185], v[212:215], v[12:15]
	v_mfma_f32_16x16x32_bf16 v[8:11], v[170:173], v[216:219], v[8:11]
	v_mfma_f32_16x16x32_bf16 v[8:11], v[174:177], v[220:223], v[8:11]
	s_setprio 2
	s_barrier
	v_mfma_f32_16x16x32_bf16 v[4:7], v[178:181], v[216:219], v[4:7]
	v_mfma_f32_16x16x32_bf16 v[4:7], v[182:185], v[220:223], v[4:7]
	s_setprio 0
	s_add_i32 s25, s25, 2
	s_add_u32 s6, s6, 0x100
	s_addc_u32 s7, s7, 0
	s_add_u32 s19, s19, 0x100
	s_addc_u32 s24, s24, 0
	s_cmp_gt_u32 s25, 29
	s_cbranch_scc1 .Lpeel_exit_77
.LBB0_77:
	s_add_u32 s26, s6, 0xfff80080
	s_addc_u32 s27, s7, -1
	s_add_i32 s30, 0, 0x10000
	s_cmp_eq_u32 s25, 28
	s_cselect_b32 s45, s15, s27
	s_cselect_b32 s44, s17, s26
	s_cselect_b32 s43, s13, s24
	s_cselect_b32 s42, s18, s19
	s_add_i32 s31, 0, 0x14000
	v_add_u32_e32 v144, s30, v166
	v_add_u32_e32 v156, s31, v166
	ds_read_b128 v[132:135], v144
	ds_read_b128 v[136:139], v144 offset:1024
	ds_read_b128 v[140:143], v144 offset:2048
	ds_read_b128 v[144:147], v144 offset:3072
	ds_read_b128 v[170:173], v156
	ds_read_b128 v[174:177], v156 offset:1024
	ds_read_b128 v[178:181], v156 offset:2048
	ds_read_b128 v[182:185], v156 offset:3072
	v_lshl_add_u64 v[156:157], s[6:7], 0, v[152:153]
	s_add_i32 m0, s60, 0xc000
	ds_read_b128 v[186:189], v168
	ds_read_b128 v[190:193], v168 offset:1024
	ds_read_b128 v[194:197], v168 offset:2048
	ds_read_b128 v[204:207], v168 offset:3072
	ds_read_b128 v[208:211], v168 offset:4096
	ds_read_b128 v[212:215], v168 offset:5120
	ds_read_b128 v[216:219], v168 offset:6144
	ds_read_b128 v[220:223], v168 offset:7168
	global_load_lds_dwordx4 v[156:157], off
	v_lshl_add_u64 v[156:157], s[6:7], 0, v[154:155]
	s_add_i32 m0, s60, 0xe000
	s_nop 0
	global_load_lds_dwordx4 v[156:157], off
	s_waitcnt vmcnt(8)
	s_waitcnt lgkmcnt(0)
	s_barrier
; #define PG8_STAGE(bufoff, gbase, voff) do { _Pragma("unroll") for (int _i = 0; _i < 2; ++_i) \
;         __builtin_amdgcn_global_load_lds((const unsigned*)((const char*)(gbase) + (voff)[_i]), (LAS unsigned*)(lds + (bufoff) + ldsw + _i * 8192), 16, 0, 0); } while (0)
; #define PG8_LDA(dst, b, h) do { _Pragma("unroll") for (int m = 0; m < 4; ++m) _Pragma("unroll") for (int k = 0; k < 2; ++k) dst[m][k] = *(const LAS bf16x8*)(lds + PG8_SA(b, h) + aoff + m * 2048 + k * 1024); } while (0)
; #define PG8_MMA(ai, bj, At, Bt) do { __builtin_amdgcn_s_setprio(1); _Pragma("unroll") for (int m = 0; m < 4; ++m) _Pragma("unroll") for (int n = 0; n < 2; ++n) _Pragma("unroll") for (int k = 0; k < 2; ++k) \
;         acc[ai][bj][m][n] = __builtin_amdgcn_mfma_f32_16x16x32_bf16(Bt[n][k], At[m][k], acc[ai][bj][m][n], 0, 0, 0); __builtin_amdgcn_s_setprio(0); } while (0)
; #define PG8_WAIT_V(n) asm volatile("s_waitcnt vmcnt(" #n ")" ::: "memory")
; #define PG8_WAIT_L(n) asm volatile("s_waitcnt lgkmcnt(" #n ")" ::: "memory")
; #define PG8_BAR __builtin_amdgcn_s_barrier()
; #define PG8_SCHED __builtin_amdgcn_sched_barrier(0)
; template <class Epi, class Sched, bool ALIGN_EPI = true>
; __device__ __forceinline__ void gemm_phase(LAS unsigned char* lds, const Gemm g, const Sched& S, const Epi& E) {
;     ...
;             PG8_WAIT_V(8); PG8_WAIT_L(0); PG8_BAR; PG8_MMA(0, 0, At, B0); PG8_MMA(0, 1, At, B1); PG8_BAR; PG8_SCHED;
;             PG8_LDA(At, 0, 1); PG8_STAGE(PG8_SB(0, 0), b2, voffB); PG8_STAGE(PG8_SB(0, 1), b2 + hB, voffB); PG8_STAGE(PG8_SA(0, 0), a2, voffA);
;             PG8_WAIT_V(8); PG8_WAIT_L(0); PG8_BAR; PG8_MMA(1, 0, At, B0); PG8_MMA(1, 1, At, B1); PG8_BAR; PG8_SCHED;
	s_setprio 1
	s_waitcnt lgkmcnt(0)
	v_mfma_f32_16x16x32_bf16 v[128:131], v[132:135], v[186:189], v[128:131]
	v_mfma_f32_16x16x32_bf16 v[128:131], v[136:139], v[190:193], v[128:131]
	v_mfma_f32_16x16x32_bf16 v[124:127], v[140:143], v[186:189], v[124:127]
	v_mfma_f32_16x16x32_bf16 v[124:127], v[144:147], v[190:193], v[124:127]
	v_mfma_f32_16x16x32_bf16 v[116:119], v[132:135], v[194:197], v[116:119]
	v_mfma_f32_16x16x32_bf16 v[116:119], v[136:139], v[204:207], v[116:119]
	v_mfma_f32_16x16x32_bf16 v[112:115], v[140:143], v[194:197], v[112:115]
	v_mfma_f32_16x16x32_bf16 v[112:115], v[144:147], v[204:207], v[112:115]
	v_mfma_f32_16x16x32_bf16 v[104:107], v[132:135], v[208:211], v[104:107]
	v_mfma_f32_16x16x32_bf16 v[104:107], v[136:139], v[212:215], v[104:107]
	v_mfma_f32_16x16x32_bf16 v[96:99], v[140:143], v[208:211], v[96:99]
	v_mfma_f32_16x16x32_bf16 v[96:99], v[144:147], v[212:215], v[96:99]
	v_mfma_f32_16x16x32_bf16 v[88:91], v[132:135], v[216:219], v[88:91]
	v_mfma_f32_16x16x32_bf16 v[88:91], v[136:139], v[220:223], v[88:91]
	v_mfma_f32_16x16x32_bf16 v[80:83], v[140:143], v[216:219], v[80:83]
	v_mfma_f32_16x16x32_bf16 v[80:83], v[144:147], v[220:223], v[80:83]
	s_setprio 0
	s_setprio 1
	v_mfma_f32_16x16x32_bf16 v[120:123], v[170:173], v[186:189], v[120:123]
	v_mfma_f32_16x16x32_bf16 v[120:123], v[174:177], v[190:193], v[120:123]
	v_mfma_f32_16x16x32_bf16 v[108:111], v[178:181], v[186:189], v[108:111]
	v_mfma_f32_16x16x32_bf16 v[108:111], v[182:185], v[190:193], v[108:111]
	v_mfma_f32_16x16x32_bf16 v[100:103], v[170:173], v[194:197], v[100:103]
	v_mfma_f32_16x16x32_bf16 v[100:103], v[174:177], v[204:207], v[100:103]
	v_mfma_f32_16x16x32_bf16 v[92:95], v[178:181], v[194:197], v[92:95]
	v_mfma_f32_16x16x32_bf16 v[92:95], v[182:185], v[204:207], v[92:95]
	v_mfma_f32_16x16x32_bf16 v[84:87], v[170:173], v[208:211], v[84:87]
	v_mfma_f32_16x16x32_bf16 v[84:87], v[174:177], v[212:215], v[84:87]
	v_mfma_f32_16x16x32_bf16 v[76:79], v[178:181], v[208:211], v[76:79]
	v_mfma_f32_16x16x32_bf16 v[76:79], v[182:185], v[212:215], v[76:79]
	v_mfma_f32_16x16x32_bf16 v[72:75], v[170:173], v[216:219], v[72:75]
	v_mfma_f32_16x16x32_bf16 v[72:75], v[174:177], v[220:223], v[72:75]
	s_setprio 2
	s_barrier
	v_mfma_f32_16x16x32_bf16 v[68:71], v[178:181], v[216:219], v[68:71]
	v_mfma_f32_16x16x32_bf16 v[68:71], v[182:185], v[220:223], v[68:71]
	s_setprio 0
	s_add_i32 s26, s30, s59
	v_lshl_add_u64 v[156:157], s[42:43], 0, v[2:3]
	s_mov_b32 m0, s26
	ds_read_b128 v[186:189], v168 offset:16384
	ds_read_b128 v[190:193], v168 offset:17408
	ds_read_b128 v[194:197], v168 offset:18432
	ds_read_b128 v[204:207], v168 offset:19456
	ds_read_b128 v[208:211], v168 offset:20480
	ds_read_b128 v[212:215], v168 offset:21504
	ds_read_b128 v[216:219], v168 offset:22528
	ds_read_b128 v[220:223], v168 offset:23552
	global_load_lds_dwordx4 v[156:157], off
	s_add_i32 m0, s26, 0x2000
	s_add_u32 s26, s42, 0x80000
	v_lshl_add_u64 v[164:165], s[42:43], 0, v[0:1]
	s_addc_u32 s27, s43, 0
	s_add_i32 s30, s31, s59
	global_load_lds_dwordx4 v[164:165], off
	v_lshl_add_u64 v[224:225], s[26:27], 0, v[2:3]
	s_mov_b32 m0, s30
	v_lshl_add_u64 v[226:227], s[44:45], 0, v[148:149]
	global_load_lds_dwordx4 v[224:225], off
	v_lshl_add_u64 v[224:225], s[26:27], 0, v[0:1]
	s_add_i32 m0, s30, 0x2000
	s_nop 0
	global_load_lds_dwordx4 v[224:225], off
	v_lshl_add_u64 v[224:225], s[44:45], 0, v[150:151]
	s_mov_b32 m0, s60
	s_nop 0
	global_load_lds_dwordx4 v[224:225], off
	s_mov_b32 m0, s61
	s_nop 0
	global_load_lds_dwordx4 v[226:227], off
	s_waitcnt vmcnt(8)
	s_waitcnt lgkmcnt(0)
	s_barrier
	s_setprio 1
	s_waitcnt lgkmcnt(0)
	v_mfma_f32_16x16x32_bf16 v[64:67], v[132:135], v[186:189], v[64:67]
	v_mfma_f32_16x16x32_bf16 v[64:67], v[136:139], v[190:193], v[64:67]
	v_mfma_f32_16x16x32_bf16 v[60:63], v[140:143], v[186:189], v[60:63]
	v_mfma_f32_16x16x32_bf16 v[60:63], v[144:147], v[190:193], v[60:63]
	v_mfma_f32_16x16x32_bf16 v[56:59], v[132:135], v[194:197], v[56:59]
	v_mfma_f32_16x16x32_bf16 v[56:59], v[136:139], v[204:207], v[56:59]
	v_mfma_f32_16x16x32_bf16 v[48:51], v[140:143], v[194:197], v[48:51]
	v_mfma_f32_16x16x32_bf16 v[48:51], v[144:147], v[204:207], v[48:51]
	v_mfma_f32_16x16x32_bf16 v[40:43], v[132:135], v[208:211], v[40:43]
	v_mfma_f32_16x16x32_bf16 v[40:43], v[136:139], v[212:215], v[40:43]
	v_mfma_f32_16x16x32_bf16 v[32:35], v[140:143], v[208:211], v[32:35]
	v_mfma_f32_16x16x32_bf16 v[32:35], v[144:147], v[212:215], v[32:35]
	v_mfma_f32_16x16x32_bf16 v[24:27], v[132:135], v[216:219], v[24:27]
	v_mfma_f32_16x16x32_bf16 v[24:27], v[136:139], v[220:223], v[24:27]
	v_mfma_f32_16x16x32_bf16 v[16:19], v[140:143], v[216:219], v[16:19]
	v_mfma_f32_16x16x32_bf16 v[16:19], v[144:147], v[220:223], v[16:19]
	s_setprio 0
	s_setprio 1
	v_mfma_f32_16x16x32_bf16 v[52:55], v[170:173], v[186:189], v[52:55]
	v_mfma_f32_16x16x32_bf16 v[52:55], v[174:177], v[190:193], v[52:55]
	v_mfma_f32_16x16x32_bf16 v[44:47], v[178:181], v[186:189], v[44:47]
	v_mfma_f32_16x16x32_bf16 v[44:47], v[182:185], v[190:193], v[44:47]
	v_mfma_f32_16x16x32_bf16 v[36:39], v[170:173], v[194:197], v[36:39]
	v_mfma_f32_16x16x32_bf16 v[36:39], v[174:177], v[204:207], v[36:39]
	v_mfma_f32_16x16x32_bf16 v[28:31], v[178:181], v[194:197], v[28:31]
	v_mfma_f32_16x16x32_bf16 v[28:31], v[182:185], v[204:207], v[28:31]
	v_mfma_f32_16x16x32_bf16 v[20:23], v[170:173], v[208:211], v[20:23]
	v_mfma_f32_16x16x32_bf16 v[20:23], v[174:177], v[212:215], v[20:23]
	v_mfma_f32_16x16x32_bf16 v[12:15], v[178:181], v[208:211], v[12:15]
	v_mfma_f32_16x16x32_bf16 v[12:15], v[182:185], v[212:215], v[12:15]
	v_mfma_f32_16x16x32_bf16 v[8:11], v[170:173], v[216:219], v[8:11]
	v_mfma_f32_16x16x32_bf16 v[8:11], v[174:177], v[220:223], v[8:11]
	s_setprio 2
	s_barrier
; #define PG8_STAGE(bufoff, gbase, voff) do { _Pragma("unroll") for (int _i = 0; _i < 2; ++_i) \
;         __builtin_amdgcn_global_load_lds((const unsigned*)((const char*)(gbase) + (voff)[_i]), (LAS unsigned*)(lds + (bufoff) + ldsw + _i * 8192), 16, 0, 0); } while (0)
; #define PG8_LDA(dst, b, h) do { _Pragma("unroll") for (int m = 0; m < 4; ++m) _Pragma("unroll") for (int k = 0; k < 2; ++k) dst[m][k] = *(const LAS bf16x8*)(lds + PG8_SA(b, h) + aoff + m * 2048 + k * 1024); } while (0)
; #define PG8_LDB(dst, b, h) do { _Pragma("unroll") for (int n = 0; n < 2; ++n) _Pragma("unroll") for (int k = 0; k < 2; ++k) dst[n][k] = *(const LAS bf16x8*)(lds + PG8_SB(b, h) + boff + n * 2048 + k * 1024); } while (0)
; #define PG8_MMA(ai, bj, At, Bt) do { __builtin_amdgcn_s_setprio(1); _Pragma("unroll") for (int m = 0; m < 4; ++m) _Pragma("unroll") for (int n = 0; n < 2; ++n) _Pragma("unroll") for (int k = 0; k < 2; ++k) \
;         acc[ai][bj][m][n] = __builtin_amdgcn_mfma_f32_16x16x32_bf16(Bt[n][k], At[m][k], acc[ai][bj][m][n], 0, 0, 0); __builtin_amdgcn_s_setprio(0); } while (0)
; #define PG8_WAIT_V(n) asm volatile("s_waitcnt vmcnt(" #n ")" ::: "memory")
; #define PG8_WAIT_L(n) asm volatile("s_waitcnt lgkmcnt(" #n ")" ::: "memory")
; #define PG8_BAR __builtin_amdgcn_s_barrier()
; #define PG8_SCHED __builtin_amdgcn_sched_barrier(0)
; template <class Epi, class Sched, bool ALIGN_EPI = true>
; __device__ __forceinline__ void gemm_phase(LAS unsigned char* lds, const Gemm g, const Sched& S, const Epi& E) {
;     ...
;             PG8_WAIT_V(8); PG8_WAIT_L(0); PG8_BAR; PG8_MMA(1, 0, At, B0); PG8_MMA(1, 1, At, B1); PG8_BAR; PG8_SCHED;
;             PG8_LDB(B0, 1, 0); PG8_LDB(B1, 1, 1); PG8_SCHED; PG8_LDA(At, 1, 0); PG8_STAGE(PG8_SA(0, 1), a2 + hA, voffA);
;             PG8_WAIT_V(8); PG8_WAIT_L(0); PG8_BAR; PG8_MMA(0, 0, At, B0); PG8_MMA(0, 1, At, B1); PG8_BAR; PG8_SCHED;
	v_mfma_f32_16x16x32_bf16 v[4:7], v[178:181], v[216:219], v[4:7]
	v_mfma_f32_16x16x32_bf16 v[4:7], v[182:185], v[220:223], v[4:7]
	s_setprio 0
	s_add_i32 s30, 0, 0x18000
	s_add_i32 s31, 0, 0x1c000
	v_add_u32_e32 v144, s30, v166
	v_add_u32_e32 v160, s31, v166
	ds_read_b128 v[132:135], v144
	ds_read_b128 v[136:139], v144 offset:1024
	ds_read_b128 v[140:143], v144 offset:2048
	ds_read_b128 v[144:147], v144 offset:3072
	ds_read_b128 v[170:173], v160
	ds_read_b128 v[174:177], v160 offset:1024
	ds_read_b128 v[178:181], v160 offset:2048
	ds_read_b128 v[182:185], v160 offset:3072
	s_add_u32 s26, s44, 0x80000
	s_addc_u32 s27, s45, 0
	s_mov_b32 m0, s62
	v_lshl_add_u64 v[228:229], s[26:27], 0, v[150:151]
	ds_read_b128 v[186:189], v168 offset:32768
	ds_read_b128 v[190:193], v168 offset:33792
	ds_read_b128 v[194:197], v168 offset:34816
	ds_read_b128 v[204:207], v168 offset:35840
	ds_read_b128 v[208:211], v168 offset:36864
	ds_read_b128 v[212:215], v168 offset:37888
	ds_read_b128 v[216:219], v168 offset:38912
	ds_read_b128 v[220:223], v168 offset:39936
	global_load_lds_dwordx4 v[228:229], off
	v_lshl_add_u64 v[228:229], s[26:27], 0, v[148:149]
	s_mov_b32 m0, s63
	s_nop 0
	global_load_lds_dwordx4 v[228:229], off
	s_waitcnt vmcnt(8)
	s_waitcnt lgkmcnt(0)
	s_barrier
	s_setprio 1
	s_waitcnt lgkmcnt(0)
	v_mfma_f32_16x16x32_bf16 v[128:131], v[132:135], v[186:189], v[128:131]
	v_mfma_f32_16x16x32_bf16 v[128:131], v[136:139], v[190:193], v[128:131]
	v_mfma_f32_16x16x32_bf16 v[124:127], v[140:143], v[186:189], v[124:127]
	v_mfma_f32_16x16x32_bf16 v[124:127], v[144:147], v[190:193], v[124:127]
	v_mfma_f32_16x16x32_bf16 v[116:119], v[132:135], v[194:197], v[116:119]
	v_mfma_f32_16x16x32_bf16 v[116:119], v[136:139], v[204:207], v[116:119]
	v_mfma_f32_16x16x32_bf16 v[112:115], v[140:143], v[194:197], v[112:115]
	v_mfma_f32_16x16x32_bf16 v[112:115], v[144:147], v[204:207], v[112:115]
	v_mfma_f32_16x16x32_bf16 v[104:107], v[132:135], v[208:211], v[104:107]
	v_mfma_f32_16x16x32_bf16 v[104:107], v[136:139], v[212:215], v[104:107]
	v_mfma_f32_16x16x32_bf16 v[96:99], v[140:143], v[208:211], v[96:99]
	v_mfma_f32_16x16x32_bf16 v[96:99], v[144:147], v[212:215], v[96:99]
	v_mfma_f32_16x16x32_bf16 v[88:91], v[132:135], v[216:219], v[88:91]
	v_mfma_f32_16x16x32_bf16 v[88:91], v[136:139], v[220:223], v[88:91]
	v_mfma_f32_16x16x32_bf16 v[80:83], v[140:143], v[216:219], v[80:83]
	v_mfma_f32_16x16x32_bf16 v[80:83], v[144:147], v[220:223], v[80:83]
	s_setprio 0
	s_setprio 1
	v_mfma_f32_16x16x32_bf16 v[120:123], v[170:173], v[186:189], v[120:123]
	v_mfma_f32_16x16x32_bf16 v[120:123], v[174:177], v[190:193], v[120:123]
	v_mfma_f32_16x16x32_bf16 v[108:111], v[178:181], v[186:189], v[108:111]
	v_mfma_f32_16x16x32_bf16 v[108:111], v[182:185], v[190:193], v[108:111]
	v_mfma_f32_16x16x32_bf16 v[100:103], v[170:173], v[194:197], v[100:103]
	v_mfma_f32_16x16x32_bf16 v[100:103], v[174:177], v[204:207], v[100:103]
	v_mfma_f32_16x16x32_bf16 v[92:95], v[178:181], v[194:197], v[92:95]
	v_mfma_f32_16x16x32_bf16 v[92:95], v[182:185], v[204:207], v[92:95]
	v_mfma_f32_16x16x32_bf16 v[84:87], v[170:173], v[208:211], v[84:87]
	v_mfma_f32_16x16x32_bf16 v[84:87], v[174:177], v[212:215], v[84:87]
	v_mfma_f32_16x16x32_bf16 v[76:79], v[178:181], v[208:211], v[76:79]
	v_mfma_f32_16x16x32_bf16 v[76:79], v[182:185], v[212:215], v[76:79]
	v_mfma_f32_16x16x32_bf16 v[72:75], v[170:173], v[216:219], v[72:75]
	v_mfma_f32_16x16x32_bf16 v[72:75], v[174:177], v[220:223], v[72:75]
	s_setprio 2
	s_barrier
; #define PG8_STAGE(bufoff, gbase, voff) do { _Pragma("unroll") for (int _i = 0; _i < 2; ++_i) \
;         __builtin_amdgcn_global_load_lds((const unsigned*)((const char*)(gbase) + (voff)[_i]), (LAS unsigned*)(lds + (bufoff) + ldsw + _i * 8192), 16, 0, 0); } while (0)
; #define PG8_LDA(dst, b, h) do { _Pragma("unroll") for (int m = 0; m < 4; ++m) _Pragma("unroll") for (int k = 0; k < 2; ++k) dst[m][k] = *(const LAS bf16x8*)(lds + PG8_SA(b, h) + aoff + m * 2048 + k * 1024); } while (0)
; #define PG8_MMA(ai, bj, At, Bt) do { __builtin_amdgcn_s_setprio(1); _Pragma("unroll") for (int m = 0; m < 4; ++m) _Pragma("unroll") for (int n = 0; n < 2; ++n) _Pragma("unroll") for (int k = 0; k < 2; ++k) \
;         acc[ai][bj][m][n] = __builtin_amdgcn_mfma_f32_16x16x32_bf16(Bt[n][k], At[m][k], acc[ai][bj][m][n], 0, 0, 0); __builtin_amdgcn_s_setprio(0); } while (0)
; #define PG8_WAIT_V(n) asm volatile("s_waitcnt vmcnt(" #n ")" ::: "memory")
; #define PG8_WAIT_L(n) asm volatile("s_waitcnt lgkmcnt(" #n ")" ::: "memory")
; #define PG8_BAR __builtin_amdgcn_s_barrier()
; #define PG8_SCHED __builtin_amdgcn_sched_barrier(0)
; template <class Epi, class Sched, bool ALIGN_EPI = true>
; __device__ __forceinline__ void gemm_phase(LAS unsigned char* lds, const Gemm g, const Sched& S, const Epi& E) {
;     ...
;             PG8_WAIT_V(8); PG8_WAIT_L(0); PG8_BAR; PG8_MMA(0, 0, At, B0); PG8_MMA(0, 1, At, B1); PG8_BAR; PG8_SCHED;
;             PG8_LDA(At, 1, 1); PG8_STAGE(PG8_SB(1, 0), b3, voffB); PG8_STAGE(PG8_SB(1, 1), b3 + hB, voffB); PG8_STAGE(PG8_SA(1, 0), a3, voffA);
;             PG8_WAIT_V(8); PG8_WAIT_L(0); PG8_BAR; PG8_MMA(1, 0, At, B0); PG8_MMA(1, 1, At, B1); PG8_BAR; PG8_SCHED;
	v_mfma_f32_16x16x32_bf16 v[68:71], v[178:181], v[216:219], v[68:71]
	v_mfma_f32_16x16x32_bf16 v[68:71], v[182:185], v[220:223], v[68:71]
	s_setprio 0
	s_add_i32 s26, s30, s59
	v_lshl_add_u64 v[156:157], v[156:157], 0, s[86:87]
	s_mov_b32 m0, s26
	ds_read_b128 v[186:189], v168 offset:49152
	ds_read_b128 v[190:193], v168 offset:50176
	ds_read_b128 v[194:197], v168 offset:51200
	ds_read_b128 v[204:207], v168 offset:52224
	ds_read_b128 v[208:211], v168 offset:53248
	ds_read_b128 v[212:215], v168 offset:54272
	ds_read_b128 v[216:219], v168 offset:55296
	ds_read_b128 v[220:223], v168 offset:56320
	global_load_lds_dwordx4 v[156:157], off
	s_add_i32 m0, s26, 0x2000
	s_add_u32 s26, s42, 0x80080
	v_lshl_add_u64 v[156:157], v[164:165], 0, s[86:87]
	s_addc_u32 s27, s43, 0
	s_add_i32 s30, s31, s59
	global_load_lds_dwordx4 v[156:157], off
	v_lshl_add_u64 v[156:157], s[26:27], 0, v[2:3]
	s_mov_b32 m0, s30
	s_nop 0
	global_load_lds_dwordx4 v[156:157], off
	v_lshl_add_u64 v[156:157], s[26:27], 0, v[0:1]
	s_add_i32 m0, s30, 0x2000
	s_nop 0
	global_load_lds_dwordx4 v[156:157], off
	v_lshl_add_u64 v[156:157], v[224:225], 0, s[86:87]
	s_mov_b32 m0, s64
	s_nop 0
	global_load_lds_dwordx4 v[156:157], off
	v_lshl_add_u64 v[156:157], v[226:227], 0, s[86:87]
	s_mov_b32 m0, s65
	s_nop 0
	global_load_lds_dwordx4 v[156:157], off
	s_waitcnt vmcnt(8)
	s_waitcnt lgkmcnt(0)
	s_barrier
	s_setprio 1
	s_waitcnt lgkmcnt(0)
	v_mfma_f32_16x16x32_bf16 v[64:67], v[132:135], v[186:189], v[64:67]
	v_mfma_f32_16x16x32_bf16 v[64:67], v[136:139], v[190:193], v[64:67]
	v_mfma_f32_16x16x32_bf16 v[60:63], v[140:143], v[186:189], v[60:63]
	v_mfma_f32_16x16x32_bf16 v[60:63], v[144:147], v[190:193], v[60:63]
	v_mfma_f32_16x16x32_bf16 v[56:59], v[132:135], v[194:197], v[56:59]
	v_mfma_f32_16x16x32_bf16 v[56:59], v[136:139], v[204:207], v[56:59]
	v_mfma_f32_16x16x32_bf16 v[48:51], v[140:143], v[194:197], v[48:51]
	v_mfma_f32_16x16x32_bf16 v[48:51], v[144:147], v[204:207], v[48:51]
	v_mfma_f32_16x16x32_bf16 v[40:43], v[132:135], v[208:211], v[40:43]
	v_mfma_f32_16x16x32_bf16 v[40:43], v[136:139], v[212:215], v[40:43]
	v_mfma_f32_16x16x32_bf16 v[32:35], v[140:143], v[208:211], v[32:35]
	v_mfma_f32_16x16x32_bf16 v[32:35], v[144:147], v[212:215], v[32:35]
	v_mfma_f32_16x16x32_bf16 v[24:27], v[132:135], v[216:219], v[24:27]
	v_mfma_f32_16x16x32_bf16 v[24:27], v[136:139], v[220:223], v[24:27]
	v_mfma_f32_16x16x32_bf16 v[16:19], v[140:143], v[216:219], v[16:19]
	v_mfma_f32_16x16x32_bf16 v[16:19], v[144:147], v[220:223], v[16:19]
	s_setprio 0
	s_setprio 1
	v_mfma_f32_16x16x32_bf16 v[52:55], v[170:173], v[186:189], v[52:55]
	v_mfma_f32_16x16x32_bf16 v[52:55], v[174:177], v[190:193], v[52:55]
	v_mfma_f32_16x16x32_bf16 v[44:47], v[178:181], v[186:189], v[44:47]
	v_mfma_f32_16x16x32_bf16 v[44:47], v[182:185], v[190:193], v[44:47]
	v_mfma_f32_16x16x32_bf16 v[36:39], v[170:173], v[194:197], v[36:39]
	v_mfma_f32_16x16x32_bf16 v[36:39], v[174:177], v[204:207], v[36:39]
	v_mfma_f32_16x16x32_bf16 v[28:31], v[178:181], v[194:197], v[28:31]
	v_mfma_f32_16x16x32_bf16 v[28:31], v[182:185], v[204:207], v[28:31]
	v_mfma_f32_16x16x32_bf16 v[20:23], v[170:173], v[208:211], v[20:23]
	v_mfma_f32_16x16x32_bf16 v[20:23], v[174:177], v[212:215], v[20:23]
	v_mfma_f32_16x16x32_bf16 v[12:15], v[178:181], v[208:211], v[12:15]
	v_mfma_f32_16x16x32_bf16 v[12:15], v[182:185], v[212:215], v[12:15]
	v_mfma_f32_16x16x32_bf16 v[8:11], v[170:173], v[216:219], v[8:11]
	v_mfma_f32_16x16x32_bf16 v[8:11], v[174:177], v[220:223], v[8:11]
	s_setprio 2
	s_barrier
	v_mfma_f32_16x16x32_bf16 v[4:7], v[178:181], v[216:219], v[4:7]
	v_mfma_f32_16x16x32_bf16 v[4:7], v[182:185], v[220:223], v[4:7]
	s_setprio 0
	s_add_i32 s25, s25, 2
	s_add_u32 s6, s6, 0x100
	s_addc_u32 s7, s7, 0
	s_add_u32 s19, s19, 0x100
	s_addc_u32 s24, s24, 0
	s_cmp_gt_u32 s25, 29
	s_cbranch_scc0 .LBB0_77

;     __device__ bool next(int i, Unit& u) const { if (i >= 2) return false; const int x = c & 7, j = c >> 3; u.pm = 32 * i + 4 * x + (j & 3); u.pn = j >> 2; return true; }
; #define PG8_STAGE(bufoff, gbase, voff) do { _Pragma("unroll") for (int _i = 0; _i < 2; ++_i) \
;         __builtin_amdgcn_global_load_lds((const unsigned*)((const char*)(gbase) + (voff)[_i]), (LAS unsigned*)(lds + (bufoff) + ldsw + _i * 8192), 16, 0, 0); } while (0)
; #define PG8_LDA(dst, b, h) do { _Pragma("unroll") for (int m = 0; m < 4; ++m) _Pragma("unroll") for (int k = 0; k < 2; ++k) dst[m][k] = *(const LAS bf16x8*)(lds + PG8_SA(b, h) + aoff + m * 2048 + k * 1024); } while (0)
; #define PG8_LDB(dst, b, h) do { _Pragma("unroll") for (int n = 0; n < 2; ++n) _Pragma("unroll") for (int k = 0; k < 2; ++k) dst[n][k] = *(const LAS bf16x8*)(lds + PG8_SB(b, h) + boff + n * 2048 + k * 1024); } while (0)
; #define PG8_WAIT_V(n) asm volatile("s_waitcnt vmcnt(" #n ")" ::: "memory")
; #define PG8_WAIT_L(n) asm volatile("s_waitcnt lgkmcnt(" #n ")" ::: "memory")
; #define PG8_BAR __builtin_amdgcn_s_barrier()
; #define PG8_SCHED __builtin_amdgcn_sched_barrier(0)
; template <class Epi, class Sched, bool ALIGN_EPI = true>
; __device__ __forceinline__ void gemm_phase(LAS unsigned char* lds, const Gemm g, const Sched& S, const Epi& E) {
;     ...
;         const bool has_next = S.next(ui + 1, nxt);
;         const char* nA = has_next ? (const char*)g.A + ((size_t)nxt.pm * BM * g.lda + (size_t)nxt.pn * g.a_pn_off) * 2 : cA; const char* nB = has_next ? (const char*)g.Bt + (size_t)nxt.pn * BM * g.ldb * 2 : cB;
;         for (int t = 0; t < nt; t += 2) {
;             const bool last = (t == nt - 2);
;             const char* a1 = cA + (size_t)(t + 1) * kstep;
;             const char* a2 = last ? nA : cA + (size_t)(t + 2) * kstep; const char* b2 = last ? nB : cB + (size_t)(t + 2) * kstep;
;             const char* a3 = a2 + kstep; const char* b3 = b2 + kstep;
;             PG8_LDB(B0, 0, 0); PG8_LDB(B1, 0, 1); PG8_SCHED; PG8_LDA(At, 0, 0); PG8_STAGE(PG8_SA(1, 1), a1 + hA, voffA);
;             PG8_WAIT_V(8); PG8_WAIT_L(0); PG8_BAR; PG8_MMA(0, 0, At, B0); PG8_MMA(0, 1, At, B1); PG8_BAR; PG8_SCHED;
;             PG8_LDA(At, 0, 1); PG8_STAGE(PG8_SB(0, 0), b2, voffB); PG8_STAGE(PG8_SB(0, 1), b2 + hB, voffB); PG8_STAGE(PG8_SA(0, 0), a2, voffA);
.LBB0_217:
	s_ashr_i32 s11, s10, 31
	s_lshl_b64 s[12:13], s[10:11], 20
	s_add_u32 s12, s46, s12
	s_addc_u32 s13, s47, s13
	s_and_b64 s[14:15], s[4:5], exec
	s_cselect_b32 s11, s13, s39
	s_cselect_b32 s18, s12, s38
	s_ashr_i32 s9, s8, 31
	s_lshl_b64 s[14:15], s[8:9], 20
	s_add_u32 s14, s44, s14
	s_addc_u32 s15, s45, s15
	s_and_b64 s[24:25], s[4:5], exec
	s_cselect_b32 s9, s15, s41
	s_cselect_b32 s19, s14, s40
	s_add_u32 s38, s38, 0x80080
	s_addc_u32 s39, s39, 0
	s_add_u32 s24, s40, 0x100
	s_addc_u32 s25, s41, 0
	s_mov_b32 s26, -2
	s_add_u32 s27, s38, 0xfff80080
	s_addc_u32 s30, s39, -1
	s_add_i32 s31, 0, 0x10000
	s_cmp_eq_u32 s26, 28
	s_cselect_b32 s43, s11, s30
	s_cselect_b32 s42, s18, s27
	v_add_u32_e32 v156, s31, v145
	s_cselect_b32 s41, s9, s25
	s_cselect_b32 s40, s19, s24
	s_add_i32 s27, 0, 0x14000
	ds_read_b128 v[140:143], v156
	ds_read_b128 v[148:151], v156 offset:1024
	ds_read_b128 v[152:155], v156 offset:2048
	ds_read_b128 v[164:167], v156 offset:3072
	v_add_u32_e32 v156, s27, v145
	ds_read_b128 v[168:171], v156
	ds_read_b128 v[172:175], v156 offset:1024
	ds_read_b128 v[176:179], v156 offset:2048
	ds_read_b128 v[180:183], v156 offset:3072
	v_lshl_add_u64 v[156:157], s[38:39], 0, v[136:137]
	s_add_i32 m0, s58, 0xc000
	ds_read_b128 v[184:187], v147
	ds_read_b128 v[188:191], v147 offset:1024
	ds_read_b128 v[192:195], v147 offset:2048
	ds_read_b128 v[204:207], v147 offset:3072
	ds_read_b128 v[208:211], v147 offset:4096
	ds_read_b128 v[212:215], v147 offset:5120
	ds_read_b128 v[216:219], v147 offset:6144
	ds_read_b128 v[220:223], v147 offset:7168
	global_load_lds_dwordx4 v[156:157], off
	v_lshl_add_u64 v[156:157], s[38:39], 0, v[138:139]
	s_add_i32 m0, s58, 0xe000
	s_nop 0
	global_load_lds_dwordx4 v[156:157], off
	s_waitcnt vmcnt(8)
	s_waitcnt lgkmcnt(0)
	s_barrier
	s_setprio 1
	s_waitcnt lgkmcnt(0)
	v_mfma_f32_16x16x32_bf16 v[128:131], v[140:143], v[184:187], 0
	v_mfma_f32_16x16x32_bf16 v[128:131], v[148:151], v[188:191], v[128:131]
	v_mfma_f32_16x16x32_bf16 v[124:127], v[152:155], v[184:187], 0
	v_mfma_f32_16x16x32_bf16 v[124:127], v[164:167], v[188:191], v[124:127]
	v_mfma_f32_16x16x32_bf16 v[120:123], v[140:143], v[192:195], 0
	v_mfma_f32_16x16x32_bf16 v[120:123], v[148:151], v[204:207], v[120:123]
	v_mfma_f32_16x16x32_bf16 v[112:115], v[152:155], v[192:195], 0
	v_mfma_f32_16x16x32_bf16 v[112:115], v[164:167], v[204:207], v[112:115]
	v_mfma_f32_16x16x32_bf16 v[104:107], v[140:143], v[208:211], 0
	v_mfma_f32_16x16x32_bf16 v[104:107], v[148:151], v[212:215], v[104:107]
	v_mfma_f32_16x16x32_bf16 v[96:99], v[152:155], v[208:211], 0
	v_mfma_f32_16x16x32_bf16 v[96:99], v[164:167], v[212:215], v[96:99]
	v_mfma_f32_16x16x32_bf16 v[88:91], v[140:143], v[216:219], 0
	v_mfma_f32_16x16x32_bf16 v[88:91], v[148:151], v[220:223], v[88:91]
	v_mfma_f32_16x16x32_bf16 v[80:83], v[152:155], v[216:219], 0
	v_mfma_f32_16x16x32_bf16 v[80:83], v[164:167], v[220:223], v[80:83]
	s_setprio 0
	s_setprio 1
	v_mfma_f32_16x16x32_bf16 v[116:119], v[168:171], v[184:187], 0
	v_mfma_f32_16x16x32_bf16 v[116:119], v[172:175], v[188:191], v[116:119]
	v_mfma_f32_16x16x32_bf16 v[108:111], v[176:179], v[184:187], 0
	v_mfma_f32_16x16x32_bf16 v[108:111], v[180:183], v[188:191], v[108:111]
	v_mfma_f32_16x16x32_bf16 v[100:103], v[168:171], v[192:195], 0
	v_mfma_f32_16x16x32_bf16 v[100:103], v[172:175], v[204:207], v[100:103]
	v_mfma_f32_16x16x32_bf16 v[92:95], v[176:179], v[192:195], 0
	v_mfma_f32_16x16x32_bf16 v[92:95], v[180:183], v[204:207], v[92:95]
	v_mfma_f32_16x16x32_bf16 v[84:87], v[168:171], v[208:211], 0
	v_mfma_f32_16x16x32_bf16 v[84:87], v[172:175], v[212:215], v[84:87]
	v_mfma_f32_16x16x32_bf16 v[76:79], v[176:179], v[208:211], 0
	v_mfma_f32_16x16x32_bf16 v[76:79], v[180:183], v[212:215], v[76:79]
	v_mfma_f32_16x16x32_bf16 v[72:75], v[168:171], v[216:219], 0
	v_mfma_f32_16x16x32_bf16 v[72:75], v[172:175], v[220:223], v[72:75]
	s_setprio 2
	s_barrier
	v_mfma_f32_16x16x32_bf16 v[68:71], v[176:179], v[216:219], 0
	v_mfma_f32_16x16x32_bf16 v[68:71], v[180:183], v[220:223], v[68:71]
	s_setprio 0
	s_add_i32 s30, s31, s53
	v_lshl_add_u64 v[156:157], s[40:41], 0, v[2:3]
	s_mov_b32 m0, s30
	ds_read_b128 v[184:187], v147 offset:16384
	ds_read_b128 v[188:191], v147 offset:17408
	ds_read_b128 v[192:195], v147 offset:18432
	ds_read_b128 v[204:207], v147 offset:19456
	ds_read_b128 v[208:211], v147 offset:20480
	ds_read_b128 v[212:215], v147 offset:21504
	ds_read_b128 v[216:219], v147 offset:22528
	ds_read_b128 v[220:223], v147 offset:23552
	global_load_lds_dwordx4 v[156:157], off
	s_add_i32 m0, s30, 0x2000
	s_add_u32 s30, s40, 0x80000
	v_lshl_add_u64 v[196:197], s[40:41], 0, v[0:1]
	s_addc_u32 s31, s41, 0
	s_add_i32 s27, s27, s53
	global_load_lds_dwordx4 v[196:197], off
	v_lshl_add_u64 v[224:225], s[30:31], 0, v[2:3]
	s_mov_b32 m0, s27
	v_lshl_add_u64 v[226:227], s[42:43], 0, v[132:133]
	global_load_lds_dwordx4 v[224:225], off
	v_lshl_add_u64 v[224:225], s[30:31], 0, v[0:1]
	s_add_i32 m0, s27, 0x2000
	s_nop 0
	global_load_lds_dwordx4 v[224:225], off
	v_lshl_add_u64 v[224:225], s[42:43], 0, v[134:135]
	s_mov_b32 m0, s58
	s_nop 0
	global_load_lds_dwordx4 v[224:225], off
	s_mov_b32 m0, s59
	s_nop 0
	global_load_lds_dwordx4 v[226:227], off
	s_waitcnt vmcnt(8)
	s_waitcnt lgkmcnt(0)
	s_barrier
; #define PG8_STAGE(bufoff, gbase, voff) do { _Pragma("unroll") for (int _i = 0; _i < 2; ++_i) \
;         __builtin_amdgcn_global_load_lds((const unsigned*)((const char*)(gbase) + (voff)[_i]), (LAS unsigned*)(lds + (bufoff) + ldsw + _i * 8192), 16, 0, 0); } while (0)
; #define PG8_LDA(dst, b, h) do { _Pragma("unroll") for (int m = 0; m < 4; ++m) _Pragma("unroll") for (int k = 0; k < 2; ++k) dst[m][k] = *(const LAS bf16x8*)(lds + PG8_SA(b, h) + aoff + m * 2048 + k * 1024); } while (0)
; #define PG8_LDB(dst, b, h) do { _Pragma("unroll") for (int n = 0; n < 2; ++n) _Pragma("unroll") for (int k = 0; k < 2; ++k) dst[n][k] = *(const LAS bf16x8*)(lds + PG8_SB(b, h) + boff + n * 2048 + k * 1024); } while (0)
; #define PG8_MMA(ai, bj, At, Bt) do { __builtin_amdgcn_s_setprio(1); _Pragma("unroll") for (int m = 0; m < 4; ++m) _Pragma("unroll") for (int n = 0; n < 2; ++n) _Pragma("unroll") for (int k = 0; k < 2; ++k) \
;         acc[ai][bj][m][n] = __builtin_amdgcn_mfma_f32_16x16x32_bf16(Bt[n][k], At[m][k], acc[ai][bj][m][n], 0, 0, 0); __builtin_amdgcn_s_setprio(0); } while (0)
; #define PG8_WAIT_V(n) asm volatile("s_waitcnt vmcnt(" #n ")" ::: "memory")
; #define PG8_WAIT_L(n) asm volatile("s_waitcnt lgkmcnt(" #n ")" ::: "memory")
; #define PG8_BAR __builtin_amdgcn_s_barrier()
; #define PG8_SCHED __builtin_amdgcn_sched_barrier(0)
; template <class Epi, class Sched, bool ALIGN_EPI = true>
; __device__ __forceinline__ void gemm_phase(LAS unsigned char* lds, const Gemm g, const Sched& S, const Epi& E) {
;     ...
;             PG8_WAIT_V(8); PG8_WAIT_L(0); PG8_BAR; PG8_MMA(0, 0, At, B0); PG8_MMA(0, 1, At, B1); PG8_BAR; PG8_SCHED;
;             PG8_LDA(At, 0, 1); PG8_STAGE(PG8_SB(0, 0), b2, voffB); PG8_STAGE(PG8_SB(0, 1), b2 + hB, voffB); PG8_STAGE(PG8_SA(0, 0), a2, voffA);
;             PG8_WAIT_V(8); PG8_WAIT_L(0); PG8_BAR; PG8_MMA(1, 0, At, B0); PG8_MMA(1, 1, At, B1); PG8_BAR; PG8_SCHED;
;             PG8_LDB(B0, 1, 0); PG8_LDB(B1, 1, 1); PG8_SCHED; PG8_LDA(At, 1, 0); PG8_STAGE(PG8_SA(0, 1), a2 + hA, voffA);
;             PG8_WAIT_V(8); PG8_WAIT_L(0); PG8_BAR; PG8_MMA(0, 0, At, B0); PG8_MMA(0, 1, At, B1); PG8_BAR; PG8_SCHED;
	s_setprio 1
	s_waitcnt lgkmcnt(0)
	v_mfma_f32_16x16x32_bf16 v[64:67], v[140:143], v[184:187], 0
	v_mfma_f32_16x16x32_bf16 v[64:67], v[148:151], v[188:191], v[64:67]
	v_mfma_f32_16x16x32_bf16 v[60:63], v[152:155], v[184:187], 0
	v_mfma_f32_16x16x32_bf16 v[60:63], v[164:167], v[188:191], v[60:63]
	v_mfma_f32_16x16x32_bf16 v[56:59], v[140:143], v[192:195], 0
	v_mfma_f32_16x16x32_bf16 v[56:59], v[148:151], v[204:207], v[56:59]
	v_mfma_f32_16x16x32_bf16 v[48:51], v[152:155], v[192:195], 0
	v_mfma_f32_16x16x32_bf16 v[48:51], v[164:167], v[204:207], v[48:51]
	v_mfma_f32_16x16x32_bf16 v[40:43], v[140:143], v[208:211], 0
	v_mfma_f32_16x16x32_bf16 v[40:43], v[148:151], v[212:215], v[40:43]
	v_mfma_f32_16x16x32_bf16 v[32:35], v[152:155], v[208:211], 0
	v_mfma_f32_16x16x32_bf16 v[32:35], v[164:167], v[212:215], v[32:35]
	v_mfma_f32_16x16x32_bf16 v[24:27], v[140:143], v[216:219], 0
	v_mfma_f32_16x16x32_bf16 v[24:27], v[148:151], v[220:223], v[24:27]
	v_mfma_f32_16x16x32_bf16 v[16:19], v[152:155], v[216:219], 0
	v_mfma_f32_16x16x32_bf16 v[16:19], v[164:167], v[220:223], v[16:19]
	s_setprio 0
	s_setprio 1
	v_mfma_f32_16x16x32_bf16 v[52:55], v[168:171], v[184:187], 0
	v_mfma_f32_16x16x32_bf16 v[52:55], v[172:175], v[188:191], v[52:55]
	v_mfma_f32_16x16x32_bf16 v[44:47], v[176:179], v[184:187], 0
	v_mfma_f32_16x16x32_bf16 v[44:47], v[180:183], v[188:191], v[44:47]
	v_mfma_f32_16x16x32_bf16 v[36:39], v[168:171], v[192:195], 0
	v_mfma_f32_16x16x32_bf16 v[36:39], v[172:175], v[204:207], v[36:39]
	v_mfma_f32_16x16x32_bf16 v[28:31], v[176:179], v[192:195], 0
	v_mfma_f32_16x16x32_bf16 v[28:31], v[180:183], v[204:207], v[28:31]
	v_mfma_f32_16x16x32_bf16 v[20:23], v[168:171], v[208:211], 0
	v_mfma_f32_16x16x32_bf16 v[20:23], v[172:175], v[212:215], v[20:23]
	v_mfma_f32_16x16x32_bf16 v[12:15], v[176:179], v[208:211], 0
	v_mfma_f32_16x16x32_bf16 v[12:15], v[180:183], v[212:215], v[12:15]
	v_mfma_f32_16x16x32_bf16 v[8:11], v[168:171], v[216:219], 0
	v_mfma_f32_16x16x32_bf16 v[8:11], v[172:175], v[220:223], v[8:11]
	s_setprio 2
	s_barrier
	v_mfma_f32_16x16x32_bf16 v[4:7], v[176:179], v[216:219], 0
	v_mfma_f32_16x16x32_bf16 v[4:7], v[180:183], v[220:223], v[4:7]
	s_setprio 0
	s_add_i32 s27, 0, 0x18000
	v_add_u32_e32 v158, s27, v145
	s_add_i32 s65, 0, 0x1c000
	ds_read_b128 v[140:143], v158
	ds_read_b128 v[148:151], v158 offset:1024
	ds_read_b128 v[152:155], v158 offset:2048
	ds_read_b128 v[164:167], v158 offset:3072
	v_add_u32_e32 v158, s65, v145
	ds_read_b128 v[168:171], v158
	ds_read_b128 v[172:175], v158 offset:1024
	ds_read_b128 v[176:179], v158 offset:2048
	ds_read_b128 v[180:183], v158 offset:3072
	s_add_u32 s30, s42, 0x80000
	s_addc_u32 s31, s43, 0
	s_mov_b32 m0, s60
	v_lshl_add_u64 v[228:229], s[30:31], 0, v[134:135]
	ds_read_b128 v[184:187], v147 offset:32768
	ds_read_b128 v[188:191], v147 offset:33792
	ds_read_b128 v[192:195], v147 offset:34816
	ds_read_b128 v[204:207], v147 offset:35840
	ds_read_b128 v[208:211], v147 offset:36864
	ds_read_b128 v[212:215], v147 offset:37888
	ds_read_b128 v[216:219], v147 offset:38912
	ds_read_b128 v[220:223], v147 offset:39936
	global_load_lds_dwordx4 v[228:229], off
	v_lshl_add_u64 v[228:229], s[30:31], 0, v[132:133]
	s_mov_b32 m0, s61
	s_nop 0
	global_load_lds_dwordx4 v[228:229], off
	s_waitcnt vmcnt(8)
	s_waitcnt lgkmcnt(0)
	s_barrier
	s_setprio 1
	s_waitcnt lgkmcnt(0)
	v_mfma_f32_16x16x32_bf16 v[128:131], v[140:143], v[184:187], v[128:131]
	v_mfma_f32_16x16x32_bf16 v[128:131], v[148:151], v[188:191], v[128:131]
	v_mfma_f32_16x16x32_bf16 v[124:127], v[152:155], v[184:187], v[124:127]
	v_mfma_f32_16x16x32_bf16 v[124:127], v[164:167], v[188:191], v[124:127]
	v_mfma_f32_16x16x32_bf16 v[120:123], v[140:143], v[192:195], v[120:123]
	v_mfma_f32_16x16x32_bf16 v[120:123], v[148:151], v[204:207], v[120:123]
	v_mfma_f32_16x16x32_bf16 v[112:115], v[152:155], v[192:195], v[112:115]
	v_mfma_f32_16x16x32_bf16 v[112:115], v[164:167], v[204:207], v[112:115]
	v_mfma_f32_16x16x32_bf16 v[104:107], v[140:143], v[208:211], v[104:107]
	v_mfma_f32_16x16x32_bf16 v[104:107], v[148:151], v[212:215], v[104:107]
	v_mfma_f32_16x16x32_bf16 v[96:99], v[152:155], v[208:211], v[96:99]
	v_mfma_f32_16x16x32_bf16 v[96:99], v[164:167], v[212:215], v[96:99]
	v_mfma_f32_16x16x32_bf16 v[88:91], v[140:143], v[216:219], v[88:91]
	v_mfma_f32_16x16x32_bf16 v[88:91], v[148:151], v[220:223], v[88:91]
	v_mfma_f32_16x16x32_bf16 v[80:83], v[152:155], v[216:219], v[80:83]
	v_mfma_f32_16x16x32_bf16 v[80:83], v[164:167], v[220:223], v[80:83]
	s_setprio 0
	s_setprio 1
	v_mfma_f32_16x16x32_bf16 v[116:119], v[168:171], v[184:187], v[116:119]
	v_mfma_f32_16x16x32_bf16 v[116:119], v[172:175], v[188:191], v[116:119]
	v_mfma_f32_16x16x32_bf16 v[108:111], v[176:179], v[184:187], v[108:111]
	v_mfma_f32_16x16x32_bf16 v[108:111], v[180:183], v[188:191], v[108:111]
	v_mfma_f32_16x16x32_bf16 v[100:103], v[168:171], v[192:195], v[100:103]
	v_mfma_f32_16x16x32_bf16 v[100:103], v[172:175], v[204:207], v[100:103]
	v_mfma_f32_16x16x32_bf16 v[92:95], v[176:179], v[192:195], v[92:95]
	v_mfma_f32_16x16x32_bf16 v[92:95], v[180:183], v[204:207], v[92:95]
	v_mfma_f32_16x16x32_bf16 v[84:87], v[168:171], v[208:211], v[84:87]
	v_mfma_f32_16x16x32_bf16 v[84:87], v[172:175], v[212:215], v[84:87]
	v_mfma_f32_16x16x32_bf16 v[76:79], v[176:179], v[208:211], v[76:79]
	v_mfma_f32_16x16x32_bf16 v[76:79], v[180:183], v[212:215], v[76:79]
	v_mfma_f32_16x16x32_bf16 v[72:75], v[168:171], v[216:219], v[72:75]
	v_mfma_f32_16x16x32_bf16 v[72:75], v[172:175], v[220:223], v[72:75]
	s_setprio 2
	s_barrier
; #define PG8_STAGE(bufoff, gbase, voff) do { _Pragma("unroll") for (int _i = 0; _i < 2; ++_i) \
;         __builtin_amdgcn_global_load_lds((const unsigned*)((const char*)(gbase) + (voff)[_i]), (LAS unsigned*)(lds + (bufoff) + ldsw + _i * 8192), 16, 0, 0); } while (0)
; #define PG8_LDA(dst, b, h) do { _Pragma("unroll") for (int m = 0; m < 4; ++m) _Pragma("unroll") for (int k = 0; k < 2; ++k) dst[m][k] = *(const LAS bf16x8*)(lds + PG8_SA(b, h) + aoff + m * 2048 + k * 1024); } while (0)
; #define PG8_LDB(dst, b, h) do { _Pragma("unroll") for (int n = 0; n < 2; ++n) _Pragma("unroll") for (int k = 0; k < 2; ++k) dst[n][k] = *(const LAS bf16x8*)(lds + PG8_SB(b, h) + boff + n * 2048 + k * 1024); } while (0)
; #define PG8_WAIT_V(n) asm volatile("s_waitcnt vmcnt(" #n ")" ::: "memory")
; #define PG8_WAIT_L(n) asm volatile("s_waitcnt lgkmcnt(" #n ")" ::: "memory")
; template <class Epi, class Sched, bool ALIGN_EPI = true>
; __device__ __forceinline__ void gemm_phase(LAS unsigned char* lds, const Gemm g, const Sched& S, const Epi& E) {
;     ...
;             const bool last = (t == nt - 2);
;             const char* a1 = cA + (size_t)(t + 1) * kstep;
;             const char* a2 = last ? nA : cA + (size_t)(t + 2) * kstep; const char* b2 = last ? nB : cB + (size_t)(t + 2) * kstep;
;             const char* a3 = a2 + kstep; const char* b3 = b2 + kstep;
;             PG8_LDB(B0, 0, 0); PG8_LDB(B1, 0, 1); PG8_SCHED; PG8_LDA(At, 0, 0); PG8_STAGE(PG8_SA(1, 1), a1 + hA, voffA);
;             PG8_WAIT_V(8); PG8_WAIT_L(0); PG8_BAR; PG8_MMA(0, 0, At, B0); PG8_MMA(0, 1, At, B1); PG8_BAR; PG8_SCHED;
;             PG8_LDA(At, 0, 1); PG8_STAGE(PG8_SB(0, 0), b2, voffB); PG8_STAGE(PG8_SB(0, 1), b2 + hB, voffB); PG8_STAGE(PG8_SA(0, 0), a2, voffA);
;             PG8_WAIT_V(8); PG8_WAIT_L(0); PG8_BAR; PG8_MMA(1, 0, At, B0); PG8_MMA(1, 1, At, B1); PG8_BAR; PG8_SCHED;
;             PG8_LDB(B0, 1, 0); PG8_LDB(B1, 1, 1); PG8_SCHED; PG8_LDA(At, 1, 0); PG8_STAGE(PG8_SA(0, 1), a2 + hA, voffA);
;             PG8_WAIT_V(8); PG8_WAIT_L(0); PG8_BAR; PG8_MMA(0, 0, At, B0); PG8_MMA(0, 1, At, B1); PG8_BAR; PG8_SCHED;
;             PG8_LDA(At, 1, 1); PG8_STAGE(PG8_SB(1, 0), b3, voffB); PG8_STAGE(PG8_SB(1, 1), b3 + hB, voffB); PG8_STAGE(PG8_SA(1, 0), a3, voffA);
;             PG8_WAIT_V(8); PG8_WAIT_L(0); PG8_BAR; PG8_MMA(1, 0, At, B0); PG8_MMA(1, 1, At, B1); PG8_BAR; PG8_SCHED;
	v_mfma_f32_16x16x32_bf16 v[68:71], v[176:179], v[216:219], v[68:71]
	v_mfma_f32_16x16x32_bf16 v[68:71], v[180:183], v[220:223], v[68:71]
	s_setprio 0
	s_add_i32 s27, s27, s53
	v_lshl_add_u64 v[156:157], v[156:157], 0, s[86:87]
	s_mov_b32 m0, s27
	ds_read_b128 v[184:187], v147 offset:49152
	ds_read_b128 v[188:191], v147 offset:50176
	ds_read_b128 v[192:195], v147 offset:51200
	ds_read_b128 v[204:207], v147 offset:52224
	ds_read_b128 v[208:211], v147 offset:53248
	ds_read_b128 v[212:215], v147 offset:54272
	ds_read_b128 v[216:219], v147 offset:55296
	ds_read_b128 v[220:223], v147 offset:56320
	global_load_lds_dwordx4 v[156:157], off
	s_add_i32 m0, s27, 0x2000
	s_add_u32 s30, s40, 0x80080
	v_lshl_add_u64 v[156:157], v[196:197], 0, s[86:87]
	s_addc_u32 s31, s41, 0
	s_add_i32 s27, s65, s53
	global_load_lds_dwordx4 v[156:157], off
	v_lshl_add_u64 v[156:157], s[30:31], 0, v[2:3]
	s_mov_b32 m0, s27
	s_nop 0
	global_load_lds_dwordx4 v[156:157], off
	v_lshl_add_u64 v[156:157], s[30:31], 0, v[0:1]
	s_add_i32 m0, s27, 0x2000
	s_nop 0
	global_load_lds_dwordx4 v[156:157], off
	v_lshl_add_u64 v[156:157], v[224:225], 0, s[86:87]
	s_mov_b32 m0, s62
	s_nop 0
	global_load_lds_dwordx4 v[156:157], off
	v_lshl_add_u64 v[156:157], v[226:227], 0, s[86:87]
	s_mov_b32 m0, s63
	s_nop 0
	global_load_lds_dwordx4 v[156:157], off
	s_waitcnt vmcnt(8)
	s_waitcnt lgkmcnt(0)
	s_barrier
	s_setprio 1
	s_waitcnt lgkmcnt(0)
	v_mfma_f32_16x16x32_bf16 v[64:67], v[140:143], v[184:187], v[64:67]
	v_mfma_f32_16x16x32_bf16 v[64:67], v[148:151], v[188:191], v[64:67]
	v_mfma_f32_16x16x32_bf16 v[60:63], v[152:155], v[184:187], v[60:63]
	v_mfma_f32_16x16x32_bf16 v[60:63], v[164:167], v[188:191], v[60:63]
	v_mfma_f32_16x16x32_bf16 v[56:59], v[140:143], v[192:195], v[56:59]
	v_mfma_f32_16x16x32_bf16 v[56:59], v[148:151], v[204:207], v[56:59]
	v_mfma_f32_16x16x32_bf16 v[48:51], v[152:155], v[192:195], v[48:51]
	v_mfma_f32_16x16x32_bf16 v[48:51], v[164:167], v[204:207], v[48:51]
	v_mfma_f32_16x16x32_bf16 v[40:43], v[140:143], v[208:211], v[40:43]
	v_mfma_f32_16x16x32_bf16 v[40:43], v[148:151], v[212:215], v[40:43]
	v_mfma_f32_16x16x32_bf16 v[32:35], v[152:155], v[208:211], v[32:35]
	v_mfma_f32_16x16x32_bf16 v[32:35], v[164:167], v[212:215], v[32:35]
	v_mfma_f32_16x16x32_bf16 v[24:27], v[140:143], v[216:219], v[24:27]
	v_mfma_f32_16x16x32_bf16 v[24:27], v[148:151], v[220:223], v[24:27]
	v_mfma_f32_16x16x32_bf16 v[16:19], v[152:155], v[216:219], v[16:19]
	v_mfma_f32_16x16x32_bf16 v[16:19], v[164:167], v[220:223], v[16:19]
	s_setprio 0
	s_setprio 1
	v_mfma_f32_16x16x32_bf16 v[52:55], v[168:171], v[184:187], v[52:55]
	v_mfma_f32_16x16x32_bf16 v[52:55], v[172:175], v[188:191], v[52:55]
	v_mfma_f32_16x16x32_bf16 v[44:47], v[176:179], v[184:187], v[44:47]
	v_mfma_f32_16x16x32_bf16 v[44:47], v[180:183], v[188:191], v[44:47]
	v_mfma_f32_16x16x32_bf16 v[36:39], v[168:171], v[192:195], v[36:39]
	v_mfma_f32_16x16x32_bf16 v[36:39], v[172:175], v[204:207], v[36:39]
	v_mfma_f32_16x16x32_bf16 v[28:31], v[176:179], v[192:195], v[28:31]
	v_mfma_f32_16x16x32_bf16 v[28:31], v[180:183], v[204:207], v[28:31]
	v_mfma_f32_16x16x32_bf16 v[20:23], v[168:171], v[208:211], v[20:23]
	v_mfma_f32_16x16x32_bf16 v[20:23], v[172:175], v[212:215], v[20:23]
	v_mfma_f32_16x16x32_bf16 v[12:15], v[176:179], v[208:211], v[12:15]
	v_mfma_f32_16x16x32_bf16 v[12:15], v[180:183], v[212:215], v[12:15]
	v_mfma_f32_16x16x32_bf16 v[8:11], v[168:171], v[216:219], v[8:11]
	v_mfma_f32_16x16x32_bf16 v[8:11], v[172:175], v[220:223], v[8:11]
	s_setprio 2
	s_barrier
	v_mfma_f32_16x16x32_bf16 v[4:7], v[176:179], v[216:219], v[4:7]
	v_mfma_f32_16x16x32_bf16 v[4:7], v[180:183], v[220:223], v[4:7]
	s_setprio 0
	s_add_i32 s26, s26, 2
	s_add_u32 s38, s38, 0x100
	s_addc_u32 s39, s39, 0
	s_add_u32 s24, s24, 0x100
	s_addc_u32 s25, s25, 0
	s_cmp_gt_u32 s26, 29
	s_cbranch_scc1 .Lpeel_exit_218
.LBB0_218:
	s_add_u32 s27, s38, 0xfff80080
	s_addc_u32 s30, s39, -1
	s_add_i32 s31, 0, 0x10000
	s_cmp_eq_u32 s26, 28
	s_cselect_b32 s43, s11, s30
	s_cselect_b32 s42, s18, s27
	v_add_u32_e32 v156, s31, v145
	s_cselect_b32 s41, s9, s25
	s_cselect_b32 s40, s19, s24
	s_add_i32 s27, 0, 0x14000
	ds_read_b128 v[140:143], v156
	ds_read_b128 v[148:151], v156 offset:1024
	ds_read_b128 v[152:155], v156 offset:2048
	ds_read_b128 v[164:167], v156 offset:3072
	v_add_u32_e32 v156, s27, v145
	ds_read_b128 v[168:171], v156
	ds_read_b128 v[172:175], v156 offset:1024
	ds_read_b128 v[176:179], v156 offset:2048
	ds_read_b128 v[180:183], v156 offset:3072
	v_lshl_add_u64 v[156:157], s[38:39], 0, v[136:137]
	s_add_i32 m0, s58, 0xc000
	ds_read_b128 v[184:187], v147
	ds_read_b128 v[188:191], v147 offset:1024
	ds_read_b128 v[192:195], v147 offset:2048
	ds_read_b128 v[204:207], v147 offset:3072
	ds_read_b128 v[208:211], v147 offset:4096
	ds_read_b128 v[212:215], v147 offset:5120
	ds_read_b128 v[216:219], v147 offset:6144
	ds_read_b128 v[220:223], v147 offset:7168
	global_load_lds_dwordx4 v[156:157], off
	v_lshl_add_u64 v[156:157], s[38:39], 0, v[138:139]
	s_add_i32 m0, s58, 0xe000
	s_nop 0
	global_load_lds_dwordx4 v[156:157], off
	s_waitcnt vmcnt(8)
	s_waitcnt lgkmcnt(0)
	s_barrier
; #define PG8_STAGE(bufoff, gbase, voff) do { _Pragma("unroll") for (int _i = 0; _i < 2; ++_i) \
;         __builtin_amdgcn_global_load_lds((const unsigned*)((const char*)(gbase) + (voff)[_i]), (LAS unsigned*)(lds + (bufoff) + ldsw + _i * 8192), 16, 0, 0); } while (0)
; #define PG8_LDA(dst, b, h) do { _Pragma("unroll") for (int m = 0; m < 4; ++m) _Pragma("unroll") for (int k = 0; k < 2; ++k) dst[m][k] = *(const LAS bf16x8*)(lds + PG8_SA(b, h) + aoff + m * 2048 + k * 1024); } while (0)
; #define PG8_MMA(ai, bj, At, Bt) do { __builtin_amdgcn_s_setprio(1); _Pragma("unroll") for (int m = 0; m < 4; ++m) _Pragma("unroll") for (int n = 0; n < 2; ++n) _Pragma("unroll") for (int k = 0; k < 2; ++k) \
;         acc[ai][bj][m][n] = __builtin_amdgcn_mfma_f32_16x16x32_bf16(Bt[n][k], At[m][k], acc[ai][bj][m][n], 0, 0, 0); __builtin_amdgcn_s_setprio(0); } while (0)
; #define PG8_WAIT_V(n) asm volatile("s_waitcnt vmcnt(" #n ")" ::: "memory")
; #define PG8_WAIT_L(n) asm volatile("s_waitcnt lgkmcnt(" #n ")" ::: "memory")
; #define PG8_BAR __builtin_amdgcn_s_barrier()
; #define PG8_SCHED __builtin_amdgcn_sched_barrier(0)
; template <class Epi, class Sched, bool ALIGN_EPI = true>
; __device__ __forceinline__ void gemm_phase(LAS unsigned char* lds, const Gemm g, const Sched& S, const Epi& E) {
;     ...
;             PG8_WAIT_V(8); PG8_WAIT_L(0); PG8_BAR; PG8_MMA(0, 0, At, B0); PG8_MMA(0, 1, At, B1); PG8_BAR; PG8_SCHED;
;             PG8_LDA(At, 0, 1); PG8_STAGE(PG8_SB(0, 0), b2, voffB); PG8_STAGE(PG8_SB(0, 1), b2 + hB, voffB); PG8_STAGE(PG8_SA(0, 0), a2, voffA);
;             PG8_WAIT_V(8); PG8_WAIT_L(0); PG8_BAR; PG8_MMA(1, 0, At, B0); PG8_MMA(1, 1, At, B1); PG8_BAR; PG8_SCHED;
	s_setprio 1
	s_waitcnt lgkmcnt(0)
	v_mfma_f32_16x16x32_bf16 v[128:131], v[140:143], v[184:187], v[128:131]
	v_mfma_f32_16x16x32_bf16 v[128:131], v[148:151], v[188:191], v[128:131]
	v_mfma_f32_16x16x32_bf16 v[124:127], v[152:155], v[184:187], v[124:127]
	v_mfma_f32_16x16x32_bf16 v[124:127], v[164:167], v[188:191], v[124:127]
	v_mfma_f32_16x16x32_bf16 v[120:123], v[140:143], v[192:195], v[120:123]
	v_mfma_f32_16x16x32_bf16 v[120:123], v[148:151], v[204:207], v[120:123]
	v_mfma_f32_16x16x32_bf16 v[112:115], v[152:155], v[192:195], v[112:115]
	v_mfma_f32_16x16x32_bf16 v[112:115], v[164:167], v[204:207], v[112:115]
	v_mfma_f32_16x16x32_bf16 v[104:107], v[140:143], v[208:211], v[104:107]
	v_mfma_f32_16x16x32_bf16 v[104:107], v[148:151], v[212:215], v[104:107]
	v_mfma_f32_16x16x32_bf16 v[96:99], v[152:155], v[208:211], v[96:99]
	v_mfma_f32_16x16x32_bf16 v[96:99], v[164:167], v[212:215], v[96:99]
	v_mfma_f32_16x16x32_bf16 v[88:91], v[140:143], v[216:219], v[88:91]
	v_mfma_f32_16x16x32_bf16 v[88:91], v[148:151], v[220:223], v[88:91]
	v_mfma_f32_16x16x32_bf16 v[80:83], v[152:155], v[216:219], v[80:83]
	v_mfma_f32_16x16x32_bf16 v[80:83], v[164:167], v[220:223], v[80:83]
	s_setprio 0
	s_setprio 1
	v_mfma_f32_16x16x32_bf16 v[116:119], v[168:171], v[184:187], v[116:119]
	v_mfma_f32_16x16x32_bf16 v[116:119], v[172:175], v[188:191], v[116:119]
	v_mfma_f32_16x16x32_bf16 v[108:111], v[176:179], v[184:187], v[108:111]
	v_mfma_f32_16x16x32_bf16 v[108:111], v[180:183], v[188:191], v[108:111]
	v_mfma_f32_16x16x32_bf16 v[100:103], v[168:171], v[192:195], v[100:103]
	v_mfma_f32_16x16x32_bf16 v[100:103], v[172:175], v[204:207], v[100:103]
	v_mfma_f32_16x16x32_bf16 v[92:95], v[176:179], v[192:195], v[92:95]
	v_mfma_f32_16x16x32_bf16 v[92:95], v[180:183], v[204:207], v[92:95]
	v_mfma_f32_16x16x32_bf16 v[84:87], v[168:171], v[208:211], v[84:87]
	v_mfma_f32_16x16x32_bf16 v[84:87], v[172:175], v[212:215], v[84:87]
	v_mfma_f32_16x16x32_bf16 v[76:79], v[176:179], v[208:211], v[76:79]
	v_mfma_f32_16x16x32_bf16 v[76:79], v[180:183], v[212:215], v[76:79]
	v_mfma_f32_16x16x32_bf16 v[72:75], v[168:171], v[216:219], v[72:75]
	v_mfma_f32_16x16x32_bf16 v[72:75], v[172:175], v[220:223], v[72:75]
	s_setprio 2
	s_barrier
	v_mfma_f32_16x16x32_bf16 v[68:71], v[176:179], v[216:219], v[68:71]
	v_mfma_f32_16x16x32_bf16 v[68:71], v[180:183], v[220:223], v[68:71]
	s_setprio 0
	s_add_i32 s30, s31, s53
	v_lshl_add_u64 v[156:157], s[40:41], 0, v[2:3]
	s_mov_b32 m0, s30
	ds_read_b128 v[184:187], v147 offset:16384
	ds_read_b128 v[188:191], v147 offset:17408
	ds_read_b128 v[192:195], v147 offset:18432
	ds_read_b128 v[204:207], v147 offset:19456
	ds_read_b128 v[208:211], v147 offset:20480
	ds_read_b128 v[212:215], v147 offset:21504
	ds_read_b128 v[216:219], v147 offset:22528
	ds_read_b128 v[220:223], v147 offset:23552
	global_load_lds_dwordx4 v[156:157], off
	s_add_i32 m0, s30, 0x2000
	s_add_u32 s30, s40, 0x80000
	v_lshl_add_u64 v[196:197], s[40:41], 0, v[0:1]
	s_addc_u32 s31, s41, 0
	s_add_i32 s27, s27, s53
	global_load_lds_dwordx4 v[196:197], off
	v_lshl_add_u64 v[224:225], s[30:31], 0, v[2:3]
	s_mov_b32 m0, s27
	v_lshl_add_u64 v[226:227], s[42:43], 0, v[132:133]
	global_load_lds_dwordx4 v[224:225], off
	v_lshl_add_u64 v[224:225], s[30:31], 0, v[0:1]
	s_add_i32 m0, s27, 0x2000
	s_nop 0
	global_load_lds_dwordx4 v[224:225], off
	v_lshl_add_u64 v[224:225], s[42:43], 0, v[134:135]
	s_mov_b32 m0, s58
	s_nop 0
	global_load_lds_dwordx4 v[224:225], off
	s_mov_b32 m0, s59
	s_nop 0
	global_load_lds_dwordx4 v[226:227], off
	s_waitcnt vmcnt(8)
	s_waitcnt lgkmcnt(0)
	s_barrier
	s_setprio 1
	s_waitcnt lgkmcnt(0)
	v_mfma_f32_16x16x32_bf16 v[64:67], v[140:143], v[184:187], v[64:67]
	v_mfma_f32_16x16x32_bf16 v[64:67], v[148:151], v[188:191], v[64:67]
	v_mfma_f32_16x16x32_bf16 v[60:63], v[152:155], v[184:187], v[60:63]
	v_mfma_f32_16x16x32_bf16 v[60:63], v[164:167], v[188:191], v[60:63]
	v_mfma_f32_16x16x32_bf16 v[56:59], v[140:143], v[192:195], v[56:59]
	v_mfma_f32_16x16x32_bf16 v[56:59], v[148:151], v[204:207], v[56:59]
	v_mfma_f32_16x16x32_bf16 v[48:51], v[152:155], v[192:195], v[48:51]
	v_mfma_f32_16x16x32_bf16 v[48:51], v[164:167], v[204:207], v[48:51]
	v_mfma_f32_16x16x32_bf16 v[40:43], v[140:143], v[208:211], v[40:43]
	v_mfma_f32_16x16x32_bf16 v[40:43], v[148:151], v[212:215], v[40:43]
	v_mfma_f32_16x16x32_bf16 v[32:35], v[152:155], v[208:211], v[32:35]
	v_mfma_f32_16x16x32_bf16 v[32:35], v[164:167], v[212:215], v[32:35]
	v_mfma_f32_16x16x32_bf16 v[24:27], v[140:143], v[216:219], v[24:27]
	v_mfma_f32_16x16x32_bf16 v[24:27], v[148:151], v[220:223], v[24:27]
	v_mfma_f32_16x16x32_bf16 v[16:19], v[152:155], v[216:219], v[16:19]
	v_mfma_f32_16x16x32_bf16 v[16:19], v[164:167], v[220:223], v[16:19]
	s_setprio 0
	s_setprio 1
	v_mfma_f32_16x16x32_bf16 v[52:55], v[168:171], v[184:187], v[52:55]
	v_mfma_f32_16x16x32_bf16 v[52:55], v[172:175], v[188:191], v[52:55]
	v_mfma_f32_16x16x32_bf16 v[44:47], v[176:179], v[184:187], v[44:47]
	v_mfma_f32_16x16x32_bf16 v[44:47], v[180:183], v[188:191], v[44:47]
	v_mfma_f32_16x16x32_bf16 v[36:39], v[168:171], v[192:195], v[36:39]
	v_mfma_f32_16x16x32_bf16 v[36:39], v[172:175], v[204:207], v[36:39]
	v_mfma_f32_16x16x32_bf16 v[28:31], v[176:179], v[192:195], v[28:31]
	v_mfma_f32_16x16x32_bf16 v[28:31], v[180:183], v[204:207], v[28:31]
	v_mfma_f32_16x16x32_bf16 v[20:23], v[168:171], v[208:211], v[20:23]
	v_mfma_f32_16x16x32_bf16 v[20:23], v[172:175], v[212:215], v[20:23]
	v_mfma_f32_16x16x32_bf16 v[12:15], v[176:179], v[208:211], v[12:15]
	v_mfma_f32_16x16x32_bf16 v[12:15], v[180:183], v[212:215], v[12:15]
	v_mfma_f32_16x16x32_bf16 v[8:11], v[168:171], v[216:219], v[8:11]
	v_mfma_f32_16x16x32_bf16 v[8:11], v[172:175], v[220:223], v[8:11]
	s_setprio 2
	s_barrier
; #define PG8_STAGE(bufoff, gbase, voff) do { _Pragma("unroll") for (int _i = 0; _i < 2; ++_i) \
;         __builtin_amdgcn_global_load_lds((const unsigned*)((const char*)(gbase) + (voff)[_i]), (LAS unsigned*)(lds + (bufoff) + ldsw + _i * 8192), 16, 0, 0); } while (0)
; #define PG8_LDA(dst, b, h) do { _Pragma("unroll") for (int m = 0; m < 4; ++m) _Pragma("unroll") for (int k = 0; k < 2; ++k) dst[m][k] = *(const LAS bf16x8*)(lds + PG8_SA(b, h) + aoff + m * 2048 + k * 1024); } while (0)
; #define PG8_LDB(dst, b, h) do { _Pragma("unroll") for (int n = 0; n < 2; ++n) _Pragma("unroll") for (int k = 0; k < 2; ++k) dst[n][k] = *(const LAS bf16x8*)(lds + PG8_SB(b, h) + boff + n * 2048 + k * 1024); } while (0)
; #define PG8_MMA(ai, bj, At, Bt) do { __builtin_amdgcn_s_setprio(1); _Pragma("unroll") for (int m = 0; m < 4; ++m) _Pragma("unroll") for (int n = 0; n < 2; ++n) _Pragma("unroll") for (int k = 0; k < 2; ++k) \
;         acc[ai][bj][m][n] = __builtin_amdgcn_mfma_f32_16x16x32_bf16(Bt[n][k], At[m][k], acc[ai][bj][m][n], 0, 0, 0); __builtin_amdgcn_s_setprio(0); } while (0)
; #define PG8_WAIT_V(n) asm volatile("s_waitcnt vmcnt(" #n ")" ::: "memory")
; #define PG8_WAIT_L(n) asm volatile("s_waitcnt lgkmcnt(" #n ")" ::: "memory")
; #define PG8_BAR __builtin_amdgcn_s_barrier()
; #define PG8_SCHED __builtin_amdgcn_sched_barrier(0)
; template <class Epi, class Sched, bool ALIGN_EPI = true>
; __device__ __forceinline__ void gemm_phase(LAS unsigned char* lds, const Gemm g, const Sched& S, const Epi& E) {
;     ...
;             PG8_WAIT_V(8); PG8_WAIT_L(0); PG8_BAR; PG8_MMA(1, 0, At, B0); PG8_MMA(1, 1, At, B1); PG8_BAR; PG8_SCHED;
;             PG8_LDB(B0, 1, 0); PG8_LDB(B1, 1, 1); PG8_SCHED; PG8_LDA(At, 1, 0); PG8_STAGE(PG8_SA(0, 1), a2 + hA, voffA);
;             PG8_WAIT_V(8); PG8_WAIT_L(0); PG8_BAR; PG8_MMA(0, 0, At, B0); PG8_MMA(0, 1, At, B1); PG8_BAR; PG8_SCHED;
	v_mfma_f32_16x16x32_bf16 v[4:7], v[176:179], v[216:219], v[4:7]
	v_mfma_f32_16x16x32_bf16 v[4:7], v[180:183], v[220:223], v[4:7]
	s_setprio 0
	s_add_i32 s27, 0, 0x18000
	v_add_u32_e32 v158, s27, v145
	s_add_i32 s65, 0, 0x1c000
	ds_read_b128 v[140:143], v158
	ds_read_b128 v[148:151], v158 offset:1024
	ds_read_b128 v[152:155], v158 offset:2048
	ds_read_b128 v[164:167], v158 offset:3072
	v_add_u32_e32 v158, s65, v145
	ds_read_b128 v[168:171], v158
	ds_read_b128 v[172:175], v158 offset:1024
	ds_read_b128 v[176:179], v158 offset:2048
	ds_read_b128 v[180:183], v158 offset:3072
	s_add_u32 s30, s42, 0x80000
	s_addc_u32 s31, s43, 0
	s_mov_b32 m0, s60
	v_lshl_add_u64 v[228:229], s[30:31], 0, v[134:135]
	ds_read_b128 v[184:187], v147 offset:32768
	ds_read_b128 v[188:191], v147 offset:33792
	ds_read_b128 v[192:195], v147 offset:34816
	ds_read_b128 v[204:207], v147 offset:35840
	ds_read_b128 v[208:211], v147 offset:36864
	ds_read_b128 v[212:215], v147 offset:37888
	ds_read_b128 v[216:219], v147 offset:38912
	ds_read_b128 v[220:223], v147 offset:39936
	global_load_lds_dwordx4 v[228:229], off
	v_lshl_add_u64 v[228:229], s[30:31], 0, v[132:133]
	s_mov_b32 m0, s61
	s_nop 0
	global_load_lds_dwordx4 v[228:229], off
	s_waitcnt vmcnt(8)
	s_waitcnt lgkmcnt(0)
	s_barrier
	s_setprio 1
	s_waitcnt lgkmcnt(0)
	v_mfma_f32_16x16x32_bf16 v[128:131], v[140:143], v[184:187], v[128:131]
	v_mfma_f32_16x16x32_bf16 v[128:131], v[148:151], v[188:191], v[128:131]
	v_mfma_f32_16x16x32_bf16 v[124:127], v[152:155], v[184:187], v[124:127]
	v_mfma_f32_16x16x32_bf16 v[124:127], v[164:167], v[188:191], v[124:127]
	v_mfma_f32_16x16x32_bf16 v[120:123], v[140:143], v[192:195], v[120:123]
	v_mfma_f32_16x16x32_bf16 v[120:123], v[148:151], v[204:207], v[120:123]
	v_mfma_f32_16x16x32_bf16 v[112:115], v[152:155], v[192:195], v[112:115]
	v_mfma_f32_16x16x32_bf16 v[112:115], v[164:167], v[204:207], v[112:115]
	v_mfma_f32_16x16x32_bf16 v[104:107], v[140:143], v[208:211], v[104:107]
	v_mfma_f32_16x16x32_bf16 v[104:107], v[148:151], v[212:215], v[104:107]
	v_mfma_f32_16x16x32_bf16 v[96:99], v[152:155], v[208:211], v[96:99]
	v_mfma_f32_16x16x32_bf16 v[96:99], v[164:167], v[212:215], v[96:99]
	v_mfma_f32_16x16x32_bf16 v[88:91], v[140:143], v[216:219], v[88:91]
	v_mfma_f32_16x16x32_bf16 v[88:91], v[148:151], v[220:223], v[88:91]
	v_mfma_f32_16x16x32_bf16 v[80:83], v[152:155], v[216:219], v[80:83]
	v_mfma_f32_16x16x32_bf16 v[80:83], v[164:167], v[220:223], v[80:83]
	s_setprio 0
	s_setprio 1
	v_mfma_f32_16x16x32_bf16 v[116:119], v[168:171], v[184:187], v[116:119]
	v_mfma_f32_16x16x32_bf16 v[116:119], v[172:175], v[188:191], v[116:119]
	v_mfma_f32_16x16x32_bf16 v[108:111], v[176:179], v[184:187], v[108:111]
	v_mfma_f32_16x16x32_bf16 v[108:111], v[180:183], v[188:191], v[108:111]
	v_mfma_f32_16x16x32_bf16 v[100:103], v[168:171], v[192:195], v[100:103]
	v_mfma_f32_16x16x32_bf16 v[100:103], v[172:175], v[204:207], v[100:103]
	v_mfma_f32_16x16x32_bf16 v[92:95], v[176:179], v[192:195], v[92:95]
	v_mfma_f32_16x16x32_bf16 v[92:95], v[180:183], v[204:207], v[92:95]
	v_mfma_f32_16x16x32_bf16 v[84:87], v[168:171], v[208:211], v[84:87]
	v_mfma_f32_16x16x32_bf16 v[84:87], v[172:175], v[212:215], v[84:87]
	v_mfma_f32_16x16x32_bf16 v[76:79], v[176:179], v[208:211], v[76:79]
	v_mfma_f32_16x16x32_bf16 v[76:79], v[180:183], v[212:215], v[76:79]
	v_mfma_f32_16x16x32_bf16 v[72:75], v[168:171], v[216:219], v[72:75]
	v_mfma_f32_16x16x32_bf16 v[72:75], v[172:175], v[220:223], v[72:75]
	s_setprio 2
	s_barrier
; #define PG8_STAGE(bufoff, gbase, voff) do { _Pragma("unroll") for (int _i = 0; _i < 2; ++_i) \
;         __builtin_amdgcn_global_load_lds((const unsigned*)((const char*)(gbase) + (voff)[_i]), (LAS unsigned*)(lds + (bufoff) + ldsw + _i * 8192), 16, 0, 0); } while (0)
; #define PG8_LDA(dst, b, h) do { _Pragma("unroll") for (int m = 0; m < 4; ++m) _Pragma("unroll") for (int k = 0; k < 2; ++k) dst[m][k] = *(const LAS bf16x8*)(lds + PG8_SA(b, h) + aoff + m * 2048 + k * 1024); } while (0)
; #define PG8_MMA(ai, bj, At, Bt) do { __builtin_amdgcn_s_setprio(1); _Pragma("unroll") for (int m = 0; m < 4; ++m) _Pragma("unroll") for (int n = 0; n < 2; ++n) _Pragma("unroll") for (int k = 0; k < 2; ++k) \
;         acc[ai][bj][m][n] = __builtin_amdgcn_mfma_f32_16x16x32_bf16(Bt[n][k], At[m][k], acc[ai][bj][m][n], 0, 0, 0); __builtin_amdgcn_s_setprio(0); } while (0)
; #define PG8_WAIT_V(n) asm volatile("s_waitcnt vmcnt(" #n ")" ::: "memory")
; #define PG8_WAIT_L(n) asm volatile("s_waitcnt lgkmcnt(" #n ")" ::: "memory")
; #define PG8_BAR __builtin_amdgcn_s_barrier()
; #define PG8_SCHED __builtin_amdgcn_sched_barrier(0)
; template <class Epi, class Sched, bool ALIGN_EPI = true>
; __device__ __forceinline__ void gemm_phase(LAS unsigned char* lds, const Gemm g, const Sched& S, const Epi& E) {
;     ...
;             PG8_WAIT_V(8); PG8_WAIT_L(0); PG8_BAR; PG8_MMA(0, 0, At, B0); PG8_MMA(0, 1, At, B1); PG8_BAR; PG8_SCHED;
;             PG8_LDA(At, 1, 1); PG8_STAGE(PG8_SB(1, 0), b3, voffB); PG8_STAGE(PG8_SB(1, 1), b3 + hB, voffB); PG8_STAGE(PG8_SA(1, 0), a3, voffA);
;             PG8_WAIT_V(8); PG8_WAIT_L(0); PG8_BAR; PG8_MMA(1, 0, At, B0); PG8_MMA(1, 1, At, B1); PG8_BAR; PG8_SCHED;
	v_mfma_f32_16x16x32_bf16 v[68:71], v[176:179], v[216:219], v[68:71]
	v_mfma_f32_16x16x32_bf16 v[68:71], v[180:183], v[220:223], v[68:71]
	s_setprio 0
	s_add_i32 s27, s27, s53
	v_lshl_add_u64 v[156:157], v[156:157], 0, s[86:87]
	s_mov_b32 m0, s27
	ds_read_b128 v[184:187], v147 offset:49152
	ds_read_b128 v[188:191], v147 offset:50176
	ds_read_b128 v[192:195], v147 offset:51200
	ds_read_b128 v[204:207], v147 offset:52224
	ds_read_b128 v[208:211], v147 offset:53248
	ds_read_b128 v[212:215], v147 offset:54272
	ds_read_b128 v[216:219], v147 offset:55296
	ds_read_b128 v[220:223], v147 offset:56320
	global_load_lds_dwordx4 v[156:157], off
	s_add_i32 m0, s27, 0x2000
	s_add_u32 s30, s40, 0x80080
	v_lshl_add_u64 v[156:157], v[196:197], 0, s[86:87]
	s_addc_u32 s31, s41, 0
	s_add_i32 s27, s65, s53
	global_load_lds_dwordx4 v[156:157], off
	v_lshl_add_u64 v[156:157], s[30:31], 0, v[2:3]
	s_mov_b32 m0, s27
	s_nop 0
	global_load_lds_dwordx4 v[156:157], off
	v_lshl_add_u64 v[156:157], s[30:31], 0, v[0:1]
	s_add_i32 m0, s27, 0x2000
	s_nop 0
	global_load_lds_dwordx4 v[156:157], off
	v_lshl_add_u64 v[156:157], v[224:225], 0, s[86:87]
	s_mov_b32 m0, s62
	s_nop 0
	global_load_lds_dwordx4 v[156:157], off
	v_lshl_add_u64 v[156:157], v[226:227], 0, s[86:87]
	s_mov_b32 m0, s63
	s_nop 0
	global_load_lds_dwordx4 v[156:157], off
	s_waitcnt vmcnt(8)
	s_waitcnt lgkmcnt(0)
	s_barrier
	s_setprio 1
	s_waitcnt lgkmcnt(0)
	v_mfma_f32_16x16x32_bf16 v[64:67], v[140:143], v[184:187], v[64:67]
	v_mfma_f32_16x16x32_bf16 v[64:67], v[148:151], v[188:191], v[64:67]
	v_mfma_f32_16x16x32_bf16 v[60:63], v[152:155], v[184:187], v[60:63]
	v_mfma_f32_16x16x32_bf16 v[60:63], v[164:167], v[188:191], v[60:63]
	v_mfma_f32_16x16x32_bf16 v[56:59], v[140:143], v[192:195], v[56:59]
	v_mfma_f32_16x16x32_bf16 v[56:59], v[148:151], v[204:207], v[56:59]
	v_mfma_f32_16x16x32_bf16 v[48:51], v[152:155], v[192:195], v[48:51]
	v_mfma_f32_16x16x32_bf16 v[48:51], v[164:167], v[204:207], v[48:51]
	v_mfma_f32_16x16x32_bf16 v[40:43], v[140:143], v[208:211], v[40:43]
	v_mfma_f32_16x16x32_bf16 v[40:43], v[148:151], v[212:215], v[40:43]
	v_mfma_f32_16x16x32_bf16 v[32:35], v[152:155], v[208:211], v[32:35]
	v_mfma_f32_16x16x32_bf16 v[32:35], v[164:167], v[212:215], v[32:35]
	v_mfma_f32_16x16x32_bf16 v[24:27], v[140:143], v[216:219], v[24:27]
	v_mfma_f32_16x16x32_bf16 v[24:27], v[148:151], v[220:223], v[24:27]
	v_mfma_f32_16x16x32_bf16 v[16:19], v[152:155], v[216:219], v[16:19]
	v_mfma_f32_16x16x32_bf16 v[16:19], v[164:167], v[220:223], v[16:19]
	s_setprio 0
	s_setprio 1
	v_mfma_f32_16x16x32_bf16 v[52:55], v[168:171], v[184:187], v[52:55]
	v_mfma_f32_16x16x32_bf16 v[52:55], v[172:175], v[188:191], v[52:55]
	v_mfma_f32_16x16x32_bf16 v[44:47], v[176:179], v[184:187], v[44:47]
	v_mfma_f32_16x16x32_bf16 v[44:47], v[180:183], v[188:191], v[44:47]
	v_mfma_f32_16x16x32_bf16 v[36:39], v[168:171], v[192:195], v[36:39]
	v_mfma_f32_16x16x32_bf16 v[36:39], v[172:175], v[204:207], v[36:39]
	v_mfma_f32_16x16x32_bf16 v[28:31], v[176:179], v[192:195], v[28:31]
	v_mfma_f32_16x16x32_bf16 v[28:31], v[180:183], v[204:207], v[28:31]
	v_mfma_f32_16x16x32_bf16 v[20:23], v[168:171], v[208:211], v[20:23]
	v_mfma_f32_16x16x32_bf16 v[20:23], v[172:175], v[212:215], v[20:23]
	v_mfma_f32_16x16x32_bf16 v[12:15], v[176:179], v[208:211], v[12:15]
	v_mfma_f32_16x16x32_bf16 v[12:15], v[180:183], v[212:215], v[12:15]
	v_mfma_f32_16x16x32_bf16 v[8:11], v[168:171], v[216:219], v[8:11]
	v_mfma_f32_16x16x32_bf16 v[8:11], v[172:175], v[220:223], v[8:11]
	s_setprio 2
	s_barrier
	v_mfma_f32_16x16x32_bf16 v[4:7], v[176:179], v[216:219], v[4:7]
	v_mfma_f32_16x16x32_bf16 v[4:7], v[180:183], v[220:223], v[4:7]
	s_setprio 0
	s_add_i32 s26, s26, 2
	s_add_u32 s38, s38, 0x100
	s_addc_u32 s39, s39, 0
	s_add_u32 s24, s24, 0x100
	s_addc_u32 s25, s25, 0
	s_cmp_gt_u32 s26, 29
	s_cbranch_scc0 .LBB0_218

;     __device__ bool next(int i, Unit& u) const { if (i >= 2) return false; const int x = c & 7, j = c >> 3; u.pm = 32 * i + 4 * x + (j & 3); u.pn = j >> 2; return true; }
; #define PG8_STAGE(bufoff, gbase, voff) do { _Pragma("unroll") for (int _i = 0; _i < 2; ++_i) \
;         __builtin_amdgcn_global_load_lds((const unsigned*)((const char*)(gbase) + (voff)[_i]), (LAS unsigned*)(lds + (bufoff) + ldsw + _i * 8192), 16, 0, 0); } while (0)
; #define PG8_LDA(dst, b, h) do { _Pragma("unroll") for (int m = 0; m < 4; ++m) _Pragma("unroll") for (int k = 0; k < 2; ++k) dst[m][k] = *(const LAS bf16x8*)(lds + PG8_SA(b, h) + aoff + m * 2048 + k * 1024); } while (0)
; #define PG8_LDB(dst, b, h) do { _Pragma("unroll") for (int n = 0; n < 2; ++n) _Pragma("unroll") for (int k = 0; k < 2; ++k) dst[n][k] = *(const LAS bf16x8*)(lds + PG8_SB(b, h) + boff + n * 2048 + k * 1024); } while (0)
; #define PG8_WAIT_V(n) asm volatile("s_waitcnt vmcnt(" #n ")" ::: "memory")
; #define PG8_WAIT_L(n) asm volatile("s_waitcnt lgkmcnt(" #n ")" ::: "memory")
; #define PG8_BAR __builtin_amdgcn_s_barrier()
; #define PG8_SCHED __builtin_amdgcn_sched_barrier(0)
; template <class Epi, class Sched, bool ALIGN_EPI = true>
; __device__ __forceinline__ void gemm_phase(LAS unsigned char* lds, const Gemm g, const Sched& S, const Epi& E) {
;     ...
;         const bool has_next = S.next(ui + 1, nxt);
;         const char* nA = has_next ? (const char*)g.A + ((size_t)nxt.pm * BM * g.lda + (size_t)nxt.pn * g.a_pn_off) * 2 : cA; const char* nB = has_next ? (const char*)g.Bt + (size_t)nxt.pn * BM * g.ldb * 2 : cB;
;         for (int t = 0; t < nt; t += 2) {
;             const bool last = (t == nt - 2);
;             const char* a1 = cA + (size_t)(t + 1) * kstep;
;             const char* a2 = last ? nA : cA + (size_t)(t + 2) * kstep; const char* b2 = last ? nB : cB + (size_t)(t + 2) * kstep;
;             const char* a3 = a2 + kstep; const char* b3 = b2 + kstep;
;             PG8_LDB(B0, 0, 0); PG8_LDB(B1, 0, 1); PG8_SCHED; PG8_LDA(At, 0, 0); PG8_STAGE(PG8_SA(1, 1), a1 + hA, voffA);
;             PG8_WAIT_V(8); PG8_WAIT_L(0); PG8_BAR; PG8_MMA(0, 0, At, B0); PG8_MMA(0, 1, At, B1); PG8_BAR; PG8_SCHED;
;             PG8_LDA(At, 0, 1); PG8_STAGE(PG8_SB(0, 0), b2, voffB); PG8_STAGE(PG8_SB(0, 1), b2 + hB, voffB); PG8_STAGE(PG8_SA(0, 0), a2, voffA);
.LBB0_666:
	s_mov_b32 s82, s81
	s_or_b32 s81, s17, s68
	s_mov_b64 s[10:11], s[12:13]
	s_lshl_b32 s12, s81, 20
	s_add_u32 s12, s28, s12
	s_addc_u32 s13, s29, 0
	s_and_b64 s[16:17], s[38:39], exec
	s_cselect_b32 s16, s13, s11
	s_cselect_b32 s17, s12, s10
	s_add_u32 s18, s10, 0x100
	s_addc_u32 s19, s11, 0
	s_add_u32 s10, s10, 0x80080
	s_addc_u32 s11, s11, 0
	v_lshl_add_u64 v[132:133], s[10:11], 0, v[166:167]
	v_lshl_add_u64 v[134:135], s[10:11], 0, v[168:169]
	s_mov_b32 s24, -2
	s_mov_b64 s[10:11], 0
	s_add_u32 vcc_lo, s10, 0x100
	s_addc_u32 vcc_hi, s11, 0
	s_add_u32 s25, s18, s10
	s_addc_u32 s26, s19, s11
	s_add_i32 s27, 0, 0x10000
	s_cmp_eq_u32 s24, 28
	s_cselect_b32 s65, s16, s26
	s_cselect_b32 s26, 0, vcc_lo
	s_cselect_b32 s64, s17, s25
	s_cselect_b32 s25, 0, vcc_hi
	s_add_u32 s62, s14, s26
	v_add_u32_e32 v160, s27, v186
	s_addc_u32 s63, s15, s25
	s_add_i32 s25, 0, 0x14000
	ds_read_b128 v[136:139], v160
	ds_read_b128 v[140:143], v160 offset:1024
	ds_read_b128 v[144:147], v160 offset:2048
	ds_read_b128 v[170:173], v160 offset:3072
	v_add_u32_e32 v160, s25, v186
	ds_read_b128 v[174:177], v160
	ds_read_b128 v[178:181], v160 offset:1024
	ds_read_b128 v[182:185], v160 offset:2048
	ds_read_b128 v[208:211], v160 offset:3072
	v_lshl_add_u64 v[244:245], v[132:133], 0, s[10:11]
	s_add_i32 m0, s53, 0xc000
	ds_read_b128 v[212:215], v197
	ds_read_b128 v[216:219], v197 offset:1024
	ds_read_b128 v[220:223], v197 offset:2048
	ds_read_b128 v[224:227], v197 offset:3072
	ds_read_b128 v[228:231], v197 offset:4096
	ds_read_b128 v[232:235], v197 offset:5120
	ds_read_b128 v[236:239], v197 offset:6144
	ds_read_b128 v[240:243], v197 offset:7168
	global_load_lds_dwordx4 v[244:245], off
	v_lshl_add_u64 v[244:245], v[134:135], 0, s[10:11]
	s_add_i32 m0, s53, 0xe000
	s_nop 0
	global_load_lds_dwordx4 v[244:245], off
	s_waitcnt vmcnt(8)
	s_waitcnt lgkmcnt(0)
	s_barrier
	s_setprio 1
	s_waitcnt lgkmcnt(0)
	v_mfma_f32_16x16x32_bf16 v[36:39], v[136:139], v[212:215], 0
	v_mfma_f32_16x16x32_bf16 v[36:39], v[140:143], v[216:219], v[36:39]
	v_mfma_f32_16x16x32_bf16 v[40:43], v[144:147], v[212:215], 0
	v_mfma_f32_16x16x32_bf16 v[40:43], v[170:173], v[216:219], v[40:43]
	v_mfma_f32_16x16x32_bf16 v[68:71], v[136:139], v[220:223], 0
	v_mfma_f32_16x16x32_bf16 v[68:71], v[140:143], v[224:227], v[68:71]
	v_mfma_f32_16x16x32_bf16 v[72:75], v[144:147], v[220:223], 0
	v_mfma_f32_16x16x32_bf16 v[72:75], v[170:173], v[224:227], v[72:75]
	v_mfma_f32_16x16x32_bf16 v[100:103], v[136:139], v[228:231], 0
	v_mfma_f32_16x16x32_bf16 v[100:103], v[140:143], v[232:235], v[100:103]
	v_mfma_f32_16x16x32_bf16 v[104:107], v[144:147], v[228:231], 0
	v_mfma_f32_16x16x32_bf16 v[104:107], v[170:173], v[232:235], v[104:107]
	v_mfma_f32_16x16x32_bf16 v[128:131], v[136:139], v[236:239], 0
	v_mfma_f32_16x16x32_bf16 v[128:131], v[140:143], v[240:243], v[128:131]
	v_mfma_f32_16x16x32_bf16 v[124:127], v[144:147], v[236:239], 0
	v_mfma_f32_16x16x32_bf16 v[124:127], v[170:173], v[240:243], v[124:127]
	s_setprio 0
	s_setprio 1
	v_mfma_f32_16x16x32_bf16 v[8:11], v[174:177], v[212:215], 0
	v_mfma_f32_16x16x32_bf16 v[8:11], v[178:181], v[216:219], v[8:11]
	v_mfma_f32_16x16x32_bf16 v[4:7], v[182:185], v[212:215], 0
	v_mfma_f32_16x16x32_bf16 v[4:7], v[208:211], v[216:219], v[4:7]
	v_mfma_f32_16x16x32_bf16 v[32:35], v[174:177], v[220:223], 0
	v_mfma_f32_16x16x32_bf16 v[32:35], v[178:181], v[224:227], v[32:35]
	v_mfma_f32_16x16x32_bf16 v[28:31], v[182:185], v[220:223], 0
	v_mfma_f32_16x16x32_bf16 v[28:31], v[208:211], v[224:227], v[28:31]
	v_mfma_f32_16x16x32_bf16 v[56:59], v[174:177], v[228:231], 0
	v_mfma_f32_16x16x32_bf16 v[56:59], v[178:181], v[232:235], v[56:59]
	v_mfma_f32_16x16x32_bf16 v[52:55], v[182:185], v[228:231], 0
	v_mfma_f32_16x16x32_bf16 v[52:55], v[208:211], v[232:235], v[52:55]
	v_mfma_f32_16x16x32_bf16 v[80:83], v[174:177], v[236:239], 0
	v_mfma_f32_16x16x32_bf16 v[80:83], v[178:181], v[240:243], v[80:83]
	s_setprio 2
	s_barrier
	v_mfma_f32_16x16x32_bf16 v[76:79], v[182:185], v[236:239], 0
	v_mfma_f32_16x16x32_bf16 v[76:79], v[208:211], v[240:243], v[76:79]
	s_setprio 0
	s_add_i32 s10, s27, s67
	v_lshl_add_u64 v[244:245], s[62:63], 0, v[2:3]
	s_mov_b32 m0, s10
	ds_read_b128 v[212:215], v197 offset:16384
	ds_read_b128 v[216:219], v197 offset:17408
	ds_read_b128 v[220:223], v197 offset:18432
	ds_read_b128 v[224:227], v197 offset:19456
	ds_read_b128 v[228:231], v197 offset:20480
	ds_read_b128 v[232:235], v197 offset:21504
	ds_read_b128 v[236:239], v197 offset:22528
	ds_read_b128 v[240:243], v197 offset:23552
	global_load_lds_dwordx4 v[244:245], off
	s_add_i32 m0, s10, 0x2000
	s_add_u32 s10, s62, 0x80000
	v_lshl_add_u64 v[246:247], s[62:63], 0, v[150:151]
	s_addc_u32 s11, s63, 0
	s_add_i32 s25, s25, s67
	global_load_lds_dwordx4 v[246:247], off
	v_lshl_add_u64 v[248:249], s[10:11], 0, v[2:3]
	s_mov_b32 m0, s25
	v_lshl_add_u64 v[160:161], s[64:65], 0, v[148:149]
	global_load_lds_dwordx4 v[248:249], off
	v_lshl_add_u64 v[248:249], s[10:11], 0, v[150:151]
	s_add_i32 m0, s25, 0x2000
	s_nop 0
	global_load_lds_dwordx4 v[248:249], off
	v_lshl_add_u64 v[248:249], s[64:65], 0, v[0:1]
	s_mov_b32 m0, s53
	s_nop 0
	global_load_lds_dwordx4 v[248:249], off
	s_mov_b32 m0, s66
	s_nop 0
	global_load_lds_dwordx4 v[160:161], off
	s_waitcnt vmcnt(8)
	s_waitcnt lgkmcnt(0)
	s_barrier
; #define PG8_STAGE(bufoff, gbase, voff) do { _Pragma("unroll") for (int _i = 0; _i < 2; ++_i) \
;         __builtin_amdgcn_global_load_lds((const unsigned*)((const char*)(gbase) + (voff)[_i]), (LAS unsigned*)(lds + (bufoff) + ldsw + _i * 8192), 16, 0, 0); } while (0)
; #define PG8_LDA(dst, b, h) do { _Pragma("unroll") for (int m = 0; m < 4; ++m) _Pragma("unroll") for (int k = 0; k < 2; ++k) dst[m][k] = *(const LAS bf16x8*)(lds + PG8_SA(b, h) + aoff + m * 2048 + k * 1024); } while (0)
; #define PG8_LDB(dst, b, h) do { _Pragma("unroll") for (int n = 0; n < 2; ++n) _Pragma("unroll") for (int k = 0; k < 2; ++k) dst[n][k] = *(const LAS bf16x8*)(lds + PG8_SB(b, h) + boff + n * 2048 + k * 1024); } while (0)
; #define PG8_MMA(ai, bj, At, Bt) do { __builtin_amdgcn_s_setprio(1); _Pragma("unroll") for (int m = 0; m < 4; ++m) _Pragma("unroll") for (int n = 0; n < 2; ++n) _Pragma("unroll") for (int k = 0; k < 2; ++k) \
;         acc[ai][bj][m][n] = __builtin_amdgcn_mfma_f32_16x16x32_bf16(Bt[n][k], At[m][k], acc[ai][bj][m][n], 0, 0, 0); __builtin_amdgcn_s_setprio(0); } while (0)
; #define PG8_WAIT_V(n) asm volatile("s_waitcnt vmcnt(" #n ")" ::: "memory")
; #define PG8_WAIT_L(n) asm volatile("s_waitcnt lgkmcnt(" #n ")" ::: "memory")
; #define PG8_BAR __builtin_amdgcn_s_barrier()
; #define PG8_SCHED __builtin_amdgcn_sched_barrier(0)
; template <class Epi, class Sched, bool ALIGN_EPI = true>
; __device__ __forceinline__ void gemm_phase(LAS unsigned char* lds, const Gemm g, const Sched& S, const Epi& E) {
;     ...
;             PG8_WAIT_V(8); PG8_WAIT_L(0); PG8_BAR; PG8_MMA(0, 0, At, B0); PG8_MMA(0, 1, At, B1); PG8_BAR; PG8_SCHED;
;             PG8_LDA(At, 0, 1); PG8_STAGE(PG8_SB(0, 0), b2, voffB); PG8_STAGE(PG8_SB(0, 1), b2 + hB, voffB); PG8_STAGE(PG8_SA(0, 0), a2, voffA);
;             PG8_WAIT_V(8); PG8_WAIT_L(0); PG8_BAR; PG8_MMA(1, 0, At, B0); PG8_MMA(1, 1, At, B1); PG8_BAR; PG8_SCHED;
;             PG8_LDB(B0, 1, 0); PG8_LDB(B1, 1, 1); PG8_SCHED; PG8_LDA(At, 1, 0); PG8_STAGE(PG8_SA(0, 1), a2 + hA, voffA);
;             PG8_WAIT_V(8); PG8_WAIT_L(0); PG8_BAR; PG8_MMA(0, 0, At, B0); PG8_MMA(0, 1, At, B1); PG8_BAR; PG8_SCHED;
	s_setprio 1
	s_waitcnt lgkmcnt(0)
	v_mfma_f32_16x16x32_bf16 v[120:123], v[136:139], v[212:215], 0
	v_mfma_f32_16x16x32_bf16 v[120:123], v[140:143], v[216:219], v[120:123]
	v_mfma_f32_16x16x32_bf16 v[116:119], v[144:147], v[212:215], 0
	v_mfma_f32_16x16x32_bf16 v[116:119], v[170:173], v[216:219], v[116:119]
	v_mfma_f32_16x16x32_bf16 v[96:99], v[136:139], v[220:223], 0
	v_mfma_f32_16x16x32_bf16 v[96:99], v[140:143], v[224:227], v[96:99]
	v_mfma_f32_16x16x32_bf16 v[92:95], v[144:147], v[220:223], 0
	v_mfma_f32_16x16x32_bf16 v[92:95], v[170:173], v[224:227], v[92:95]
	v_mfma_f32_16x16x32_bf16 v[64:67], v[136:139], v[228:231], 0
	v_mfma_f32_16x16x32_bf16 v[64:67], v[140:143], v[232:235], v[64:67]
	v_mfma_f32_16x16x32_bf16 v[60:63], v[144:147], v[228:231], 0
	v_mfma_f32_16x16x32_bf16 v[60:63], v[170:173], v[232:235], v[60:63]
	v_mfma_f32_16x16x32_bf16 v[24:27], v[136:139], v[236:239], 0
	v_mfma_f32_16x16x32_bf16 v[24:27], v[140:143], v[240:243], v[24:27]
	v_mfma_f32_16x16x32_bf16 v[20:23], v[144:147], v[236:239], 0
	v_mfma_f32_16x16x32_bf16 v[20:23], v[170:173], v[240:243], v[20:23]
	s_setprio 0
	s_setprio 1
	v_mfma_f32_16x16x32_bf16 v[112:115], v[174:177], v[212:215], 0
	v_mfma_f32_16x16x32_bf16 v[112:115], v[178:181], v[216:219], v[112:115]
	v_mfma_f32_16x16x32_bf16 v[108:111], v[182:185], v[212:215], 0
	v_mfma_f32_16x16x32_bf16 v[108:111], v[208:211], v[216:219], v[108:111]
	v_mfma_f32_16x16x32_bf16 v[88:91], v[174:177], v[220:223], 0
	v_mfma_f32_16x16x32_bf16 v[88:91], v[178:181], v[224:227], v[88:91]
	v_mfma_f32_16x16x32_bf16 v[84:87], v[182:185], v[220:223], 0
	v_mfma_f32_16x16x32_bf16 v[84:87], v[208:211], v[224:227], v[84:87]
	v_mfma_f32_16x16x32_bf16 v[48:51], v[174:177], v[228:231], 0
	v_mfma_f32_16x16x32_bf16 v[48:51], v[178:181], v[232:235], v[48:51]
	v_mfma_f32_16x16x32_bf16 v[44:47], v[182:185], v[228:231], 0
	v_mfma_f32_16x16x32_bf16 v[44:47], v[208:211], v[232:235], v[44:47]
	v_mfma_f32_16x16x32_bf16 v[16:19], v[174:177], v[236:239], 0
	v_mfma_f32_16x16x32_bf16 v[16:19], v[178:181], v[240:243], v[16:19]
	s_setprio 2
	s_barrier
	v_mfma_f32_16x16x32_bf16 v[12:15], v[182:185], v[236:239], 0
	v_mfma_f32_16x16x32_bf16 v[12:15], v[208:211], v[240:243], v[12:15]
	s_setprio 0
	s_add_i32 s25, 0, 0x18000
	v_add_u32_e32 v162, s25, v186
	s_add_i32 s26, 0, 0x1c000
	ds_read_b128 v[136:139], v162
	ds_read_b128 v[140:143], v162 offset:1024
	ds_read_b128 v[144:147], v162 offset:2048
	ds_read_b128 v[170:173], v162 offset:3072
	v_add_u32_e32 v162, s26, v186
	ds_read_b128 v[174:177], v162
	ds_read_b128 v[178:181], v162 offset:1024
	ds_read_b128 v[182:185], v162 offset:2048
	ds_read_b128 v[208:211], v162 offset:3072
	s_add_u32 s10, s64, 0x80000
	s_addc_u32 s11, s65, 0
	s_mov_b32 m0, s75
	v_lshl_add_u64 v[162:163], s[10:11], 0, v[0:1]
	ds_read_b128 v[212:215], v197 offset:32768
	ds_read_b128 v[216:219], v197 offset:33792
	ds_read_b128 v[220:223], v197 offset:34816
	ds_read_b128 v[224:227], v197 offset:35840
	ds_read_b128 v[228:231], v197 offset:36864
	ds_read_b128 v[232:235], v197 offset:37888
	ds_read_b128 v[236:239], v197 offset:38912
	ds_read_b128 v[240:243], v197 offset:39936
	global_load_lds_dwordx4 v[162:163], off
	v_lshl_add_u64 v[162:163], s[10:11], 0, v[148:149]
	s_mov_b32 m0, s76
	s_nop 0
	global_load_lds_dwordx4 v[162:163], off
	s_waitcnt vmcnt(8)
	s_waitcnt lgkmcnt(0)
	s_barrier
	s_setprio 1
	s_waitcnt lgkmcnt(0)
	v_mfma_f32_16x16x32_bf16 v[36:39], v[136:139], v[212:215], v[36:39]
	v_mfma_f32_16x16x32_bf16 v[36:39], v[140:143], v[216:219], v[36:39]
	v_mfma_f32_16x16x32_bf16 v[40:43], v[144:147], v[212:215], v[40:43]
	v_mfma_f32_16x16x32_bf16 v[40:43], v[170:173], v[216:219], v[40:43]
	v_mfma_f32_16x16x32_bf16 v[68:71], v[136:139], v[220:223], v[68:71]
	v_mfma_f32_16x16x32_bf16 v[68:71], v[140:143], v[224:227], v[68:71]
	v_mfma_f32_16x16x32_bf16 v[72:75], v[144:147], v[220:223], v[72:75]
	v_mfma_f32_16x16x32_bf16 v[72:75], v[170:173], v[224:227], v[72:75]
	v_mfma_f32_16x16x32_bf16 v[100:103], v[136:139], v[228:231], v[100:103]
	v_mfma_f32_16x16x32_bf16 v[100:103], v[140:143], v[232:235], v[100:103]
	v_mfma_f32_16x16x32_bf16 v[104:107], v[144:147], v[228:231], v[104:107]
	v_mfma_f32_16x16x32_bf16 v[104:107], v[170:173], v[232:235], v[104:107]
	v_mfma_f32_16x16x32_bf16 v[128:131], v[136:139], v[236:239], v[128:131]
	v_mfma_f32_16x16x32_bf16 v[128:131], v[140:143], v[240:243], v[128:131]
	v_mfma_f32_16x16x32_bf16 v[124:127], v[144:147], v[236:239], v[124:127]
	v_mfma_f32_16x16x32_bf16 v[124:127], v[170:173], v[240:243], v[124:127]
	s_setprio 0
	s_setprio 1
	v_mfma_f32_16x16x32_bf16 v[8:11], v[174:177], v[212:215], v[8:11]
	v_mfma_f32_16x16x32_bf16 v[8:11], v[178:181], v[216:219], v[8:11]
	v_mfma_f32_16x16x32_bf16 v[4:7], v[182:185], v[212:215], v[4:7]
	v_mfma_f32_16x16x32_bf16 v[4:7], v[208:211], v[216:219], v[4:7]
	v_mfma_f32_16x16x32_bf16 v[32:35], v[174:177], v[220:223], v[32:35]
	v_mfma_f32_16x16x32_bf16 v[32:35], v[178:181], v[224:227], v[32:35]
	v_mfma_f32_16x16x32_bf16 v[28:31], v[182:185], v[220:223], v[28:31]
	v_mfma_f32_16x16x32_bf16 v[28:31], v[208:211], v[224:227], v[28:31]
	v_mfma_f32_16x16x32_bf16 v[56:59], v[174:177], v[228:231], v[56:59]
	v_mfma_f32_16x16x32_bf16 v[56:59], v[178:181], v[232:235], v[56:59]
	v_mfma_f32_16x16x32_bf16 v[52:55], v[182:185], v[228:231], v[52:55]
	v_mfma_f32_16x16x32_bf16 v[52:55], v[208:211], v[232:235], v[52:55]
	v_mfma_f32_16x16x32_bf16 v[80:83], v[174:177], v[236:239], v[80:83]
	v_mfma_f32_16x16x32_bf16 v[80:83], v[178:181], v[240:243], v[80:83]
	s_setprio 2
	s_barrier
; #define PG8_STAGE(bufoff, gbase, voff) do { _Pragma("unroll") for (int _i = 0; _i < 2; ++_i) \
;         __builtin_amdgcn_global_load_lds((const unsigned*)((const char*)(gbase) + (voff)[_i]), (LAS unsigned*)(lds + (bufoff) + ldsw + _i * 8192), 16, 0, 0); } while (0)
; #define PG8_LDA(dst, b, h) do { _Pragma("unroll") for (int m = 0; m < 4; ++m) _Pragma("unroll") for (int k = 0; k < 2; ++k) dst[m][k] = *(const LAS bf16x8*)(lds + PG8_SA(b, h) + aoff + m * 2048 + k * 1024); } while (0)
; #define PG8_LDB(dst, b, h) do { _Pragma("unroll") for (int n = 0; n < 2; ++n) _Pragma("unroll") for (int k = 0; k < 2; ++k) dst[n][k] = *(const LAS bf16x8*)(lds + PG8_SB(b, h) + boff + n * 2048 + k * 1024); } while (0)
; #define PG8_WAIT_V(n) asm volatile("s_waitcnt vmcnt(" #n ")" ::: "memory")
; #define PG8_WAIT_L(n) asm volatile("s_waitcnt lgkmcnt(" #n ")" ::: "memory")
; template <class Epi, class Sched, bool ALIGN_EPI = true>
; __device__ __forceinline__ void gemm_phase(LAS unsigned char* lds, const Gemm g, const Sched& S, const Epi& E) {
;     ...
;             const bool last = (t == nt - 2);
;             const char* a1 = cA + (size_t)(t + 1) * kstep;
;             const char* a2 = last ? nA : cA + (size_t)(t + 2) * kstep; const char* b2 = last ? nB : cB + (size_t)(t + 2) * kstep;
;             const char* a3 = a2 + kstep; const char* b3 = b2 + kstep;
;             PG8_LDB(B0, 0, 0); PG8_LDB(B1, 0, 1); PG8_SCHED; PG8_LDA(At, 0, 0); PG8_STAGE(PG8_SA(1, 1), a1 + hA, voffA);
;             PG8_WAIT_V(8); PG8_WAIT_L(0); PG8_BAR; PG8_MMA(0, 0, At, B0); PG8_MMA(0, 1, At, B1); PG8_BAR; PG8_SCHED;
;             PG8_LDA(At, 0, 1); PG8_STAGE(PG8_SB(0, 0), b2, voffB); PG8_STAGE(PG8_SB(0, 1), b2 + hB, voffB); PG8_STAGE(PG8_SA(0, 0), a2, voffA);
;             PG8_WAIT_V(8); PG8_WAIT_L(0); PG8_BAR; PG8_MMA(1, 0, At, B0); PG8_MMA(1, 1, At, B1); PG8_BAR; PG8_SCHED;
;             PG8_LDB(B0, 1, 0); PG8_LDB(B1, 1, 1); PG8_SCHED; PG8_LDA(At, 1, 0); PG8_STAGE(PG8_SA(0, 1), a2 + hA, voffA);
;             PG8_WAIT_V(8); PG8_WAIT_L(0); PG8_BAR; PG8_MMA(0, 0, At, B0); PG8_MMA(0, 1, At, B1); PG8_BAR; PG8_SCHED;
;             PG8_LDA(At, 1, 1); PG8_STAGE(PG8_SB(1, 0), b3, voffB); PG8_STAGE(PG8_SB(1, 1), b3 + hB, voffB); PG8_STAGE(PG8_SA(1, 0), a3, voffA);
;             PG8_WAIT_V(8); PG8_WAIT_L(0); PG8_BAR; PG8_MMA(1, 0, At, B0); PG8_MMA(1, 1, At, B1); PG8_BAR; PG8_SCHED;
	v_mfma_f32_16x16x32_bf16 v[76:79], v[182:185], v[236:239], v[76:79]
	v_mfma_f32_16x16x32_bf16 v[76:79], v[208:211], v[240:243], v[76:79]
	s_setprio 0
	s_add_i32 s10, s25, s67
	v_lshl_add_u64 v[162:163], v[244:245], 0, s[86:87]
	s_mov_b32 m0, s10
	ds_read_b128 v[212:215], v197 offset:49152
	ds_read_b128 v[216:219], v197 offset:50176
	ds_read_b128 v[220:223], v197 offset:51200
	ds_read_b128 v[224:227], v197 offset:52224
	ds_read_b128 v[228:231], v197 offset:53248
	ds_read_b128 v[232:235], v197 offset:54272
	ds_read_b128 v[236:239], v197 offset:55296
	ds_read_b128 v[240:243], v197 offset:56320
	global_load_lds_dwordx4 v[162:163], off
	s_add_i32 m0, s10, 0x2000
	s_add_u32 s10, s62, 0x80080
	v_lshl_add_u64 v[162:163], v[246:247], 0, s[86:87]
	s_addc_u32 s11, s63, 0
	s_add_i32 s25, s26, s67
	global_load_lds_dwordx4 v[162:163], off
	v_lshl_add_u64 v[162:163], s[10:11], 0, v[2:3]
	s_mov_b32 m0, s25
	v_lshl_add_u64 v[160:161], v[160:161], 0, s[86:87]
	global_load_lds_dwordx4 v[162:163], off
	v_lshl_add_u64 v[162:163], s[10:11], 0, v[150:151]
	s_add_i32 m0, s25, 0x2000
	s_nop 0
	global_load_lds_dwordx4 v[162:163], off
	v_lshl_add_u64 v[162:163], v[248:249], 0, s[86:87]
	s_mov_b32 m0, s79
	s_nop 0
	global_load_lds_dwordx4 v[162:163], off
	s_mov_b32 m0, s80
	s_nop 0
	global_load_lds_dwordx4 v[160:161], off
	s_waitcnt vmcnt(8)
	s_waitcnt lgkmcnt(0)
	s_barrier
	s_setprio 1
	s_waitcnt lgkmcnt(0)
	v_mfma_f32_16x16x32_bf16 v[120:123], v[136:139], v[212:215], v[120:123]
	v_mfma_f32_16x16x32_bf16 v[120:123], v[140:143], v[216:219], v[120:123]
	v_mfma_f32_16x16x32_bf16 v[116:119], v[144:147], v[212:215], v[116:119]
	v_mfma_f32_16x16x32_bf16 v[116:119], v[170:173], v[216:219], v[116:119]
	v_mfma_f32_16x16x32_bf16 v[96:99], v[136:139], v[220:223], v[96:99]
	v_mfma_f32_16x16x32_bf16 v[96:99], v[140:143], v[224:227], v[96:99]
	v_mfma_f32_16x16x32_bf16 v[92:95], v[144:147], v[220:223], v[92:95]
	v_mfma_f32_16x16x32_bf16 v[92:95], v[170:173], v[224:227], v[92:95]
	v_mfma_f32_16x16x32_bf16 v[64:67], v[136:139], v[228:231], v[64:67]
	v_mfma_f32_16x16x32_bf16 v[64:67], v[140:143], v[232:235], v[64:67]
	v_mfma_f32_16x16x32_bf16 v[60:63], v[144:147], v[228:231], v[60:63]
	v_mfma_f32_16x16x32_bf16 v[60:63], v[170:173], v[232:235], v[60:63]
	v_mfma_f32_16x16x32_bf16 v[24:27], v[136:139], v[236:239], v[24:27]
	v_mfma_f32_16x16x32_bf16 v[24:27], v[140:143], v[240:243], v[24:27]
	v_mfma_f32_16x16x32_bf16 v[20:23], v[144:147], v[236:239], v[20:23]
	v_mfma_f32_16x16x32_bf16 v[20:23], v[170:173], v[240:243], v[20:23]
	s_setprio 0
	s_setprio 1
	v_mfma_f32_16x16x32_bf16 v[112:115], v[174:177], v[212:215], v[112:115]
	v_mfma_f32_16x16x32_bf16 v[112:115], v[178:181], v[216:219], v[112:115]
	v_mfma_f32_16x16x32_bf16 v[108:111], v[182:185], v[212:215], v[108:111]
	v_mfma_f32_16x16x32_bf16 v[108:111], v[208:211], v[216:219], v[108:111]
	v_mfma_f32_16x16x32_bf16 v[88:91], v[174:177], v[220:223], v[88:91]
	v_mfma_f32_16x16x32_bf16 v[88:91], v[178:181], v[224:227], v[88:91]
	v_mfma_f32_16x16x32_bf16 v[84:87], v[182:185], v[220:223], v[84:87]
	v_mfma_f32_16x16x32_bf16 v[84:87], v[208:211], v[224:227], v[84:87]
	v_mfma_f32_16x16x32_bf16 v[48:51], v[174:177], v[228:231], v[48:51]
	v_mfma_f32_16x16x32_bf16 v[48:51], v[178:181], v[232:235], v[48:51]
	v_mfma_f32_16x16x32_bf16 v[44:47], v[182:185], v[228:231], v[44:47]
	v_mfma_f32_16x16x32_bf16 v[44:47], v[208:211], v[232:235], v[44:47]
	v_mfma_f32_16x16x32_bf16 v[16:19], v[174:177], v[236:239], v[16:19]
	v_mfma_f32_16x16x32_bf16 v[16:19], v[178:181], v[240:243], v[16:19]
	s_setprio 2
	s_barrier
	v_mfma_f32_16x16x32_bf16 v[12:15], v[182:185], v[236:239], v[12:15]
	v_mfma_f32_16x16x32_bf16 v[12:15], v[208:211], v[240:243], v[12:15]
	s_setprio 0
	s_add_i32 s24, s24, 2
	s_cmp_gt_u32 s24, 29
	s_mov_b64 s[10:11], vcc
	s_cbranch_scc1 .Lpeel_exit_667
.LBB0_667:
	s_add_u32 vcc_lo, s10, 0x100
	s_addc_u32 vcc_hi, s11, 0
	s_add_u32 s25, s18, s10
	s_addc_u32 s26, s19, s11
	s_add_i32 s27, 0, 0x10000
	s_cmp_eq_u32 s24, 28
	s_cselect_b32 s65, s16, s26
	s_cselect_b32 s26, 0, vcc_lo
	s_cselect_b32 s64, s17, s25
	s_cselect_b32 s25, 0, vcc_hi
	s_add_u32 s62, s14, s26
	v_add_u32_e32 v160, s27, v186
	s_addc_u32 s63, s15, s25
	s_add_i32 s25, 0, 0x14000
	ds_read_b128 v[136:139], v160
	ds_read_b128 v[140:143], v160 offset:1024
	ds_read_b128 v[144:147], v160 offset:2048
	ds_read_b128 v[170:173], v160 offset:3072
	v_add_u32_e32 v160, s25, v186
	ds_read_b128 v[174:177], v160
	ds_read_b128 v[178:181], v160 offset:1024
	ds_read_b128 v[182:185], v160 offset:2048
	ds_read_b128 v[208:211], v160 offset:3072
	v_lshl_add_u64 v[244:245], v[132:133], 0, s[10:11]
	s_add_i32 m0, s53, 0xc000
	ds_read_b128 v[212:215], v197
	ds_read_b128 v[216:219], v197 offset:1024
	ds_read_b128 v[220:223], v197 offset:2048
	ds_read_b128 v[224:227], v197 offset:3072
	ds_read_b128 v[228:231], v197 offset:4096
	ds_read_b128 v[232:235], v197 offset:5120
	ds_read_b128 v[236:239], v197 offset:6144
	ds_read_b128 v[240:243], v197 offset:7168
	global_load_lds_dwordx4 v[244:245], off
	v_lshl_add_u64 v[244:245], v[134:135], 0, s[10:11]
	s_add_i32 m0, s53, 0xe000
	s_nop 0
	global_load_lds_dwordx4 v[244:245], off
	s_waitcnt vmcnt(8)
	s_waitcnt lgkmcnt(0)
	s_barrier
; #define PG8_STAGE(bufoff, gbase, voff) do { _Pragma("unroll") for (int _i = 0; _i < 2; ++_i) \
;         __builtin_amdgcn_global_load_lds((const unsigned*)((const char*)(gbase) + (voff)[_i]), (LAS unsigned*)(lds + (bufoff) + ldsw + _i * 8192), 16, 0, 0); } while (0)
; #define PG8_LDA(dst, b, h) do { _Pragma("unroll") for (int m = 0; m < 4; ++m) _Pragma("unroll") for (int k = 0; k < 2; ++k) dst[m][k] = *(const LAS bf16x8*)(lds + PG8_SA(b, h) + aoff + m * 2048 + k * 1024); } while (0)
; #define PG8_MMA(ai, bj, At, Bt) do { __builtin_amdgcn_s_setprio(1); _Pragma("unroll") for (int m = 0; m < 4; ++m) _Pragma("unroll") for (int n = 0; n < 2; ++n) _Pragma("unroll") for (int k = 0; k < 2; ++k) \
;         acc[ai][bj][m][n] = __builtin_amdgcn_mfma_f32_16x16x32_bf16(Bt[n][k], At[m][k], acc[ai][bj][m][n], 0, 0, 0); __builtin_amdgcn_s_setprio(0); } while (0)
; #define PG8_WAIT_V(n) asm volatile("s_waitcnt vmcnt(" #n ")" ::: "memory")
; #define PG8_WAIT_L(n) asm volatile("s_waitcnt lgkmcnt(" #n ")" ::: "memory")
; #define PG8_BAR __builtin_amdgcn_s_barrier()
; #define PG8_SCHED __builtin_amdgcn_sched_barrier(0)
; template <class Epi, class Sched, bool ALIGN_EPI = true>
; __device__ __forceinline__ void gemm_phase(LAS unsigned char* lds, const Gemm g, const Sched& S, const Epi& E) {
;     ...
;             PG8_WAIT_V(8); PG8_WAIT_L(0); PG8_BAR; PG8_MMA(0, 0, At, B0); PG8_MMA(0, 1, At, B1); PG8_BAR; PG8_SCHED;
;             PG8_LDA(At, 0, 1); PG8_STAGE(PG8_SB(0, 0), b2, voffB); PG8_STAGE(PG8_SB(0, 1), b2 + hB, voffB); PG8_STAGE(PG8_SA(0, 0), a2, voffA);
;             PG8_WAIT_V(8); PG8_WAIT_L(0); PG8_BAR; PG8_MMA(1, 0, At, B0); PG8_MMA(1, 1, At, B1); PG8_BAR; PG8_SCHED;
	s_setprio 1
	s_waitcnt lgkmcnt(0)
	v_mfma_f32_16x16x32_bf16 v[36:39], v[136:139], v[212:215], v[36:39]
	v_mfma_f32_16x16x32_bf16 v[36:39], v[140:143], v[216:219], v[36:39]
	v_mfma_f32_16x16x32_bf16 v[40:43], v[144:147], v[212:215], v[40:43]
	v_mfma_f32_16x16x32_bf16 v[40:43], v[170:173], v[216:219], v[40:43]
	v_mfma_f32_16x16x32_bf16 v[68:71], v[136:139], v[220:223], v[68:71]
	v_mfma_f32_16x16x32_bf16 v[68:71], v[140:143], v[224:227], v[68:71]
	v_mfma_f32_16x16x32_bf16 v[72:75], v[144:147], v[220:223], v[72:75]
	v_mfma_f32_16x16x32_bf16 v[72:75], v[170:173], v[224:227], v[72:75]
	v_mfma_f32_16x16x32_bf16 v[100:103], v[136:139], v[228:231], v[100:103]
	v_mfma_f32_16x16x32_bf16 v[100:103], v[140:143], v[232:235], v[100:103]
	v_mfma_f32_16x16x32_bf16 v[104:107], v[144:147], v[228:231], v[104:107]
	v_mfma_f32_16x16x32_bf16 v[104:107], v[170:173], v[232:235], v[104:107]
	v_mfma_f32_16x16x32_bf16 v[128:131], v[136:139], v[236:239], v[128:131]
	v_mfma_f32_16x16x32_bf16 v[128:131], v[140:143], v[240:243], v[128:131]
	v_mfma_f32_16x16x32_bf16 v[124:127], v[144:147], v[236:239], v[124:127]
	v_mfma_f32_16x16x32_bf16 v[124:127], v[170:173], v[240:243], v[124:127]
	s_setprio 0
	s_setprio 1
	v_mfma_f32_16x16x32_bf16 v[8:11], v[174:177], v[212:215], v[8:11]
	v_mfma_f32_16x16x32_bf16 v[8:11], v[178:181], v[216:219], v[8:11]
	v_mfma_f32_16x16x32_bf16 v[4:7], v[182:185], v[212:215], v[4:7]
	v_mfma_f32_16x16x32_bf16 v[4:7], v[208:211], v[216:219], v[4:7]
	v_mfma_f32_16x16x32_bf16 v[32:35], v[174:177], v[220:223], v[32:35]
	v_mfma_f32_16x16x32_bf16 v[32:35], v[178:181], v[224:227], v[32:35]
	v_mfma_f32_16x16x32_bf16 v[28:31], v[182:185], v[220:223], v[28:31]
	v_mfma_f32_16x16x32_bf16 v[28:31], v[208:211], v[224:227], v[28:31]
	v_mfma_f32_16x16x32_bf16 v[56:59], v[174:177], v[228:231], v[56:59]
	v_mfma_f32_16x16x32_bf16 v[56:59], v[178:181], v[232:235], v[56:59]
	v_mfma_f32_16x16x32_bf16 v[52:55], v[182:185], v[228:231], v[52:55]
	v_mfma_f32_16x16x32_bf16 v[52:55], v[208:211], v[232:235], v[52:55]
	v_mfma_f32_16x16x32_bf16 v[80:83], v[174:177], v[236:239], v[80:83]
	v_mfma_f32_16x16x32_bf16 v[80:83], v[178:181], v[240:243], v[80:83]
	s_setprio 2
	s_barrier
	v_mfma_f32_16x16x32_bf16 v[76:79], v[182:185], v[236:239], v[76:79]
	v_mfma_f32_16x16x32_bf16 v[76:79], v[208:211], v[240:243], v[76:79]
	s_setprio 0
	s_add_i32 s10, s27, s67
	v_lshl_add_u64 v[244:245], s[62:63], 0, v[2:3]
	s_mov_b32 m0, s10
	ds_read_b128 v[212:215], v197 offset:16384
	ds_read_b128 v[216:219], v197 offset:17408
	ds_read_b128 v[220:223], v197 offset:18432
	ds_read_b128 v[224:227], v197 offset:19456
	ds_read_b128 v[228:231], v197 offset:20480
	ds_read_b128 v[232:235], v197 offset:21504
	ds_read_b128 v[236:239], v197 offset:22528
	ds_read_b128 v[240:243], v197 offset:23552
	global_load_lds_dwordx4 v[244:245], off
	s_add_i32 m0, s10, 0x2000
	s_add_u32 s10, s62, 0x80000
	v_lshl_add_u64 v[246:247], s[62:63], 0, v[150:151]
	s_addc_u32 s11, s63, 0
	s_add_i32 s25, s25, s67
	global_load_lds_dwordx4 v[246:247], off
	v_lshl_add_u64 v[248:249], s[10:11], 0, v[2:3]
	s_mov_b32 m0, s25
	v_lshl_add_u64 v[160:161], s[64:65], 0, v[148:149]
	global_load_lds_dwordx4 v[248:249], off
	v_lshl_add_u64 v[248:249], s[10:11], 0, v[150:151]
	s_add_i32 m0, s25, 0x2000
	s_nop 0
	global_load_lds_dwordx4 v[248:249], off
	v_lshl_add_u64 v[248:249], s[64:65], 0, v[0:1]
	s_mov_b32 m0, s53
	s_nop 0
	global_load_lds_dwordx4 v[248:249], off
	s_mov_b32 m0, s66
	s_nop 0
	global_load_lds_dwordx4 v[160:161], off
	s_waitcnt vmcnt(8)
	s_waitcnt lgkmcnt(0)
	s_barrier
	s_setprio 1
	s_waitcnt lgkmcnt(0)
	v_mfma_f32_16x16x32_bf16 v[120:123], v[136:139], v[212:215], v[120:123]
	v_mfma_f32_16x16x32_bf16 v[120:123], v[140:143], v[216:219], v[120:123]
	v_mfma_f32_16x16x32_bf16 v[116:119], v[144:147], v[212:215], v[116:119]
	v_mfma_f32_16x16x32_bf16 v[116:119], v[170:173], v[216:219], v[116:119]
	v_mfma_f32_16x16x32_bf16 v[96:99], v[136:139], v[220:223], v[96:99]
	v_mfma_f32_16x16x32_bf16 v[96:99], v[140:143], v[224:227], v[96:99]
	v_mfma_f32_16x16x32_bf16 v[92:95], v[144:147], v[220:223], v[92:95]
	v_mfma_f32_16x16x32_bf16 v[92:95], v[170:173], v[224:227], v[92:95]
	v_mfma_f32_16x16x32_bf16 v[64:67], v[136:139], v[228:231], v[64:67]
	v_mfma_f32_16x16x32_bf16 v[64:67], v[140:143], v[232:235], v[64:67]
	v_mfma_f32_16x16x32_bf16 v[60:63], v[144:147], v[228:231], v[60:63]
	v_mfma_f32_16x16x32_bf16 v[60:63], v[170:173], v[232:235], v[60:63]
	v_mfma_f32_16x16x32_bf16 v[24:27], v[136:139], v[236:239], v[24:27]
	v_mfma_f32_16x16x32_bf16 v[24:27], v[140:143], v[240:243], v[24:27]
	v_mfma_f32_16x16x32_bf16 v[20:23], v[144:147], v[236:239], v[20:23]
	v_mfma_f32_16x16x32_bf16 v[20:23], v[170:173], v[240:243], v[20:23]
	s_setprio 0
	s_setprio 1
	v_mfma_f32_16x16x32_bf16 v[112:115], v[174:177], v[212:215], v[112:115]
	v_mfma_f32_16x16x32_bf16 v[112:115], v[178:181], v[216:219], v[112:115]
	v_mfma_f32_16x16x32_bf16 v[108:111], v[182:185], v[212:215], v[108:111]
	v_mfma_f32_16x16x32_bf16 v[108:111], v[208:211], v[216:219], v[108:111]
	v_mfma_f32_16x16x32_bf16 v[88:91], v[174:177], v[220:223], v[88:91]
	v_mfma_f32_16x16x32_bf16 v[88:91], v[178:181], v[224:227], v[88:91]
	v_mfma_f32_16x16x32_bf16 v[84:87], v[182:185], v[220:223], v[84:87]
	v_mfma_f32_16x16x32_bf16 v[84:87], v[208:211], v[224:227], v[84:87]
	v_mfma_f32_16x16x32_bf16 v[48:51], v[174:177], v[228:231], v[48:51]
	v_mfma_f32_16x16x32_bf16 v[48:51], v[178:181], v[232:235], v[48:51]
	v_mfma_f32_16x16x32_bf16 v[44:47], v[182:185], v[228:231], v[44:47]
	v_mfma_f32_16x16x32_bf16 v[44:47], v[208:211], v[232:235], v[44:47]
	v_mfma_f32_16x16x32_bf16 v[16:19], v[174:177], v[236:239], v[16:19]
	v_mfma_f32_16x16x32_bf16 v[16:19], v[178:181], v[240:243], v[16:19]
	s_setprio 2
	s_barrier
; #define PG8_STAGE(bufoff, gbase, voff) do { _Pragma("unroll") for (int _i = 0; _i < 2; ++_i) \
;         __builtin_amdgcn_global_load_lds((const unsigned*)((const char*)(gbase) + (voff)[_i]), (LAS unsigned*)(lds + (bufoff) + ldsw + _i * 8192), 16, 0, 0); } while (0)
; #define PG8_LDA(dst, b, h) do { _Pragma("unroll") for (int m = 0; m < 4; ++m) _Pragma("unroll") for (int k = 0; k < 2; ++k) dst[m][k] = *(const LAS bf16x8*)(lds + PG8_SA(b, h) + aoff + m * 2048 + k * 1024); } while (0)
; #define PG8_LDB(dst, b, h) do { _Pragma("unroll") for (int n = 0; n < 2; ++n) _Pragma("unroll") for (int k = 0; k < 2; ++k) dst[n][k] = *(const LAS bf16x8*)(lds + PG8_SB(b, h) + boff + n * 2048 + k * 1024); } while (0)
; #define PG8_MMA(ai, bj, At, Bt) do { __builtin_amdgcn_s_setprio(1); _Pragma("unroll") for (int m = 0; m < 4; ++m) _Pragma("unroll") for (int n = 0; n < 2; ++n) _Pragma("unroll") for (int k = 0; k < 2; ++k) \
;         acc[ai][bj][m][n] = __builtin_amdgcn_mfma_f32_16x16x32_bf16(Bt[n][k], At[m][k], acc[ai][bj][m][n], 0, 0, 0); __builtin_amdgcn_s_setprio(0); } while (0)
; #define PG8_WAIT_V(n) asm volatile("s_waitcnt vmcnt(" #n ")" ::: "memory")
; #define PG8_WAIT_L(n) asm volatile("s_waitcnt lgkmcnt(" #n ")" ::: "memory")
; #define PG8_BAR __builtin_amdgcn_s_barrier()
; #define PG8_SCHED __builtin_amdgcn_sched_barrier(0)
; template <class Epi, class Sched, bool ALIGN_EPI = true>
; __device__ __forceinline__ void gemm_phase(LAS unsigned char* lds, const Gemm g, const Sched& S, const Epi& E) {
;     ...
;             PG8_WAIT_V(8); PG8_WAIT_L(0); PG8_BAR; PG8_MMA(1, 0, At, B0); PG8_MMA(1, 1, At, B1); PG8_BAR; PG8_SCHED;
;             PG8_LDB(B0, 1, 0); PG8_LDB(B1, 1, 1); PG8_SCHED; PG8_LDA(At, 1, 0); PG8_STAGE(PG8_SA(0, 1), a2 + hA, voffA);
;             PG8_WAIT_V(8); PG8_WAIT_L(0); PG8_BAR; PG8_MMA(0, 0, At, B0); PG8_MMA(0, 1, At, B1); PG8_BAR; PG8_SCHED;
	v_mfma_f32_16x16x32_bf16 v[12:15], v[182:185], v[236:239], v[12:15]
	v_mfma_f32_16x16x32_bf16 v[12:15], v[208:211], v[240:243], v[12:15]
	s_setprio 0
	s_add_i32 s25, 0, 0x18000
	v_add_u32_e32 v162, s25, v186
	s_add_i32 s26, 0, 0x1c000
	ds_read_b128 v[136:139], v162
	ds_read_b128 v[140:143], v162 offset:1024
	ds_read_b128 v[144:147], v162 offset:2048
	ds_read_b128 v[170:173], v162 offset:3072
	v_add_u32_e32 v162, s26, v186
	ds_read_b128 v[174:177], v162
	ds_read_b128 v[178:181], v162 offset:1024
	ds_read_b128 v[182:185], v162 offset:2048
	ds_read_b128 v[208:211], v162 offset:3072
	s_add_u32 s10, s64, 0x80000
	s_addc_u32 s11, s65, 0
	s_mov_b32 m0, s75
	v_lshl_add_u64 v[162:163], s[10:11], 0, v[0:1]
	ds_read_b128 v[212:215], v197 offset:32768
	ds_read_b128 v[216:219], v197 offset:33792
	ds_read_b128 v[220:223], v197 offset:34816
	ds_read_b128 v[224:227], v197 offset:35840
	ds_read_b128 v[228:231], v197 offset:36864
	ds_read_b128 v[232:235], v197 offset:37888
	ds_read_b128 v[236:239], v197 offset:38912
	ds_read_b128 v[240:243], v197 offset:39936
	global_load_lds_dwordx4 v[162:163], off
	v_lshl_add_u64 v[162:163], s[10:11], 0, v[148:149]
	s_mov_b32 m0, s76
	s_nop 0
	global_load_lds_dwordx4 v[162:163], off
	s_waitcnt vmcnt(8)
	s_waitcnt lgkmcnt(0)
	s_barrier
	s_setprio 1
	s_waitcnt lgkmcnt(0)
	v_mfma_f32_16x16x32_bf16 v[36:39], v[136:139], v[212:215], v[36:39]
	v_mfma_f32_16x16x32_bf16 v[36:39], v[140:143], v[216:219], v[36:39]
	v_mfma_f32_16x16x32_bf16 v[40:43], v[144:147], v[212:215], v[40:43]
	v_mfma_f32_16x16x32_bf16 v[40:43], v[170:173], v[216:219], v[40:43]
	v_mfma_f32_16x16x32_bf16 v[68:71], v[136:139], v[220:223], v[68:71]
	v_mfma_f32_16x16x32_bf16 v[68:71], v[140:143], v[224:227], v[68:71]
	v_mfma_f32_16x16x32_bf16 v[72:75], v[144:147], v[220:223], v[72:75]
	v_mfma_f32_16x16x32_bf16 v[72:75], v[170:173], v[224:227], v[72:75]
	v_mfma_f32_16x16x32_bf16 v[100:103], v[136:139], v[228:231], v[100:103]
	v_mfma_f32_16x16x32_bf16 v[100:103], v[140:143], v[232:235], v[100:103]
	v_mfma_f32_16x16x32_bf16 v[104:107], v[144:147], v[228:231], v[104:107]
	v_mfma_f32_16x16x32_bf16 v[104:107], v[170:173], v[232:235], v[104:107]
	v_mfma_f32_16x16x32_bf16 v[128:131], v[136:139], v[236:239], v[128:131]
	v_mfma_f32_16x16x32_bf16 v[128:131], v[140:143], v[240:243], v[128:131]
	v_mfma_f32_16x16x32_bf16 v[124:127], v[144:147], v[236:239], v[124:127]
	v_mfma_f32_16x16x32_bf16 v[124:127], v[170:173], v[240:243], v[124:127]
	s_setprio 0
	s_setprio 1
	v_mfma_f32_16x16x32_bf16 v[8:11], v[174:177], v[212:215], v[8:11]
	v_mfma_f32_16x16x32_bf16 v[8:11], v[178:181], v[216:219], v[8:11]
	v_mfma_f32_16x16x32_bf16 v[4:7], v[182:185], v[212:215], v[4:7]
	v_mfma_f32_16x16x32_bf16 v[4:7], v[208:211], v[216:219], v[4:7]
	v_mfma_f32_16x16x32_bf16 v[32:35], v[174:177], v[220:223], v[32:35]
	v_mfma_f32_16x16x32_bf16 v[32:35], v[178:181], v[224:227], v[32:35]
	v_mfma_f32_16x16x32_bf16 v[28:31], v[182:185], v[220:223], v[28:31]
	v_mfma_f32_16x16x32_bf16 v[28:31], v[208:211], v[224:227], v[28:31]
	v_mfma_f32_16x16x32_bf16 v[56:59], v[174:177], v[228:231], v[56:59]
	v_mfma_f32_16x16x32_bf16 v[56:59], v[178:181], v[232:235], v[56:59]
	v_mfma_f32_16x16x32_bf16 v[52:55], v[182:185], v[228:231], v[52:55]
	v_mfma_f32_16x16x32_bf16 v[52:55], v[208:211], v[232:235], v[52:55]
	v_mfma_f32_16x16x32_bf16 v[80:83], v[174:177], v[236:239], v[80:83]
	v_mfma_f32_16x16x32_bf16 v[80:83], v[178:181], v[240:243], v[80:83]
	s_setprio 2
	s_barrier
; #define PG8_STAGE(bufoff, gbase, voff) do { _Pragma("unroll") for (int _i = 0; _i < 2; ++_i) \
;         __builtin_amdgcn_global_load_lds((const unsigned*)((const char*)(gbase) + (voff)[_i]), (LAS unsigned*)(lds + (bufoff) + ldsw + _i * 8192), 16, 0, 0); } while (0)
; #define PG8_LDA(dst, b, h) do { _Pragma("unroll") for (int m = 0; m < 4; ++m) _Pragma("unroll") for (int k = 0; k < 2; ++k) dst[m][k] = *(const LAS bf16x8*)(lds + PG8_SA(b, h) + aoff + m * 2048 + k * 1024); } while (0)
; #define PG8_MMA(ai, bj, At, Bt) do { __builtin_amdgcn_s_setprio(1); _Pragma("unroll") for (int m = 0; m < 4; ++m) _Pragma("unroll") for (int n = 0; n < 2; ++n) _Pragma("unroll") for (int k = 0; k < 2; ++k) \
;         acc[ai][bj][m][n] = __builtin_amdgcn_mfma_f32_16x16x32_bf16(Bt[n][k], At[m][k], acc[ai][bj][m][n], 0, 0, 0); __builtin_amdgcn_s_setprio(0); } while (0)
; #define PG8_WAIT_V(n) asm volatile("s_waitcnt vmcnt(" #n ")" ::: "memory")
; #define PG8_WAIT_L(n) asm volatile("s_waitcnt lgkmcnt(" #n ")" ::: "memory")
; #define PG8_BAR __builtin_amdgcn_s_barrier()
; #define PG8_SCHED __builtin_amdgcn_sched_barrier(0)
; template <class Epi, class Sched, bool ALIGN_EPI = true>
; __device__ __forceinline__ void gemm_phase(LAS unsigned char* lds, const Gemm g, const Sched& S, const Epi& E) {
;     ...
;             PG8_WAIT_V(8); PG8_WAIT_L(0); PG8_BAR; PG8_MMA(0, 0, At, B0); PG8_MMA(0, 1, At, B1); PG8_BAR; PG8_SCHED;
;             PG8_LDA(At, 1, 1); PG8_STAGE(PG8_SB(1, 0), b3, voffB); PG8_STAGE(PG8_SB(1, 1), b3 + hB, voffB); PG8_STAGE(PG8_SA(1, 0), a3, voffA);
;             PG8_WAIT_V(8); PG8_WAIT_L(0); PG8_BAR; PG8_MMA(1, 0, At, B0); PG8_MMA(1, 1, At, B1); PG8_BAR; PG8_SCHED;
	v_mfma_f32_16x16x32_bf16 v[76:79], v[182:185], v[236:239], v[76:79]
	v_mfma_f32_16x16x32_bf16 v[76:79], v[208:211], v[240:243], v[76:79]
	s_setprio 0
	s_add_i32 s10, s25, s67
	v_lshl_add_u64 v[162:163], v[244:245], 0, s[86:87]
	s_mov_b32 m0, s10
	ds_read_b128 v[212:215], v197 offset:49152
	ds_read_b128 v[216:219], v197 offset:50176
	ds_read_b128 v[220:223], v197 offset:51200
	ds_read_b128 v[224:227], v197 offset:52224
	ds_read_b128 v[228:231], v197 offset:53248
	ds_read_b128 v[232:235], v197 offset:54272
	ds_read_b128 v[236:239], v197 offset:55296
	ds_read_b128 v[240:243], v197 offset:56320
	global_load_lds_dwordx4 v[162:163], off
	s_add_i32 m0, s10, 0x2000
	s_add_u32 s10, s62, 0x80080
	v_lshl_add_u64 v[162:163], v[246:247], 0, s[86:87]
	s_addc_u32 s11, s63, 0
	s_add_i32 s25, s26, s67
	global_load_lds_dwordx4 v[162:163], off
	v_lshl_add_u64 v[162:163], s[10:11], 0, v[2:3]
	s_mov_b32 m0, s25
	v_lshl_add_u64 v[160:161], v[160:161], 0, s[86:87]
	global_load_lds_dwordx4 v[162:163], off
	v_lshl_add_u64 v[162:163], s[10:11], 0, v[150:151]
	s_add_i32 m0, s25, 0x2000
	s_nop 0
	global_load_lds_dwordx4 v[162:163], off
	v_lshl_add_u64 v[162:163], v[248:249], 0, s[86:87]
	s_mov_b32 m0, s79
	s_nop 0
	global_load_lds_dwordx4 v[162:163], off
	s_mov_b32 m0, s80
	s_nop 0
	global_load_lds_dwordx4 v[160:161], off
	s_waitcnt vmcnt(8)
	s_waitcnt lgkmcnt(0)
	s_barrier
	s_setprio 1
	s_waitcnt lgkmcnt(0)
	v_mfma_f32_16x16x32_bf16 v[120:123], v[136:139], v[212:215], v[120:123]
	v_mfma_f32_16x16x32_bf16 v[120:123], v[140:143], v[216:219], v[120:123]
	v_mfma_f32_16x16x32_bf16 v[116:119], v[144:147], v[212:215], v[116:119]
	v_mfma_f32_16x16x32_bf16 v[116:119], v[170:173], v[216:219], v[116:119]
	v_mfma_f32_16x16x32_bf16 v[96:99], v[136:139], v[220:223], v[96:99]
	v_mfma_f32_16x16x32_bf16 v[96:99], v[140:143], v[224:227], v[96:99]
	v_mfma_f32_16x16x32_bf16 v[92:95], v[144:147], v[220:223], v[92:95]
	v_mfma_f32_16x16x32_bf16 v[92:95], v[170:173], v[224:227], v[92:95]
	v_mfma_f32_16x16x32_bf16 v[64:67], v[136:139], v[228:231], v[64:67]
	v_mfma_f32_16x16x32_bf16 v[64:67], v[140:143], v[232:235], v[64:67]
	v_mfma_f32_16x16x32_bf16 v[60:63], v[144:147], v[228:231], v[60:63]
	v_mfma_f32_16x16x32_bf16 v[60:63], v[170:173], v[232:235], v[60:63]
	v_mfma_f32_16x16x32_bf16 v[24:27], v[136:139], v[236:239], v[24:27]
	v_mfma_f32_16x16x32_bf16 v[24:27], v[140:143], v[240:243], v[24:27]
	v_mfma_f32_16x16x32_bf16 v[20:23], v[144:147], v[236:239], v[20:23]
	v_mfma_f32_16x16x32_bf16 v[20:23], v[170:173], v[240:243], v[20:23]
	s_setprio 0
	s_setprio 1
	v_mfma_f32_16x16x32_bf16 v[112:115], v[174:177], v[212:215], v[112:115]
	v_mfma_f32_16x16x32_bf16 v[112:115], v[178:181], v[216:219], v[112:115]
	v_mfma_f32_16x16x32_bf16 v[108:111], v[182:185], v[212:215], v[108:111]
	v_mfma_f32_16x16x32_bf16 v[108:111], v[208:211], v[216:219], v[108:111]
	v_mfma_f32_16x16x32_bf16 v[88:91], v[174:177], v[220:223], v[88:91]
	v_mfma_f32_16x16x32_bf16 v[88:91], v[178:181], v[224:227], v[88:91]
	v_mfma_f32_16x16x32_bf16 v[84:87], v[182:185], v[220:223], v[84:87]
	v_mfma_f32_16x16x32_bf16 v[84:87], v[208:211], v[224:227], v[84:87]
	v_mfma_f32_16x16x32_bf16 v[48:51], v[174:177], v[228:231], v[48:51]
	v_mfma_f32_16x16x32_bf16 v[48:51], v[178:181], v[232:235], v[48:51]
	v_mfma_f32_16x16x32_bf16 v[44:47], v[182:185], v[228:231], v[44:47]
	v_mfma_f32_16x16x32_bf16 v[44:47], v[208:211], v[232:235], v[44:47]
	v_mfma_f32_16x16x32_bf16 v[16:19], v[174:177], v[236:239], v[16:19]
	v_mfma_f32_16x16x32_bf16 v[16:19], v[178:181], v[240:243], v[16:19]
	s_setprio 2
	s_barrier
	v_mfma_f32_16x16x32_bf16 v[12:15], v[182:185], v[236:239], v[12:15]
	v_mfma_f32_16x16x32_bf16 v[12:15], v[208:211], v[240:243], v[12:15]
	s_setprio 0
	s_add_i32 s24, s24, 2
	s_cmp_gt_u32 s24, 29
	s_mov_b64 s[10:11], vcc
	s_cbranch_scc0 .LBB0_667

;     __device__ bool next(int i, Unit& u) const { if (i >= 2) return false; const int x = c & 7, j = c >> 3; u.pm = 32 * i + 4 * x + (j & 3); u.pn = j >> 2; return true; }
; #define PG8_STAGE(bufoff, gbase, voff) do { _Pragma("unroll") for (int _i = 0; _i < 2; ++_i) \
;         __builtin_amdgcn_global_load_lds((const unsigned*)((const char*)(gbase) + (voff)[_i]), (LAS unsigned*)(lds + (bufoff) + ldsw + _i * 8192), 16, 0, 0); } while (0)
; #define PG8_LDA(dst, b, h) do { _Pragma("unroll") for (int m = 0; m < 4; ++m) _Pragma("unroll") for (int k = 0; k < 2; ++k) dst[m][k] = *(const LAS bf16x8*)(lds + PG8_SA(b, h) + aoff + m * 2048 + k * 1024); } while (0)
; #define PG8_WAIT_V(n) asm volatile("s_waitcnt vmcnt(" #n ")" ::: "memory")
;     __device__ __forceinline__ void operator()(f32x4 (&acc)[2][2][4][2], const Unit& u, int wr, int wc, int fr_, int fq_, int wid, int lane_) const {
;     ...
;             const int t = wid * 64 + lane, kind = t >> 6, pr = t & 63, bj = kind >> 2, tap = kind & 3;
;             const float* src = (tap < 3) ? (cw + (size_t)tap * FF2 + bj * FF + u.pn * 128 + 2 * pr) : (cb + bj * FF + u.pn * 128 + 2 * pr);
;             const f32x2 wv = *(const f32x2*)src;
; template <class Epi, class Sched, bool ALIGN_EPI = true>
; __device__ __forceinline__ void gemm_phase(LAS unsigned char* lds, const Gemm g, const Sched& S, const Epi& E) {
;     ...
;         const bool has_next = S.next(ui + 1, nxt);
;         const char* nA = has_next ? (const char*)g.A + ((size_t)nxt.pm * BM * g.lda + (size_t)nxt.pn * g.a_pn_off) * 2 : cA; const char* nB = has_next ? (const char*)g.Bt + (size_t)nxt.pn * BM * g.ldb * 2 : cB;
;         for (int t = 0; t < nt; t += 2) {
;             const bool last = (t == nt - 2);
;             const char* a1 = cA + (size_t)(t + 1) * kstep;
;             const char* a2 = last ? nA : cA + (size_t)(t + 2) * kstep; const char* b2 = last ? nB : cB + (size_t)(t + 2) * kstep;
;             const char* a3 = a2 + kstep; const char* b3 = b2 + kstep;
;             PG8_LDB(B0, 0, 0); PG8_LDB(B1, 0, 1); PG8_SCHED; PG8_LDA(At, 0, 0); PG8_STAGE(PG8_SA(1, 1), a1 + hA, voffA);
;             PG8_WAIT_V(8); PG8_WAIT_L(0); PG8_BAR; PG8_MMA(0, 0, At, B0); PG8_MMA(0, 1, At, B1); PG8_BAR; PG8_SCHED;
;             PG8_LDA(At, 0, 1); PG8_STAGE(PG8_SB(0, 0), b2, voffB); PG8_STAGE(PG8_SB(0, 1), b2 + hB, voffB); PG8_STAGE(PG8_SA(0, 0), a2, voffA);
.LBB0_827:
	s_ashr_i32 s39, s38, 31
	s_lshl_b64 s[16:17], s[38:39], 20
	s_add_u32 s40, s46, s16
	s_addc_u32 s41, s47, s17
	s_and_b64 s[16:17], s[4:5], exec
	s_cselect_b32 s16, s41, s7
	s_cselect_b32 s17, s40, s6
	s_ashr_i32 s15, s14, 31
	s_lshl_b64 s[18:19], s[14:15], 20
	s_add_u32 s42, s53, s18
	s_addc_u32 s43, s60, s19
	s_and_b64 s[18:19], s[4:5], exec
	s_cselect_b32 s15, s43, s45
	s_cselect_b32 s18, s42, s44
	s_add_u32 s6, s6, 0x80080
	s_addc_u32 s7, s7, 0
	s_add_u32 s19, s44, 0x100
	s_addc_u32 s24, s45, 0
	s_mov_b32 s25, -2
	v_add_u32_e32 v228, s77, v158
	v_ashrrev_i32_e32 v229, 6, v228
	v_and_b32_e32 v230, 3, v229
	v_lshrrev_b32_e32 v231, 8, v228
	v_mul_u32_u24_e32 v228, 0x2c00, v230
	v_lshlrev_b32_e32 v228, 2, v228
	v_mov_b32_e32 v229, 0
	v_lshl_add_u64 v[232:233], s[2:3], 0, v[228:229]
	v_mov_b32_e32 v228, s9
	v_cmp_eq_u32_e32 vcc, 3, v230
	v_mul_i32_i24_e32 v234, 0x1600, v231
	v_ashrrev_i32_e32 v235, 31, v234
	v_cndmask_b32_e32 v233, v233, v228, vcc
	v_mov_b32_e32 v228, s8
	v_cndmask_b32_e32 v232, v232, v228, vcc
	v_lshl_add_u64 v[232:233], v[234:235], 2, v[232:233]
	s_lshl_b32 s26, s82, 7
	s_ashr_i32 s27, s26, 31
	v_lshl_add_u64 v[232:233], s[26:27], 2, v[232:233]
	v_and_b32_e32 v228, 63, v158
	v_lshlrev_b32_e32 v228, 3, v228
	v_mov_b32_e32 v229, 0
	v_lshl_add_u64 v[232:233], v[232:233], 0, v[228:229]
	global_load_dwordx2 v[226:227], v[232:233], off
	s_add_u32 s26, s6, 0xfff80080
	s_addc_u32 s27, s7, -1
	s_add_i32 s30, 0, 0x10000
	s_cmp_eq_u32 s25, 28
	s_cselect_b32 s59, s16, s27
	s_cselect_b32 s58, s17, s26
	v_add_u32_e32 v2, s30, v204
	s_cselect_b32 s45, s15, s24
	s_cselect_b32 s44, s18, s19
	s_add_i32 s31, 0, 0x14000
	ds_read_b128 v[132:135], v2
	ds_read_b128 v[136:139], v2 offset:1024
	ds_read_b128 v[140:143], v2 offset:2048
	ds_read_b128 v[144:147], v2 offset:3072
	v_add_u32_e32 v2, s31, v204
	ds_read_b128 v[148:151], v2
	ds_read_b128 v[152:155], v2 offset:1024
	ds_read_b128 v[174:177], v2 offset:2048
	ds_read_b128 v[178:181], v2 offset:3072
	v_lshl_add_u64 v[156:157], s[6:7], 0, v[170:171]
	s_add_i32 m0, s62, 0xc000
	ds_read_b128 v[182:185], v205
	ds_read_b128 v[186:189], v205 offset:1024
	ds_read_b128 v[190:193], v205 offset:2048
	ds_read_b128 v[194:197], v205 offset:3072
	ds_read_b128 v[206:209], v205 offset:4096
	ds_read_b128 v[210:213], v205 offset:5120
	ds_read_b128 v[214:217], v205 offset:6144
	ds_read_b128 v[218:221], v205 offset:7168
	global_load_lds_dwordx4 v[156:157], off
	v_lshl_add_u64 v[156:157], s[6:7], 0, v[172:173]
	s_add_i32 m0, s62, 0xe000
	s_nop 0
	global_load_lds_dwordx4 v[156:157], off
	s_waitcnt vmcnt(8)
	s_waitcnt lgkmcnt(0)
	s_barrier
	s_setprio 1
	s_waitcnt lgkmcnt(0)
	v_mfma_f32_16x16x32_bf16 v[116:119], v[132:135], v[182:185], 0
	v_mfma_f32_16x16x32_bf16 v[116:119], v[136:139], v[186:189], v[116:119]
	v_mfma_f32_16x16x32_bf16 v[100:103], v[140:143], v[182:185], 0
	v_mfma_f32_16x16x32_bf16 v[100:103], v[144:147], v[186:189], v[100:103]
	v_mfma_f32_16x16x32_bf16 v[108:111], v[132:135], v[190:193], 0
	v_mfma_f32_16x16x32_bf16 v[108:111], v[136:139], v[194:197], v[108:111]
	v_mfma_f32_16x16x32_bf16 v[96:99], v[140:143], v[190:193], 0
	v_mfma_f32_16x16x32_bf16 v[96:99], v[144:147], v[194:197], v[96:99]
	v_mfma_f32_16x16x32_bf16 v[88:91], v[132:135], v[206:209], 0
	v_mfma_f32_16x16x32_bf16 v[88:91], v[136:139], v[210:213], v[88:91]
	v_mfma_f32_16x16x32_bf16 v[84:87], v[140:143], v[206:209], 0
	v_mfma_f32_16x16x32_bf16 v[84:87], v[144:147], v[210:213], v[84:87]
	v_mfma_f32_16x16x32_bf16 v[72:75], v[132:135], v[214:217], 0
	v_mfma_f32_16x16x32_bf16 v[72:75], v[136:139], v[218:221], v[72:75]
	v_mfma_f32_16x16x32_bf16 v[80:83], v[140:143], v[214:217], 0
	v_mfma_f32_16x16x32_bf16 v[80:83], v[144:147], v[218:221], v[80:83]
	s_setprio 0
	s_setprio 1
	v_mfma_f32_16x16x32_bf16 v[128:131], v[148:151], v[182:185], 0
	v_mfma_f32_16x16x32_bf16 v[128:131], v[152:155], v[186:189], v[128:131]
	v_mfma_f32_16x16x32_bf16 v[44:47], v[174:177], v[182:185], 0
	v_mfma_f32_16x16x32_bf16 v[44:47], v[178:181], v[186:189], v[44:47]
	v_mfma_f32_16x16x32_bf16 v[124:127], v[148:151], v[190:193], 0
	v_mfma_f32_16x16x32_bf16 v[124:127], v[152:155], v[194:197], v[124:127]
	v_mfma_f32_16x16x32_bf16 v[36:39], v[174:177], v[190:193], 0
	v_mfma_f32_16x16x32_bf16 v[36:39], v[178:181], v[194:197], v[36:39]
	v_mfma_f32_16x16x32_bf16 v[120:123], v[148:151], v[206:209], 0
	v_mfma_f32_16x16x32_bf16 v[120:123], v[152:155], v[210:213], v[120:123]
	v_mfma_f32_16x16x32_bf16 v[32:35], v[174:177], v[206:209], 0
	v_mfma_f32_16x16x32_bf16 v[32:35], v[178:181], v[210:213], v[32:35]
	v_mfma_f32_16x16x32_bf16 v[112:115], v[148:151], v[214:217], 0
	v_mfma_f32_16x16x32_bf16 v[112:115], v[152:155], v[218:221], v[112:115]
	s_setprio 2
	s_barrier
	v_mfma_f32_16x16x32_bf16 v[28:31], v[174:177], v[214:217], 0
	v_mfma_f32_16x16x32_bf16 v[28:31], v[178:181], v[218:221], v[28:31]
	s_setprio 0
	s_add_i32 s26, s30, s61
	v_lshl_add_u64 v[156:157], s[44:45], 0, v[166:167]
	s_mov_b32 m0, s26
	ds_read_b128 v[182:185], v205 offset:16384
	ds_read_b128 v[186:189], v205 offset:17408
	ds_read_b128 v[190:193], v205 offset:18432
	ds_read_b128 v[194:197], v205 offset:19456
	ds_read_b128 v[206:209], v205 offset:20480
	ds_read_b128 v[210:213], v205 offset:21504
	ds_read_b128 v[214:217], v205 offset:22528
	ds_read_b128 v[218:221], v205 offset:23552
	global_load_lds_dwordx4 v[156:157], off
	s_add_i32 m0, s26, 0x2000
	s_add_u32 s26, s44, 0x80000
	v_lshl_add_u64 v[160:161], s[44:45], 0, v[0:1]
	s_addc_u32 s27, s45, 0
	s_add_i32 s30, s31, s61
	global_load_lds_dwordx4 v[160:161], off
	v_lshl_add_u64 v[162:163], s[26:27], 0, v[166:167]
	s_mov_b32 m0, s30
	v_lshl_add_u64 v[222:223], s[58:59], 0, v[164:165]
	global_load_lds_dwordx4 v[162:163], off
	v_lshl_add_u64 v[162:163], s[26:27], 0, v[0:1]
	s_add_i32 m0, s30, 0x2000
	s_nop 0
	global_load_lds_dwordx4 v[162:163], off
	v_lshl_add_u64 v[162:163], s[58:59], 0, v[168:169]
	s_mov_b32 m0, s62
	s_nop 0
	global_load_lds_dwordx4 v[162:163], off
	s_mov_b32 m0, s63
	s_nop 0
	global_load_lds_dwordx4 v[222:223], off
	s_waitcnt vmcnt(8)
	s_waitcnt lgkmcnt(0)
	s_barrier
; #define PG8_STAGE(bufoff, gbase, voff) do { _Pragma("unroll") for (int _i = 0; _i < 2; ++_i) \
;         __builtin_amdgcn_global_load_lds((const unsigned*)((const char*)(gbase) + (voff)[_i]), (LAS unsigned*)(lds + (bufoff) + ldsw + _i * 8192), 16, 0, 0); } while (0)
; #define PG8_LDA(dst, b, h) do { _Pragma("unroll") for (int m = 0; m < 4; ++m) _Pragma("unroll") for (int k = 0; k < 2; ++k) dst[m][k] = *(const LAS bf16x8*)(lds + PG8_SA(b, h) + aoff + m * 2048 + k * 1024); } while (0)
; #define PG8_LDB(dst, b, h) do { _Pragma("unroll") for (int n = 0; n < 2; ++n) _Pragma("unroll") for (int k = 0; k < 2; ++k) dst[n][k] = *(const LAS bf16x8*)(lds + PG8_SB(b, h) + boff + n * 2048 + k * 1024); } while (0)
; #define PG8_MMA(ai, bj, At, Bt) do { __builtin_amdgcn_s_setprio(1); _Pragma("unroll") for (int m = 0; m < 4; ++m) _Pragma("unroll") for (int n = 0; n < 2; ++n) _Pragma("unroll") for (int k = 0; k < 2; ++k) \
;         acc[ai][bj][m][n] = __builtin_amdgcn_mfma_f32_16x16x32_bf16(Bt[n][k], At[m][k], acc[ai][bj][m][n], 0, 0, 0); __builtin_amdgcn_s_setprio(0); } while (0)
; #define PG8_WAIT_V(n) asm volatile("s_waitcnt vmcnt(" #n ")" ::: "memory")
; #define PG8_WAIT_L(n) asm volatile("s_waitcnt lgkmcnt(" #n ")" ::: "memory")
; #define PG8_BAR __builtin_amdgcn_s_barrier()
; #define PG8_SCHED __builtin_amdgcn_sched_barrier(0)
; template <class Epi, class Sched, bool ALIGN_EPI = true>
; __device__ __forceinline__ void gemm_phase(LAS unsigned char* lds, const Gemm g, const Sched& S, const Epi& E) {
;     ...
;             PG8_WAIT_V(8); PG8_WAIT_L(0); PG8_BAR; PG8_MMA(0, 0, At, B0); PG8_MMA(0, 1, At, B1); PG8_BAR; PG8_SCHED;
;             PG8_LDA(At, 0, 1); PG8_STAGE(PG8_SB(0, 0), b2, voffB); PG8_STAGE(PG8_SB(0, 1), b2 + hB, voffB); PG8_STAGE(PG8_SA(0, 0), a2, voffA);
;             PG8_WAIT_V(8); PG8_WAIT_L(0); PG8_BAR; PG8_MMA(1, 0, At, B0); PG8_MMA(1, 1, At, B1); PG8_BAR; PG8_SCHED;
;             PG8_LDB(B0, 1, 0); PG8_LDB(B1, 1, 1); PG8_SCHED; PG8_LDA(At, 1, 0); PG8_STAGE(PG8_SA(0, 1), a2 + hA, voffA);
;             PG8_WAIT_V(8); PG8_WAIT_L(0); PG8_BAR; PG8_MMA(0, 0, At, B0); PG8_MMA(0, 1, At, B1); PG8_BAR; PG8_SCHED;
	s_setprio 1
	s_waitcnt lgkmcnt(0)
	v_mfma_f32_16x16x32_bf16 v[60:63], v[132:135], v[182:185], 0
	v_mfma_f32_16x16x32_bf16 v[60:63], v[136:139], v[186:189], v[60:63]
	v_mfma_f32_16x16x32_bf16 v[68:71], v[140:143], v[182:185], 0
	v_mfma_f32_16x16x32_bf16 v[68:71], v[144:147], v[186:189], v[68:71]
	v_mfma_f32_16x16x32_bf16 v[40:43], v[132:135], v[190:193], 0
	v_mfma_f32_16x16x32_bf16 v[40:43], v[136:139], v[194:197], v[40:43]
	v_mfma_f32_16x16x32_bf16 v[64:67], v[140:143], v[190:193], 0
	v_mfma_f32_16x16x32_bf16 v[64:67], v[144:147], v[194:197], v[64:67]
	v_mfma_f32_16x16x32_bf16 v[24:27], v[132:135], v[206:209], 0
	v_mfma_f32_16x16x32_bf16 v[24:27], v[136:139], v[210:213], v[24:27]
	v_mfma_f32_16x16x32_bf16 v[56:59], v[140:143], v[206:209], 0
	v_mfma_f32_16x16x32_bf16 v[56:59], v[144:147], v[210:213], v[56:59]
	v_mfma_f32_16x16x32_bf16 v[12:15], v[132:135], v[214:217], 0
	v_mfma_f32_16x16x32_bf16 v[12:15], v[136:139], v[218:221], v[12:15]
	v_mfma_f32_16x16x32_bf16 v[48:51], v[140:143], v[214:217], 0
	v_mfma_f32_16x16x32_bf16 v[48:51], v[144:147], v[218:221], v[48:51]
	s_setprio 0
	s_setprio 1
	v_mfma_f32_16x16x32_bf16 v[104:107], v[148:151], v[182:185], 0
	v_mfma_f32_16x16x32_bf16 v[104:107], v[152:155], v[186:189], v[104:107]
	v_mfma_f32_16x16x32_bf16 v[20:23], v[174:177], v[182:185], 0
	v_mfma_f32_16x16x32_bf16 v[20:23], v[178:181], v[186:189], v[20:23]
	v_mfma_f32_16x16x32_bf16 v[92:95], v[148:151], v[190:193], 0
	v_mfma_f32_16x16x32_bf16 v[92:95], v[152:155], v[194:197], v[92:95]
	v_mfma_f32_16x16x32_bf16 v[16:19], v[174:177], v[190:193], 0
	v_mfma_f32_16x16x32_bf16 v[16:19], v[178:181], v[194:197], v[16:19]
	v_mfma_f32_16x16x32_bf16 v[76:79], v[148:151], v[206:209], 0
	v_mfma_f32_16x16x32_bf16 v[76:79], v[152:155], v[210:213], v[76:79]
	v_mfma_f32_16x16x32_bf16 v[8:11], v[174:177], v[206:209], 0
	v_mfma_f32_16x16x32_bf16 v[8:11], v[178:181], v[210:213], v[8:11]
	v_mfma_f32_16x16x32_bf16 v[52:55], v[148:151], v[214:217], 0
	v_mfma_f32_16x16x32_bf16 v[52:55], v[152:155], v[218:221], v[52:55]
	s_setprio 2
	s_barrier
	v_mfma_f32_16x16x32_bf16 v[4:7], v[174:177], v[214:217], 0
	v_mfma_f32_16x16x32_bf16 v[4:7], v[178:181], v[218:221], v[4:7]
	s_setprio 0
	s_add_i32 s30, 0, 0x18000
	v_add_u32_e32 v2, s30, v204
	s_add_i32 s31, 0, 0x1c000
	ds_read_b128 v[132:135], v2
	ds_read_b128 v[136:139], v2 offset:1024
	ds_read_b128 v[140:143], v2 offset:2048
	ds_read_b128 v[144:147], v2 offset:3072
	v_add_u32_e32 v2, s31, v204
	ds_read_b128 v[148:151], v2
	ds_read_b128 v[152:155], v2 offset:1024
	ds_read_b128 v[174:177], v2 offset:2048
	ds_read_b128 v[178:181], v2 offset:3072
	s_add_u32 s26, s58, 0x80000
	s_addc_u32 s27, s59, 0
	s_mov_b32 m0, s64
	v_lshl_add_u64 v[224:225], s[26:27], 0, v[168:169]
	ds_read_b128 v[182:185], v205 offset:32768
	ds_read_b128 v[186:189], v205 offset:33792
	ds_read_b128 v[190:193], v205 offset:34816
	ds_read_b128 v[194:197], v205 offset:35840
	ds_read_b128 v[206:209], v205 offset:36864
	ds_read_b128 v[210:213], v205 offset:37888
	ds_read_b128 v[214:217], v205 offset:38912
	ds_read_b128 v[218:221], v205 offset:39936
	global_load_lds_dwordx4 v[224:225], off
	v_lshl_add_u64 v[224:225], s[26:27], 0, v[164:165]
	s_mov_b32 m0, s65
	s_nop 0
	global_load_lds_dwordx4 v[224:225], off
	s_waitcnt vmcnt(8)
	s_waitcnt lgkmcnt(0)
	s_barrier
	s_setprio 1
	s_waitcnt lgkmcnt(0)
	v_mfma_f32_16x16x32_bf16 v[116:119], v[132:135], v[182:185], v[116:119]
	v_mfma_f32_16x16x32_bf16 v[116:119], v[136:139], v[186:189], v[116:119]
	v_mfma_f32_16x16x32_bf16 v[100:103], v[140:143], v[182:185], v[100:103]
	v_mfma_f32_16x16x32_bf16 v[100:103], v[144:147], v[186:189], v[100:103]
	v_mfma_f32_16x16x32_bf16 v[108:111], v[132:135], v[190:193], v[108:111]
	v_mfma_f32_16x16x32_bf16 v[108:111], v[136:139], v[194:197], v[108:111]
	v_mfma_f32_16x16x32_bf16 v[96:99], v[140:143], v[190:193], v[96:99]
	v_mfma_f32_16x16x32_bf16 v[96:99], v[144:147], v[194:197], v[96:99]
	v_mfma_f32_16x16x32_bf16 v[88:91], v[132:135], v[206:209], v[88:91]
	v_mfma_f32_16x16x32_bf16 v[88:91], v[136:139], v[210:213], v[88:91]
	v_mfma_f32_16x16x32_bf16 v[84:87], v[140:143], v[206:209], v[84:87]
	v_mfma_f32_16x16x32_bf16 v[84:87], v[144:147], v[210:213], v[84:87]
	v_mfma_f32_16x16x32_bf16 v[72:75], v[132:135], v[214:217], v[72:75]
	v_mfma_f32_16x16x32_bf16 v[72:75], v[136:139], v[218:221], v[72:75]
	v_mfma_f32_16x16x32_bf16 v[80:83], v[140:143], v[214:217], v[80:83]
	v_mfma_f32_16x16x32_bf16 v[80:83], v[144:147], v[218:221], v[80:83]
	s_setprio 0
	s_setprio 1
	v_mfma_f32_16x16x32_bf16 v[128:131], v[148:151], v[182:185], v[128:131]
	v_mfma_f32_16x16x32_bf16 v[128:131], v[152:155], v[186:189], v[128:131]
	v_mfma_f32_16x16x32_bf16 v[44:47], v[174:177], v[182:185], v[44:47]
	v_mfma_f32_16x16x32_bf16 v[44:47], v[178:181], v[186:189], v[44:47]
	v_mfma_f32_16x16x32_bf16 v[124:127], v[148:151], v[190:193], v[124:127]
	v_mfma_f32_16x16x32_bf16 v[124:127], v[152:155], v[194:197], v[124:127]
	v_mfma_f32_16x16x32_bf16 v[36:39], v[174:177], v[190:193], v[36:39]
	v_mfma_f32_16x16x32_bf16 v[36:39], v[178:181], v[194:197], v[36:39]
	v_mfma_f32_16x16x32_bf16 v[120:123], v[148:151], v[206:209], v[120:123]
	v_mfma_f32_16x16x32_bf16 v[120:123], v[152:155], v[210:213], v[120:123]
	v_mfma_f32_16x16x32_bf16 v[32:35], v[174:177], v[206:209], v[32:35]
	v_mfma_f32_16x16x32_bf16 v[32:35], v[178:181], v[210:213], v[32:35]
	v_mfma_f32_16x16x32_bf16 v[112:115], v[148:151], v[214:217], v[112:115]
	v_mfma_f32_16x16x32_bf16 v[112:115], v[152:155], v[218:221], v[112:115]
	s_setprio 2
	s_barrier
; #define PG8_STAGE(bufoff, gbase, voff) do { _Pragma("unroll") for (int _i = 0; _i < 2; ++_i) \
;         __builtin_amdgcn_global_load_lds((const unsigned*)((const char*)(gbase) + (voff)[_i]), (LAS unsigned*)(lds + (bufoff) + ldsw + _i * 8192), 16, 0, 0); } while (0)
; #define PG8_LDA(dst, b, h) do { _Pragma("unroll") for (int m = 0; m < 4; ++m) _Pragma("unroll") for (int k = 0; k < 2; ++k) dst[m][k] = *(const LAS bf16x8*)(lds + PG8_SA(b, h) + aoff + m * 2048 + k * 1024); } while (0)
; #define PG8_LDB(dst, b, h) do { _Pragma("unroll") for (int n = 0; n < 2; ++n) _Pragma("unroll") for (int k = 0; k < 2; ++k) dst[n][k] = *(const LAS bf16x8*)(lds + PG8_SB(b, h) + boff + n * 2048 + k * 1024); } while (0)
; #define PG8_WAIT_V(n) asm volatile("s_waitcnt vmcnt(" #n ")" ::: "memory")
; #define PG8_WAIT_L(n) asm volatile("s_waitcnt lgkmcnt(" #n ")" ::: "memory")
; template <class Epi, class Sched, bool ALIGN_EPI = true>
; __device__ __forceinline__ void gemm_phase(LAS unsigned char* lds, const Gemm g, const Sched& S, const Epi& E) {
;     ...
;             const bool last = (t == nt - 2);
;             const char* a1 = cA + (size_t)(t + 1) * kstep;
;             const char* a2 = last ? nA : cA + (size_t)(t + 2) * kstep; const char* b2 = last ? nB : cB + (size_t)(t + 2) * kstep;
;             const char* a3 = a2 + kstep; const char* b3 = b2 + kstep;
;             PG8_LDB(B0, 0, 0); PG8_LDB(B1, 0, 1); PG8_SCHED; PG8_LDA(At, 0, 0); PG8_STAGE(PG8_SA(1, 1), a1 + hA, voffA);
;             PG8_WAIT_V(8); PG8_WAIT_L(0); PG8_BAR; PG8_MMA(0, 0, At, B0); PG8_MMA(0, 1, At, B1); PG8_BAR; PG8_SCHED;
;             PG8_LDA(At, 0, 1); PG8_STAGE(PG8_SB(0, 0), b2, voffB); PG8_STAGE(PG8_SB(0, 1), b2 + hB, voffB); PG8_STAGE(PG8_SA(0, 0), a2, voffA);
;             PG8_WAIT_V(8); PG8_WAIT_L(0); PG8_BAR; PG8_MMA(1, 0, At, B0); PG8_MMA(1, 1, At, B1); PG8_BAR; PG8_SCHED;
;             PG8_LDB(B0, 1, 0); PG8_LDB(B1, 1, 1); PG8_SCHED; PG8_LDA(At, 1, 0); PG8_STAGE(PG8_SA(0, 1), a2 + hA, voffA);
;             PG8_WAIT_V(8); PG8_WAIT_L(0); PG8_BAR; PG8_MMA(0, 0, At, B0); PG8_MMA(0, 1, At, B1); PG8_BAR; PG8_SCHED;
;             PG8_LDA(At, 1, 1); PG8_STAGE(PG8_SB(1, 0), b3, voffB); PG8_STAGE(PG8_SB(1, 1), b3 + hB, voffB); PG8_STAGE(PG8_SA(1, 0), a3, voffA);
;             PG8_WAIT_V(8); PG8_WAIT_L(0); PG8_BAR; PG8_MMA(1, 0, At, B0); PG8_MMA(1, 1, At, B1); PG8_BAR; PG8_SCHED;
	v_mfma_f32_16x16x32_bf16 v[28:31], v[174:177], v[214:217], v[28:31]
	v_mfma_f32_16x16x32_bf16 v[28:31], v[178:181], v[218:221], v[28:31]
	s_setprio 0
	s_add_i32 s26, s30, s61
	v_lshl_add_u64 v[156:157], v[156:157], 0, s[86:87]
	s_mov_b32 m0, s26
	ds_read_b128 v[182:185], v205 offset:49152
	ds_read_b128 v[186:189], v205 offset:50176
	ds_read_b128 v[190:193], v205 offset:51200
	ds_read_b128 v[194:197], v205 offset:52224
	ds_read_b128 v[206:209], v205 offset:53248
	ds_read_b128 v[210:213], v205 offset:54272
	ds_read_b128 v[214:217], v205 offset:55296
	ds_read_b128 v[218:221], v205 offset:56320
	global_load_lds_dwordx4 v[156:157], off
	s_add_i32 m0, s26, 0x2000
	s_add_u32 s26, s44, 0x80080
	v_lshl_add_u64 v[156:157], v[160:161], 0, s[86:87]
	s_addc_u32 s27, s45, 0
	s_add_i32 s30, s31, s61
	global_load_lds_dwordx4 v[156:157], off
	v_lshl_add_u64 v[156:157], s[26:27], 0, v[166:167]
	s_mov_b32 m0, s30
	s_nop 0
	global_load_lds_dwordx4 v[156:157], off
	v_lshl_add_u64 v[156:157], s[26:27], 0, v[0:1]
	s_add_i32 m0, s30, 0x2000
	s_nop 0
	global_load_lds_dwordx4 v[156:157], off
	v_lshl_add_u64 v[156:157], v[162:163], 0, s[86:87]
	s_mov_b32 m0, s75
	s_nop 0
	global_load_lds_dwordx4 v[156:157], off
	v_lshl_add_u64 v[156:157], v[222:223], 0, s[86:87]
	s_mov_b32 m0, s76
	s_nop 0
	global_load_lds_dwordx4 v[156:157], off
	s_waitcnt vmcnt(8)
	s_waitcnt lgkmcnt(0)
	s_barrier
	s_setprio 1
	s_waitcnt lgkmcnt(0)
	v_mfma_f32_16x16x32_bf16 v[60:63], v[132:135], v[182:185], v[60:63]
	v_mfma_f32_16x16x32_bf16 v[60:63], v[136:139], v[186:189], v[60:63]
	v_mfma_f32_16x16x32_bf16 v[68:71], v[140:143], v[182:185], v[68:71]
	v_mfma_f32_16x16x32_bf16 v[68:71], v[144:147], v[186:189], v[68:71]
	v_mfma_f32_16x16x32_bf16 v[40:43], v[132:135], v[190:193], v[40:43]
	v_mfma_f32_16x16x32_bf16 v[40:43], v[136:139], v[194:197], v[40:43]
	v_mfma_f32_16x16x32_bf16 v[64:67], v[140:143], v[190:193], v[64:67]
	v_mfma_f32_16x16x32_bf16 v[64:67], v[144:147], v[194:197], v[64:67]
	v_mfma_f32_16x16x32_bf16 v[24:27], v[132:135], v[206:209], v[24:27]
	v_mfma_f32_16x16x32_bf16 v[24:27], v[136:139], v[210:213], v[24:27]
	v_mfma_f32_16x16x32_bf16 v[56:59], v[140:143], v[206:209], v[56:59]
	v_mfma_f32_16x16x32_bf16 v[56:59], v[144:147], v[210:213], v[56:59]
	v_mfma_f32_16x16x32_bf16 v[12:15], v[132:135], v[214:217], v[12:15]
	v_mfma_f32_16x16x32_bf16 v[12:15], v[136:139], v[218:221], v[12:15]
	v_mfma_f32_16x16x32_bf16 v[48:51], v[140:143], v[214:217], v[48:51]
	v_mfma_f32_16x16x32_bf16 v[48:51], v[144:147], v[218:221], v[48:51]
	s_setprio 0
	s_setprio 1
	v_mfma_f32_16x16x32_bf16 v[104:107], v[148:151], v[182:185], v[104:107]
	v_mfma_f32_16x16x32_bf16 v[104:107], v[152:155], v[186:189], v[104:107]
	v_mfma_f32_16x16x32_bf16 v[20:23], v[174:177], v[182:185], v[20:23]
	v_mfma_f32_16x16x32_bf16 v[20:23], v[178:181], v[186:189], v[20:23]
	v_mfma_f32_16x16x32_bf16 v[92:95], v[148:151], v[190:193], v[92:95]
	v_mfma_f32_16x16x32_bf16 v[92:95], v[152:155], v[194:197], v[92:95]
	v_mfma_f32_16x16x32_bf16 v[16:19], v[174:177], v[190:193], v[16:19]
	v_mfma_f32_16x16x32_bf16 v[16:19], v[178:181], v[194:197], v[16:19]
	v_mfma_f32_16x16x32_bf16 v[76:79], v[148:151], v[206:209], v[76:79]
	v_mfma_f32_16x16x32_bf16 v[76:79], v[152:155], v[210:213], v[76:79]
	v_mfma_f32_16x16x32_bf16 v[8:11], v[174:177], v[206:209], v[8:11]
	v_mfma_f32_16x16x32_bf16 v[8:11], v[178:181], v[210:213], v[8:11]
	v_mfma_f32_16x16x32_bf16 v[52:55], v[148:151], v[214:217], v[52:55]
	v_mfma_f32_16x16x32_bf16 v[52:55], v[152:155], v[218:221], v[52:55]
	s_setprio 2
	s_barrier
	v_mfma_f32_16x16x32_bf16 v[4:7], v[174:177], v[214:217], v[4:7]
	v_mfma_f32_16x16x32_bf16 v[4:7], v[178:181], v[218:221], v[4:7]
	s_setprio 0
	s_add_i32 s25, s25, 2
	s_add_u32 s6, s6, 0x100
	s_addc_u32 s7, s7, 0
	s_add_u32 s19, s19, 0x100
	s_addc_u32 s24, s24, 0
	s_cmp_gt_u32 s25, 29
	s_cbranch_scc1 .Lpeel_exit_828
.LBB0_828:
	s_add_u32 s26, s6, 0xfff80080
	s_addc_u32 s27, s7, -1
	s_add_i32 s30, 0, 0x10000
	s_cmp_eq_u32 s25, 28
	s_cselect_b32 s59, s16, s27
	s_cselect_b32 s58, s17, s26
	v_add_u32_e32 v2, s30, v204
	s_cselect_b32 s45, s15, s24
	s_cselect_b32 s44, s18, s19
	s_add_i32 s31, 0, 0x14000
	ds_read_b128 v[132:135], v2
	ds_read_b128 v[136:139], v2 offset:1024
	ds_read_b128 v[140:143], v2 offset:2048
	ds_read_b128 v[144:147], v2 offset:3072
	v_add_u32_e32 v2, s31, v204
	ds_read_b128 v[148:151], v2
	ds_read_b128 v[152:155], v2 offset:1024
	ds_read_b128 v[174:177], v2 offset:2048
	ds_read_b128 v[178:181], v2 offset:3072
	v_lshl_add_u64 v[156:157], s[6:7], 0, v[170:171]
	s_add_i32 m0, s62, 0xc000
	ds_read_b128 v[182:185], v205
	ds_read_b128 v[186:189], v205 offset:1024
	ds_read_b128 v[190:193], v205 offset:2048
	ds_read_b128 v[194:197], v205 offset:3072
	ds_read_b128 v[206:209], v205 offset:4096
	ds_read_b128 v[210:213], v205 offset:5120
	ds_read_b128 v[214:217], v205 offset:6144
	ds_read_b128 v[218:221], v205 offset:7168
	global_load_lds_dwordx4 v[156:157], off
	v_lshl_add_u64 v[156:157], s[6:7], 0, v[172:173]
	s_add_i32 m0, s62, 0xe000
	s_nop 0
	global_load_lds_dwordx4 v[156:157], off
	s_waitcnt vmcnt(8)
	s_waitcnt lgkmcnt(0)
	s_barrier
; #define PG8_STAGE(bufoff, gbase, voff) do { _Pragma("unroll") for (int _i = 0; _i < 2; ++_i) \
;         __builtin_amdgcn_global_load_lds((const unsigned*)((const char*)(gbase) + (voff)[_i]), (LAS unsigned*)(lds + (bufoff) + ldsw + _i * 8192), 16, 0, 0); } while (0)
; #define PG8_LDA(dst, b, h) do { _Pragma("unroll") for (int m = 0; m < 4; ++m) _Pragma("unroll") for (int k = 0; k < 2; ++k) dst[m][k] = *(const LAS bf16x8*)(lds + PG8_SA(b, h) + aoff + m * 2048 + k * 1024); } while (0)
; #define PG8_MMA(ai, bj, At, Bt) do { __builtin_amdgcn_s_setprio(1); _Pragma("unroll") for (int m = 0; m < 4; ++m) _Pragma("unroll") for (int n = 0; n < 2; ++n) _Pragma("unroll") for (int k = 0; k < 2; ++k) \
;         acc[ai][bj][m][n] = __builtin_amdgcn_mfma_f32_16x16x32_bf16(Bt[n][k], At[m][k], acc[ai][bj][m][n], 0, 0, 0); __builtin_amdgcn_s_setprio(0); } while (0)
; #define PG8_WAIT_V(n) asm volatile("s_waitcnt vmcnt(" #n ")" ::: "memory")
; #define PG8_WAIT_L(n) asm volatile("s_waitcnt lgkmcnt(" #n ")" ::: "memory")
; #define PG8_BAR __builtin_amdgcn_s_barrier()
; #define PG8_SCHED __builtin_amdgcn_sched_barrier(0)
; template <class Epi, class Sched, bool ALIGN_EPI = true>
; __device__ __forceinline__ void gemm_phase(LAS unsigned char* lds, const Gemm g, const Sched& S, const Epi& E) {
;     ...
;             PG8_WAIT_V(8); PG8_WAIT_L(0); PG8_BAR; PG8_MMA(0, 0, At, B0); PG8_MMA(0, 1, At, B1); PG8_BAR; PG8_SCHED;
;             PG8_LDA(At, 0, 1); PG8_STAGE(PG8_SB(0, 0), b2, voffB); PG8_STAGE(PG8_SB(0, 1), b2 + hB, voffB); PG8_STAGE(PG8_SA(0, 0), a2, voffA);
;             PG8_WAIT_V(8); PG8_WAIT_L(0); PG8_BAR; PG8_MMA(1, 0, At, B0); PG8_MMA(1, 1, At, B1); PG8_BAR; PG8_SCHED;
	s_setprio 1
	s_waitcnt lgkmcnt(0)
	v_mfma_f32_16x16x32_bf16 v[116:119], v[132:135], v[182:185], v[116:119]
	v_mfma_f32_16x16x32_bf16 v[116:119], v[136:139], v[186:189], v[116:119]
	v_mfma_f32_16x16x32_bf16 v[100:103], v[140:143], v[182:185], v[100:103]
	v_mfma_f32_16x16x32_bf16 v[100:103], v[144:147], v[186:189], v[100:103]
	v_mfma_f32_16x16x32_bf16 v[108:111], v[132:135], v[190:193], v[108:111]
	v_mfma_f32_16x16x32_bf16 v[108:111], v[136:139], v[194:197], v[108:111]
	v_mfma_f32_16x16x32_bf16 v[96:99], v[140:143], v[190:193], v[96:99]
	v_mfma_f32_16x16x32_bf16 v[96:99], v[144:147], v[194:197], v[96:99]
	v_mfma_f32_16x16x32_bf16 v[88:91], v[132:135], v[206:209], v[88:91]
	v_mfma_f32_16x16x32_bf16 v[88:91], v[136:139], v[210:213], v[88:91]
	v_mfma_f32_16x16x32_bf16 v[84:87], v[140:143], v[206:209], v[84:87]
	v_mfma_f32_16x16x32_bf16 v[84:87], v[144:147], v[210:213], v[84:87]
	v_mfma_f32_16x16x32_bf16 v[72:75], v[132:135], v[214:217], v[72:75]
	v_mfma_f32_16x16x32_bf16 v[72:75], v[136:139], v[218:221], v[72:75]
	v_mfma_f32_16x16x32_bf16 v[80:83], v[140:143], v[214:217], v[80:83]
	v_mfma_f32_16x16x32_bf16 v[80:83], v[144:147], v[218:221], v[80:83]
	s_setprio 0
	s_setprio 1
	v_mfma_f32_16x16x32_bf16 v[128:131], v[148:151], v[182:185], v[128:131]
	v_mfma_f32_16x16x32_bf16 v[128:131], v[152:155], v[186:189], v[128:131]
	v_mfma_f32_16x16x32_bf16 v[44:47], v[174:177], v[182:185], v[44:47]
	v_mfma_f32_16x16x32_bf16 v[44:47], v[178:181], v[186:189], v[44:47]
	v_mfma_f32_16x16x32_bf16 v[124:127], v[148:151], v[190:193], v[124:127]
	v_mfma_f32_16x16x32_bf16 v[124:127], v[152:155], v[194:197], v[124:127]
	v_mfma_f32_16x16x32_bf16 v[36:39], v[174:177], v[190:193], v[36:39]
	v_mfma_f32_16x16x32_bf16 v[36:39], v[178:181], v[194:197], v[36:39]
	v_mfma_f32_16x16x32_bf16 v[120:123], v[148:151], v[206:209], v[120:123]
	v_mfma_f32_16x16x32_bf16 v[120:123], v[152:155], v[210:213], v[120:123]
	v_mfma_f32_16x16x32_bf16 v[32:35], v[174:177], v[206:209], v[32:35]
	v_mfma_f32_16x16x32_bf16 v[32:35], v[178:181], v[210:213], v[32:35]
	v_mfma_f32_16x16x32_bf16 v[112:115], v[148:151], v[214:217], v[112:115]
	v_mfma_f32_16x16x32_bf16 v[112:115], v[152:155], v[218:221], v[112:115]
	s_setprio 2
	s_barrier
	v_mfma_f32_16x16x32_bf16 v[28:31], v[174:177], v[214:217], v[28:31]
	v_mfma_f32_16x16x32_bf16 v[28:31], v[178:181], v[218:221], v[28:31]
	s_setprio 0
	s_add_i32 s26, s30, s61
	v_lshl_add_u64 v[156:157], s[44:45], 0, v[166:167]
	s_mov_b32 m0, s26
	ds_read_b128 v[182:185], v205 offset:16384
	ds_read_b128 v[186:189], v205 offset:17408
	ds_read_b128 v[190:193], v205 offset:18432
	ds_read_b128 v[194:197], v205 offset:19456
	ds_read_b128 v[206:209], v205 offset:20480
	ds_read_b128 v[210:213], v205 offset:21504
	ds_read_b128 v[214:217], v205 offset:22528
	ds_read_b128 v[218:221], v205 offset:23552
	global_load_lds_dwordx4 v[156:157], off
	s_add_i32 m0, s26, 0x2000
	s_add_u32 s26, s44, 0x80000
	v_lshl_add_u64 v[160:161], s[44:45], 0, v[0:1]
	s_addc_u32 s27, s45, 0
	s_add_i32 s30, s31, s61
	global_load_lds_dwordx4 v[160:161], off
	v_lshl_add_u64 v[162:163], s[26:27], 0, v[166:167]
	s_mov_b32 m0, s30
	v_lshl_add_u64 v[222:223], s[58:59], 0, v[164:165]
	global_load_lds_dwordx4 v[162:163], off
	v_lshl_add_u64 v[162:163], s[26:27], 0, v[0:1]
	s_add_i32 m0, s30, 0x2000
	s_nop 0
	global_load_lds_dwordx4 v[162:163], off
	v_lshl_add_u64 v[162:163], s[58:59], 0, v[168:169]
	s_mov_b32 m0, s62
	s_nop 0
	global_load_lds_dwordx4 v[162:163], off
	s_mov_b32 m0, s63
	s_nop 0
	global_load_lds_dwordx4 v[222:223], off
	s_waitcnt vmcnt(8)
	s_waitcnt lgkmcnt(0)
	s_barrier
	s_setprio 1
	s_waitcnt lgkmcnt(0)
	v_mfma_f32_16x16x32_bf16 v[60:63], v[132:135], v[182:185], v[60:63]
	v_mfma_f32_16x16x32_bf16 v[60:63], v[136:139], v[186:189], v[60:63]
	v_mfma_f32_16x16x32_bf16 v[68:71], v[140:143], v[182:185], v[68:71]
	v_mfma_f32_16x16x32_bf16 v[68:71], v[144:147], v[186:189], v[68:71]
	v_mfma_f32_16x16x32_bf16 v[40:43], v[132:135], v[190:193], v[40:43]
	v_mfma_f32_16x16x32_bf16 v[40:43], v[136:139], v[194:197], v[40:43]
	v_mfma_f32_16x16x32_bf16 v[64:67], v[140:143], v[190:193], v[64:67]
	v_mfma_f32_16x16x32_bf16 v[64:67], v[144:147], v[194:197], v[64:67]
	v_mfma_f32_16x16x32_bf16 v[24:27], v[132:135], v[206:209], v[24:27]
	v_mfma_f32_16x16x32_bf16 v[24:27], v[136:139], v[210:213], v[24:27]
	v_mfma_f32_16x16x32_bf16 v[56:59], v[140:143], v[206:209], v[56:59]
	v_mfma_f32_16x16x32_bf16 v[56:59], v[144:147], v[210:213], v[56:59]
	v_mfma_f32_16x16x32_bf16 v[12:15], v[132:135], v[214:217], v[12:15]
	v_mfma_f32_16x16x32_bf16 v[12:15], v[136:139], v[218:221], v[12:15]
	v_mfma_f32_16x16x32_bf16 v[48:51], v[140:143], v[214:217], v[48:51]
	v_mfma_f32_16x16x32_bf16 v[48:51], v[144:147], v[218:221], v[48:51]
	s_setprio 0
	s_setprio 1
	v_mfma_f32_16x16x32_bf16 v[104:107], v[148:151], v[182:185], v[104:107]
	v_mfma_f32_16x16x32_bf16 v[104:107], v[152:155], v[186:189], v[104:107]
	v_mfma_f32_16x16x32_bf16 v[20:23], v[174:177], v[182:185], v[20:23]
	v_mfma_f32_16x16x32_bf16 v[20:23], v[178:181], v[186:189], v[20:23]
	v_mfma_f32_16x16x32_bf16 v[92:95], v[148:151], v[190:193], v[92:95]
	v_mfma_f32_16x16x32_bf16 v[92:95], v[152:155], v[194:197], v[92:95]
	v_mfma_f32_16x16x32_bf16 v[16:19], v[174:177], v[190:193], v[16:19]
	v_mfma_f32_16x16x32_bf16 v[16:19], v[178:181], v[194:197], v[16:19]
	v_mfma_f32_16x16x32_bf16 v[76:79], v[148:151], v[206:209], v[76:79]
	v_mfma_f32_16x16x32_bf16 v[76:79], v[152:155], v[210:213], v[76:79]
	v_mfma_f32_16x16x32_bf16 v[8:11], v[174:177], v[206:209], v[8:11]
	v_mfma_f32_16x16x32_bf16 v[8:11], v[178:181], v[210:213], v[8:11]
	v_mfma_f32_16x16x32_bf16 v[52:55], v[148:151], v[214:217], v[52:55]
	v_mfma_f32_16x16x32_bf16 v[52:55], v[152:155], v[218:221], v[52:55]
	s_setprio 2
	s_barrier
; #define PG8_STAGE(bufoff, gbase, voff) do { _Pragma("unroll") for (int _i = 0; _i < 2; ++_i) \
;         __builtin_amdgcn_global_load_lds((const unsigned*)((const char*)(gbase) + (voff)[_i]), (LAS unsigned*)(lds + (bufoff) + ldsw + _i * 8192), 16, 0, 0); } while (0)
; #define PG8_LDA(dst, b, h) do { _Pragma("unroll") for (int m = 0; m < 4; ++m) _Pragma("unroll") for (int k = 0; k < 2; ++k) dst[m][k] = *(const LAS bf16x8*)(lds + PG8_SA(b, h) + aoff + m * 2048 + k * 1024); } while (0)
; #define PG8_LDB(dst, b, h) do { _Pragma("unroll") for (int n = 0; n < 2; ++n) _Pragma("unroll") for (int k = 0; k < 2; ++k) dst[n][k] = *(const LAS bf16x8*)(lds + PG8_SB(b, h) + boff + n * 2048 + k * 1024); } while (0)
; #define PG8_MMA(ai, bj, At, Bt) do { __builtin_amdgcn_s_setprio(1); _Pragma("unroll") for (int m = 0; m < 4; ++m) _Pragma("unroll") for (int n = 0; n < 2; ++n) _Pragma("unroll") for (int k = 0; k < 2; ++k) \
;         acc[ai][bj][m][n] = __builtin_amdgcn_mfma_f32_16x16x32_bf16(Bt[n][k], At[m][k], acc[ai][bj][m][n], 0, 0, 0); __builtin_amdgcn_s_setprio(0); } while (0)
; #define PG8_WAIT_V(n) asm volatile("s_waitcnt vmcnt(" #n ")" ::: "memory")
; #define PG8_WAIT_L(n) asm volatile("s_waitcnt lgkmcnt(" #n ")" ::: "memory")
; #define PG8_BAR __builtin_amdgcn_s_barrier()
; #define PG8_SCHED __builtin_amdgcn_sched_barrier(0)
; template <class Epi, class Sched, bool ALIGN_EPI = true>
; __device__ __forceinline__ void gemm_phase(LAS unsigned char* lds, const Gemm g, const Sched& S, const Epi& E) {
;     ...
;             PG8_WAIT_V(8); PG8_WAIT_L(0); PG8_BAR; PG8_MMA(1, 0, At, B0); PG8_MMA(1, 1, At, B1); PG8_BAR; PG8_SCHED;
;             PG8_LDB(B0, 1, 0); PG8_LDB(B1, 1, 1); PG8_SCHED; PG8_LDA(At, 1, 0); PG8_STAGE(PG8_SA(0, 1), a2 + hA, voffA);
;             PG8_WAIT_V(8); PG8_WAIT_L(0); PG8_BAR; PG8_MMA(0, 0, At, B0); PG8_MMA(0, 1, At, B1); PG8_BAR; PG8_SCHED;
	v_mfma_f32_16x16x32_bf16 v[4:7], v[174:177], v[214:217], v[4:7]
	v_mfma_f32_16x16x32_bf16 v[4:7], v[178:181], v[218:221], v[4:7]
	s_setprio 0
	s_add_i32 s30, 0, 0x18000
	v_add_u32_e32 v2, s30, v204
	s_add_i32 s31, 0, 0x1c000
	ds_read_b128 v[132:135], v2
	ds_read_b128 v[136:139], v2 offset:1024
	ds_read_b128 v[140:143], v2 offset:2048
	ds_read_b128 v[144:147], v2 offset:3072
	v_add_u32_e32 v2, s31, v204
	ds_read_b128 v[148:151], v2
	ds_read_b128 v[152:155], v2 offset:1024
	ds_read_b128 v[174:177], v2 offset:2048
	ds_read_b128 v[178:181], v2 offset:3072
	s_add_u32 s26, s58, 0x80000
	s_addc_u32 s27, s59, 0
	s_mov_b32 m0, s64
	v_lshl_add_u64 v[224:225], s[26:27], 0, v[168:169]
	ds_read_b128 v[182:185], v205 offset:32768
	ds_read_b128 v[186:189], v205 offset:33792
	ds_read_b128 v[190:193], v205 offset:34816
	ds_read_b128 v[194:197], v205 offset:35840
	ds_read_b128 v[206:209], v205 offset:36864
	ds_read_b128 v[210:213], v205 offset:37888
	ds_read_b128 v[214:217], v205 offset:38912
	ds_read_b128 v[218:221], v205 offset:39936
	global_load_lds_dwordx4 v[224:225], off
	v_lshl_add_u64 v[224:225], s[26:27], 0, v[164:165]
	s_mov_b32 m0, s65
	s_nop 0
	global_load_lds_dwordx4 v[224:225], off
	s_waitcnt vmcnt(8)
	s_waitcnt lgkmcnt(0)
	s_barrier
	s_setprio 1
	s_waitcnt lgkmcnt(0)
	v_mfma_f32_16x16x32_bf16 v[116:119], v[132:135], v[182:185], v[116:119]
	v_mfma_f32_16x16x32_bf16 v[116:119], v[136:139], v[186:189], v[116:119]
	v_mfma_f32_16x16x32_bf16 v[100:103], v[140:143], v[182:185], v[100:103]
	v_mfma_f32_16x16x32_bf16 v[100:103], v[144:147], v[186:189], v[100:103]
	v_mfma_f32_16x16x32_bf16 v[108:111], v[132:135], v[190:193], v[108:111]
	v_mfma_f32_16x16x32_bf16 v[108:111], v[136:139], v[194:197], v[108:111]
	v_mfma_f32_16x16x32_bf16 v[96:99], v[140:143], v[190:193], v[96:99]
	v_mfma_f32_16x16x32_bf16 v[96:99], v[144:147], v[194:197], v[96:99]
	v_mfma_f32_16x16x32_bf16 v[88:91], v[132:135], v[206:209], v[88:91]
	v_mfma_f32_16x16x32_bf16 v[88:91], v[136:139], v[210:213], v[88:91]
	v_mfma_f32_16x16x32_bf16 v[84:87], v[140:143], v[206:209], v[84:87]
	v_mfma_f32_16x16x32_bf16 v[84:87], v[144:147], v[210:213], v[84:87]
	v_mfma_f32_16x16x32_bf16 v[72:75], v[132:135], v[214:217], v[72:75]
	v_mfma_f32_16x16x32_bf16 v[72:75], v[136:139], v[218:221], v[72:75]
	v_mfma_f32_16x16x32_bf16 v[80:83], v[140:143], v[214:217], v[80:83]
	v_mfma_f32_16x16x32_bf16 v[80:83], v[144:147], v[218:221], v[80:83]
	s_setprio 0
	s_setprio 1
	v_mfma_f32_16x16x32_bf16 v[128:131], v[148:151], v[182:185], v[128:131]
	v_mfma_f32_16x16x32_bf16 v[128:131], v[152:155], v[186:189], v[128:131]
	v_mfma_f32_16x16x32_bf16 v[44:47], v[174:177], v[182:185], v[44:47]
	v_mfma_f32_16x16x32_bf16 v[44:47], v[178:181], v[186:189], v[44:47]
	v_mfma_f32_16x16x32_bf16 v[124:127], v[148:151], v[190:193], v[124:127]
	v_mfma_f32_16x16x32_bf16 v[124:127], v[152:155], v[194:197], v[124:127]
	v_mfma_f32_16x16x32_bf16 v[36:39], v[174:177], v[190:193], v[36:39]
	v_mfma_f32_16x16x32_bf16 v[36:39], v[178:181], v[194:197], v[36:39]
	v_mfma_f32_16x16x32_bf16 v[120:123], v[148:151], v[206:209], v[120:123]
	v_mfma_f32_16x16x32_bf16 v[120:123], v[152:155], v[210:213], v[120:123]
	v_mfma_f32_16x16x32_bf16 v[32:35], v[174:177], v[206:209], v[32:35]
	v_mfma_f32_16x16x32_bf16 v[32:35], v[178:181], v[210:213], v[32:35]
	v_mfma_f32_16x16x32_bf16 v[112:115], v[148:151], v[214:217], v[112:115]
	v_mfma_f32_16x16x32_bf16 v[112:115], v[152:155], v[218:221], v[112:115]
	s_setprio 2
	s_barrier
; #define PG8_STAGE(bufoff, gbase, voff) do { _Pragma("unroll") for (int _i = 0; _i < 2; ++_i) \
;         __builtin_amdgcn_global_load_lds((const unsigned*)((const char*)(gbase) + (voff)[_i]), (LAS unsigned*)(lds + (bufoff) + ldsw + _i * 8192), 16, 0, 0); } while (0)
; #define PG8_LDA(dst, b, h) do { _Pragma("unroll") for (int m = 0; m < 4; ++m) _Pragma("unroll") for (int k = 0; k < 2; ++k) dst[m][k] = *(const LAS bf16x8*)(lds + PG8_SA(b, h) + aoff + m * 2048 + k * 1024); } while (0)
; #define PG8_MMA(ai, bj, At, Bt) do { __builtin_amdgcn_s_setprio(1); _Pragma("unroll") for (int m = 0; m < 4; ++m) _Pragma("unroll") for (int n = 0; n < 2; ++n) _Pragma("unroll") for (int k = 0; k < 2; ++k) \
;         acc[ai][bj][m][n] = __builtin_amdgcn_mfma_f32_16x16x32_bf16(Bt[n][k], At[m][k], acc[ai][bj][m][n], 0, 0, 0); __builtin_amdgcn_s_setprio(0); } while (0)
; #define PG8_WAIT_V(n) asm volatile("s_waitcnt vmcnt(" #n ")" ::: "memory")
; #define PG8_WAIT_L(n) asm volatile("s_waitcnt lgkmcnt(" #n ")" ::: "memory")
; #define PG8_BAR __builtin_amdgcn_s_barrier()
; #define PG8_SCHED __builtin_amdgcn_sched_barrier(0)
; template <class Epi, class Sched, bool ALIGN_EPI = true>
; __device__ __forceinline__ void gemm_phase(LAS unsigned char* lds, const Gemm g, const Sched& S, const Epi& E) {
;     ...
;             PG8_WAIT_V(8); PG8_WAIT_L(0); PG8_BAR; PG8_MMA(0, 0, At, B0); PG8_MMA(0, 1, At, B1); PG8_BAR; PG8_SCHED;
;             PG8_LDA(At, 1, 1); PG8_STAGE(PG8_SB(1, 0), b3, voffB); PG8_STAGE(PG8_SB(1, 1), b3 + hB, voffB); PG8_STAGE(PG8_SA(1, 0), a3, voffA);
;             PG8_WAIT_V(8); PG8_WAIT_L(0); PG8_BAR; PG8_MMA(1, 0, At, B0); PG8_MMA(1, 1, At, B1); PG8_BAR; PG8_SCHED;
	v_mfma_f32_16x16x32_bf16 v[28:31], v[174:177], v[214:217], v[28:31]
	v_mfma_f32_16x16x32_bf16 v[28:31], v[178:181], v[218:221], v[28:31]
	s_setprio 0
	s_add_i32 s26, s30, s61
	v_lshl_add_u64 v[156:157], v[156:157], 0, s[86:87]
	s_mov_b32 m0, s26
	ds_read_b128 v[182:185], v205 offset:49152
	ds_read_b128 v[186:189], v205 offset:50176
	ds_read_b128 v[190:193], v205 offset:51200
	ds_read_b128 v[194:197], v205 offset:52224
	ds_read_b128 v[206:209], v205 offset:53248
	ds_read_b128 v[210:213], v205 offset:54272
	ds_read_b128 v[214:217], v205 offset:55296
	ds_read_b128 v[218:221], v205 offset:56320
	global_load_lds_dwordx4 v[156:157], off
	s_add_i32 m0, s26, 0x2000
	s_add_u32 s26, s44, 0x80080
	v_lshl_add_u64 v[156:157], v[160:161], 0, s[86:87]
	s_addc_u32 s27, s45, 0
	s_add_i32 s30, s31, s61
	global_load_lds_dwordx4 v[156:157], off
	v_lshl_add_u64 v[156:157], s[26:27], 0, v[166:167]
	s_mov_b32 m0, s30
	s_nop 0
	global_load_lds_dwordx4 v[156:157], off
	v_lshl_add_u64 v[156:157], s[26:27], 0, v[0:1]
	s_add_i32 m0, s30, 0x2000
	s_nop 0
	global_load_lds_dwordx4 v[156:157], off
	v_lshl_add_u64 v[156:157], v[162:163], 0, s[86:87]
	s_mov_b32 m0, s75
	s_nop 0
	global_load_lds_dwordx4 v[156:157], off
	v_lshl_add_u64 v[156:157], v[222:223], 0, s[86:87]
	s_mov_b32 m0, s76
	s_nop 0
	global_load_lds_dwordx4 v[156:157], off
	s_waitcnt vmcnt(8)
	s_waitcnt lgkmcnt(0)
	s_barrier
	s_setprio 1
	s_waitcnt lgkmcnt(0)
	v_mfma_f32_16x16x32_bf16 v[60:63], v[132:135], v[182:185], v[60:63]
	v_mfma_f32_16x16x32_bf16 v[60:63], v[136:139], v[186:189], v[60:63]
	v_mfma_f32_16x16x32_bf16 v[68:71], v[140:143], v[182:185], v[68:71]
	v_mfma_f32_16x16x32_bf16 v[68:71], v[144:147], v[186:189], v[68:71]
	v_mfma_f32_16x16x32_bf16 v[40:43], v[132:135], v[190:193], v[40:43]
	v_mfma_f32_16x16x32_bf16 v[40:43], v[136:139], v[194:197], v[40:43]
	v_mfma_f32_16x16x32_bf16 v[64:67], v[140:143], v[190:193], v[64:67]
	v_mfma_f32_16x16x32_bf16 v[64:67], v[144:147], v[194:197], v[64:67]
	v_mfma_f32_16x16x32_bf16 v[24:27], v[132:135], v[206:209], v[24:27]
	v_mfma_f32_16x16x32_bf16 v[24:27], v[136:139], v[210:213], v[24:27]
	v_mfma_f32_16x16x32_bf16 v[56:59], v[140:143], v[206:209], v[56:59]
	v_mfma_f32_16x16x32_bf16 v[56:59], v[144:147], v[210:213], v[56:59]
	v_mfma_f32_16x16x32_bf16 v[12:15], v[132:135], v[214:217], v[12:15]
	v_mfma_f32_16x16x32_bf16 v[12:15], v[136:139], v[218:221], v[12:15]
	v_mfma_f32_16x16x32_bf16 v[48:51], v[140:143], v[214:217], v[48:51]
	v_mfma_f32_16x16x32_bf16 v[48:51], v[144:147], v[218:221], v[48:51]
	s_setprio 0
	s_setprio 1
	v_mfma_f32_16x16x32_bf16 v[104:107], v[148:151], v[182:185], v[104:107]
	v_mfma_f32_16x16x32_bf16 v[104:107], v[152:155], v[186:189], v[104:107]
	v_mfma_f32_16x16x32_bf16 v[20:23], v[174:177], v[182:185], v[20:23]
	v_mfma_f32_16x16x32_bf16 v[20:23], v[178:181], v[186:189], v[20:23]
	v_mfma_f32_16x16x32_bf16 v[92:95], v[148:151], v[190:193], v[92:95]
	v_mfma_f32_16x16x32_bf16 v[92:95], v[152:155], v[194:197], v[92:95]
	v_mfma_f32_16x16x32_bf16 v[16:19], v[174:177], v[190:193], v[16:19]
	v_mfma_f32_16x16x32_bf16 v[16:19], v[178:181], v[194:197], v[16:19]
	v_mfma_f32_16x16x32_bf16 v[76:79], v[148:151], v[206:209], v[76:79]
	v_mfma_f32_16x16x32_bf16 v[76:79], v[152:155], v[210:213], v[76:79]
	v_mfma_f32_16x16x32_bf16 v[8:11], v[174:177], v[206:209], v[8:11]
	v_mfma_f32_16x16x32_bf16 v[8:11], v[178:181], v[210:213], v[8:11]
	v_mfma_f32_16x16x32_bf16 v[52:55], v[148:151], v[214:217], v[52:55]
	v_mfma_f32_16x16x32_bf16 v[52:55], v[152:155], v[218:221], v[52:55]
	s_setprio 2
	s_barrier
	v_mfma_f32_16x16x32_bf16 v[4:7], v[174:177], v[214:217], v[4:7]
	v_mfma_f32_16x16x32_bf16 v[4:7], v[178:181], v[218:221], v[4:7]
	s_setprio 0
	s_add_i32 s25, s25, 2
	s_add_u32 s6, s6, 0x100
	s_addc_u32 s7, s7, 0
	s_add_u32 s19, s19, 0x100
	s_addc_u32 s24, s24, 0
	s_cmp_gt_u32 s25, 29
	s_cbranch_scc0 .LBB0_828

;     __device__ bool next(int i, Unit& u) const { if (i >= 2) return false; const int x = c & 7, j = c >> 3; u.pm = 32 * i + 4 * x + (j & 3); u.pn = j >> 2; return true; }
; #define PG8_STAGE(bufoff, gbase, voff) do { _Pragma("unroll") for (int _i = 0; _i < 2; ++_i) \
;         __builtin_amdgcn_global_load_lds((const unsigned*)((const char*)(gbase) + (voff)[_i]), (LAS unsigned*)(lds + (bufoff) + ldsw + _i * 8192), 16, 0, 0); } while (0)
; #define PG8_LDA(dst, b, h) do { _Pragma("unroll") for (int m = 0; m < 4; ++m) _Pragma("unroll") for (int k = 0; k < 2; ++k) dst[m][k] = *(const LAS bf16x8*)(lds + PG8_SA(b, h) + aoff + m * 2048 + k * 1024); } while (0)
; #define PG8_LDB(dst, b, h) do { _Pragma("unroll") for (int n = 0; n < 2; ++n) _Pragma("unroll") for (int k = 0; k < 2; ++k) dst[n][k] = *(const LAS bf16x8*)(lds + PG8_SB(b, h) + boff + n * 2048 + k * 1024); } while (0)
; #define PG8_WAIT_V(n) asm volatile("s_waitcnt vmcnt(" #n ")" ::: "memory")
; #define PG8_WAIT_L(n) asm volatile("s_waitcnt lgkmcnt(" #n ")" ::: "memory")
; #define PG8_BAR __builtin_amdgcn_s_barrier()
; #define PG8_SCHED __builtin_amdgcn_sched_barrier(0)
; template <class Epi, class Sched, bool ALIGN_EPI = true>
; __device__ __forceinline__ void gemm_phase(LAS unsigned char* lds, const Gemm g, const Sched& S, const Epi& E) {
;     ...
;         const bool has_next = S.next(ui + 1, nxt);
;         const char* nA = has_next ? (const char*)g.A + ((size_t)nxt.pm * BM * g.lda + (size_t)nxt.pn * g.a_pn_off) * 2 : cA; const char* nB = has_next ? (const char*)g.Bt + (size_t)nxt.pn * BM * g.ldb * 2 : cB;
;         for (int t = 0; t < nt; t += 2) {
;             const bool last = (t == nt - 2);
;             const char* a1 = cA + (size_t)(t + 1) * kstep;
;             const char* a2 = last ? nA : cA + (size_t)(t + 2) * kstep; const char* b2 = last ? nB : cB + (size_t)(t + 2) * kstep;
;             const char* a3 = a2 + kstep; const char* b3 = b2 + kstep;
;             PG8_LDB(B0, 0, 0); PG8_LDB(B1, 0, 1); PG8_SCHED; PG8_LDA(At, 0, 0); PG8_STAGE(PG8_SA(1, 1), a1 + hA, voffA);
;             PG8_WAIT_V(8); PG8_WAIT_L(0); PG8_BAR; PG8_MMA(0, 0, At, B0); PG8_MMA(0, 1, At, B1); PG8_BAR; PG8_SCHED;
;             PG8_LDA(At, 0, 1); PG8_STAGE(PG8_SB(0, 0), b2, voffB); PG8_STAGE(PG8_SB(0, 1), b2 + hB, voffB); PG8_STAGE(PG8_SA(0, 0), a2, voffA);
.LBB0_1110:
	s_add_u32 s16, s10, 0x100
	s_addc_u32 s17, s11, 0
	s_add_u32 s10, s10, 0x160080
	s_addc_u32 s11, s11, 0
	v_lshl_add_u64 v[132:133], s[10:11], 0, v[168:169]
	v_lshl_add_u64 v[134:135], s[10:11], 0, v[170:171]
	s_mov_b32 s18, -2
	s_mov_b64 s[10:11], 0
	s_add_u32 vcc_lo, s10, 0x100
	s_addc_u32 vcc_hi, s11, 0
	s_add_u32 s19, s16, s10
	s_addc_u32 s24, s17, s11
	s_add_i32 s25, 0, 0x10000
	s_cmpk_eq_i32 s18, 0x54
	s_cselect_b32 s65, s61, s24
	s_cselect_b32 s24, 0, vcc_lo
	s_cselect_b32 s64, s60, s19
	s_cselect_b32 s19, 0, vcc_hi
	s_add_u32 s62, s2, s24
	v_add_u32_e32 v160, s25, v188
	s_addc_u32 s63, s3, s19
	s_add_i32 s19, 0, 0x14000
	ds_read_b128 v[136:139], v160
	ds_read_b128 v[140:143], v160 offset:1024
	ds_read_b128 v[144:147], v160 offset:2048
	ds_read_b128 v[172:175], v160 offset:3072
	v_add_u32_e32 v160, s19, v188
	ds_read_b128 v[176:179], v160
	ds_read_b128 v[180:183], v160 offset:1024
	ds_read_b128 v[184:187], v160 offset:2048
	ds_read_b128 v[208:211], v160 offset:3072
	v_lshl_add_u64 v[160:161], v[132:133], 0, s[10:11]
	s_add_i32 m0, s67, 0xc000
	ds_read_b128 v[212:215], v197
	ds_read_b128 v[216:219], v197 offset:1024
	ds_read_b128 v[220:223], v197 offset:2048
	ds_read_b128 v[224:227], v197 offset:3072
	ds_read_b128 v[228:231], v197 offset:4096
	ds_read_b128 v[232:235], v197 offset:5120
	ds_read_b128 v[236:239], v197 offset:6144
	ds_read_b128 v[240:243], v197 offset:7168
	global_load_lds_dwordx4 v[160:161], off
	v_lshl_add_u64 v[160:161], v[134:135], 0, s[10:11]
	s_add_i32 m0, s67, 0xe000
	s_nop 0
	global_load_lds_dwordx4 v[160:161], off
	s_waitcnt vmcnt(8)
	s_waitcnt lgkmcnt(0)
	s_barrier
	s_setprio 1
	s_waitcnt lgkmcnt(0)
	v_mfma_f32_16x16x32_bf16 v[16:19], v[136:139], v[212:215], 0
	v_mfma_f32_16x16x32_bf16 v[16:19], v[140:143], v[216:219], v[16:19]
	v_mfma_f32_16x16x32_bf16 v[12:15], v[144:147], v[212:215], 0
	v_mfma_f32_16x16x32_bf16 v[12:15], v[172:175], v[216:219], v[12:15]
	v_mfma_f32_16x16x32_bf16 v[56:59], v[136:139], v[220:223], 0
	v_mfma_f32_16x16x32_bf16 v[56:59], v[140:143], v[224:227], v[56:59]
	v_mfma_f32_16x16x32_bf16 v[52:55], v[144:147], v[220:223], 0
	v_mfma_f32_16x16x32_bf16 v[52:55], v[172:175], v[224:227], v[52:55]
	v_mfma_f32_16x16x32_bf16 v[88:91], v[136:139], v[228:231], 0
	v_mfma_f32_16x16x32_bf16 v[88:91], v[140:143], v[232:235], v[88:91]
	v_mfma_f32_16x16x32_bf16 v[76:79], v[144:147], v[228:231], 0
	v_mfma_f32_16x16x32_bf16 v[76:79], v[172:175], v[232:235], v[76:79]
	v_mfma_f32_16x16x32_bf16 v[112:115], v[136:139], v[236:239], 0
	v_mfma_f32_16x16x32_bf16 v[112:115], v[140:143], v[240:243], v[112:115]
	v_mfma_f32_16x16x32_bf16 v[108:111], v[144:147], v[236:239], 0
	v_mfma_f32_16x16x32_bf16 v[108:111], v[172:175], v[240:243], v[108:111]
	s_setprio 0
	s_setprio 1
	v_mfma_f32_16x16x32_bf16 v[8:11], v[176:179], v[212:215], 0
	v_mfma_f32_16x16x32_bf16 v[8:11], v[180:183], v[216:219], v[8:11]
	v_mfma_f32_16x16x32_bf16 v[4:7], v[184:187], v[212:215], 0
	v_mfma_f32_16x16x32_bf16 v[4:7], v[208:211], v[216:219], v[4:7]
	v_mfma_f32_16x16x32_bf16 v[40:43], v[176:179], v[220:223], 0
	v_mfma_f32_16x16x32_bf16 v[40:43], v[180:183], v[224:227], v[40:43]
	v_mfma_f32_16x16x32_bf16 v[36:39], v[184:187], v[220:223], 0
	v_mfma_f32_16x16x32_bf16 v[36:39], v[208:211], v[224:227], v[36:39]
	v_mfma_f32_16x16x32_bf16 v[64:67], v[176:179], v[228:231], 0
	v_mfma_f32_16x16x32_bf16 v[64:67], v[180:183], v[232:235], v[64:67]
	v_mfma_f32_16x16x32_bf16 v[60:63], v[184:187], v[228:231], 0
	v_mfma_f32_16x16x32_bf16 v[60:63], v[208:211], v[232:235], v[60:63]
	v_mfma_f32_16x16x32_bf16 v[96:99], v[176:179], v[236:239], 0
	v_mfma_f32_16x16x32_bf16 v[96:99], v[180:183], v[240:243], v[96:99]
	s_setprio 2
	s_barrier
	v_mfma_f32_16x16x32_bf16 v[92:95], v[184:187], v[236:239], 0
	v_mfma_f32_16x16x32_bf16 v[92:95], v[208:211], v[240:243], v[92:95]
	s_setprio 0
	s_add_i32 s10, s25, s66
	v_lshl_add_u64 v[160:161], s[62:63], 0, v[2:3]
	s_mov_b32 m0, s10
	ds_read_b128 v[212:215], v197 offset:16384
	ds_read_b128 v[216:219], v197 offset:17408
	ds_read_b128 v[220:223], v197 offset:18432
	ds_read_b128 v[224:227], v197 offset:19456
	ds_read_b128 v[228:231], v197 offset:20480
	ds_read_b128 v[232:235], v197 offset:21504
	ds_read_b128 v[236:239], v197 offset:22528
	ds_read_b128 v[240:243], v197 offset:23552
	global_load_lds_dwordx4 v[160:161], off
	s_add_i32 m0, s10, 0x2000
	s_add_u32 s10, s62, 0x160000
	v_lshl_add_u64 v[162:163], s[62:63], 0, v[150:151]
	s_addc_u32 s11, s63, 0
	s_add_i32 s19, s19, s66
	global_load_lds_dwordx4 v[162:163], off
	v_lshl_add_u64 v[244:245], s[10:11], 0, v[2:3]
	s_mov_b32 m0, s19
	v_lshl_add_u64 v[246:247], s[64:65], 0, v[148:149]
	global_load_lds_dwordx4 v[244:245], off
	v_lshl_add_u64 v[244:245], s[10:11], 0, v[150:151]
	s_add_i32 m0, s19, 0x2000
	s_nop 0
	global_load_lds_dwordx4 v[244:245], off
	v_lshl_add_u64 v[244:245], s[64:65], 0, v[0:1]
	s_mov_b32 m0, s67
	s_nop 0
	global_load_lds_dwordx4 v[244:245], off
	s_mov_b32 m0, s75
	s_nop 0
	global_load_lds_dwordx4 v[246:247], off
	s_waitcnt vmcnt(8)
	s_waitcnt lgkmcnt(0)
	s_barrier
; #define PG8_STAGE(bufoff, gbase, voff) do { _Pragma("unroll") for (int _i = 0; _i < 2; ++_i) \
;         __builtin_amdgcn_global_load_lds((const unsigned*)((const char*)(gbase) + (voff)[_i]), (LAS unsigned*)(lds + (bufoff) + ldsw + _i * 8192), 16, 0, 0); } while (0)
; #define PG8_LDA(dst, b, h) do { _Pragma("unroll") for (int m = 0; m < 4; ++m) _Pragma("unroll") for (int k = 0; k < 2; ++k) dst[m][k] = *(const LAS bf16x8*)(lds + PG8_SA(b, h) + aoff + m * 2048 + k * 1024); } while (0)
; #define PG8_LDB(dst, b, h) do { _Pragma("unroll") for (int n = 0; n < 2; ++n) _Pragma("unroll") for (int k = 0; k < 2; ++k) dst[n][k] = *(const LAS bf16x8*)(lds + PG8_SB(b, h) + boff + n * 2048 + k * 1024); } while (0)
; #define PG8_MMA(ai, bj, At, Bt) do { __builtin_amdgcn_s_setprio(1); _Pragma("unroll") for (int m = 0; m < 4; ++m) _Pragma("unroll") for (int n = 0; n < 2; ++n) _Pragma("unroll") for (int k = 0; k < 2; ++k) \
;         acc[ai][bj][m][n] = __builtin_amdgcn_mfma_f32_16x16x32_bf16(Bt[n][k], At[m][k], acc[ai][bj][m][n], 0, 0, 0); __builtin_amdgcn_s_setprio(0); } while (0)
; #define PG8_WAIT_V(n) asm volatile("s_waitcnt vmcnt(" #n ")" ::: "memory")
; #define PG8_WAIT_L(n) asm volatile("s_waitcnt lgkmcnt(" #n ")" ::: "memory")
; #define PG8_BAR __builtin_amdgcn_s_barrier()
; #define PG8_SCHED __builtin_amdgcn_sched_barrier(0)
; template <class Epi, class Sched, bool ALIGN_EPI = true>
; __device__ __forceinline__ void gemm_phase(LAS unsigned char* lds, const Gemm g, const Sched& S, const Epi& E) {
;     ...
;             PG8_WAIT_V(8); PG8_WAIT_L(0); PG8_BAR; PG8_MMA(0, 0, At, B0); PG8_MMA(0, 1, At, B1); PG8_BAR; PG8_SCHED;
;             PG8_LDA(At, 0, 1); PG8_STAGE(PG8_SB(0, 0), b2, voffB); PG8_STAGE(PG8_SB(0, 1), b2 + hB, voffB); PG8_STAGE(PG8_SA(0, 0), a2, voffA);
;             PG8_WAIT_V(8); PG8_WAIT_L(0); PG8_BAR; PG8_MMA(1, 0, At, B0); PG8_MMA(1, 1, At, B1); PG8_BAR; PG8_SCHED;
;             PG8_LDB(B0, 1, 0); PG8_LDB(B1, 1, 1); PG8_SCHED; PG8_LDA(At, 1, 0); PG8_STAGE(PG8_SA(0, 1), a2 + hA, voffA);
;             PG8_WAIT_V(8); PG8_WAIT_L(0); PG8_BAR; PG8_MMA(0, 0, At, B0); PG8_MMA(0, 1, At, B1); PG8_BAR; PG8_SCHED;
	s_setprio 1
	s_waitcnt lgkmcnt(0)
	v_mfma_f32_16x16x32_bf16 v[128:131], v[136:139], v[212:215], 0
	v_mfma_f32_16x16x32_bf16 v[128:131], v[140:143], v[216:219], v[128:131]
	v_mfma_f32_16x16x32_bf16 v[124:127], v[144:147], v[212:215], 0
	v_mfma_f32_16x16x32_bf16 v[124:127], v[172:175], v[216:219], v[124:127]
	v_mfma_f32_16x16x32_bf16 v[104:107], v[136:139], v[220:223], 0
	v_mfma_f32_16x16x32_bf16 v[104:107], v[140:143], v[224:227], v[104:107]
	v_mfma_f32_16x16x32_bf16 v[100:103], v[144:147], v[220:223], 0
	v_mfma_f32_16x16x32_bf16 v[100:103], v[172:175], v[224:227], v[100:103]
	v_mfma_f32_16x16x32_bf16 v[72:75], v[136:139], v[228:231], 0
	v_mfma_f32_16x16x32_bf16 v[72:75], v[140:143], v[232:235], v[72:75]
	v_mfma_f32_16x16x32_bf16 v[68:71], v[144:147], v[228:231], 0
	v_mfma_f32_16x16x32_bf16 v[68:71], v[172:175], v[232:235], v[68:71]
	v_mfma_f32_16x16x32_bf16 v[32:35], v[136:139], v[236:239], 0
	v_mfma_f32_16x16x32_bf16 v[32:35], v[140:143], v[240:243], v[32:35]
	v_mfma_f32_16x16x32_bf16 v[28:31], v[144:147], v[236:239], 0
	v_mfma_f32_16x16x32_bf16 v[28:31], v[172:175], v[240:243], v[28:31]
	s_setprio 0
	s_setprio 1
	v_mfma_f32_16x16x32_bf16 v[120:123], v[176:179], v[212:215], 0
	v_mfma_f32_16x16x32_bf16 v[120:123], v[180:183], v[216:219], v[120:123]
	v_mfma_f32_16x16x32_bf16 v[116:119], v[184:187], v[212:215], 0
	v_mfma_f32_16x16x32_bf16 v[116:119], v[208:211], v[216:219], v[116:119]
	v_mfma_f32_16x16x32_bf16 v[84:87], v[176:179], v[220:223], 0
	v_mfma_f32_16x16x32_bf16 v[84:87], v[180:183], v[224:227], v[84:87]
	v_mfma_f32_16x16x32_bf16 v[80:83], v[184:187], v[220:223], 0
	v_mfma_f32_16x16x32_bf16 v[80:83], v[208:211], v[224:227], v[80:83]
	v_mfma_f32_16x16x32_bf16 v[48:51], v[176:179], v[228:231], 0
	v_mfma_f32_16x16x32_bf16 v[48:51], v[180:183], v[232:235], v[48:51]
	v_mfma_f32_16x16x32_bf16 v[44:47], v[184:187], v[228:231], 0
	v_mfma_f32_16x16x32_bf16 v[44:47], v[208:211], v[232:235], v[44:47]
	v_mfma_f32_16x16x32_bf16 v[24:27], v[176:179], v[236:239], 0
	v_mfma_f32_16x16x32_bf16 v[24:27], v[180:183], v[240:243], v[24:27]
	s_setprio 2
	s_barrier
	v_mfma_f32_16x16x32_bf16 v[20:23], v[184:187], v[236:239], 0
	v_mfma_f32_16x16x32_bf16 v[20:23], v[208:211], v[240:243], v[20:23]
	s_setprio 0
	s_add_i32 s19, 0, 0x18000
	s_add_i32 s24, 0, 0x1c000
	v_add_u32_e32 v172, s19, v188
	v_add_u32_e32 v207, s24, v188
	ds_read_b128 v[136:139], v172
	ds_read_b128 v[140:143], v172 offset:1024
	ds_read_b128 v[144:147], v172 offset:2048
	ds_read_b128 v[172:175], v172 offset:3072
	ds_read_b128 v[176:179], v207
	ds_read_b128 v[180:183], v207 offset:1024
	ds_read_b128 v[184:187], v207 offset:2048
	ds_read_b128 v[208:211], v207 offset:3072
	s_add_u32 s10, s64, 0x160000
	s_addc_u32 s11, s65, 0
	s_mov_b32 m0, s76
	v_lshl_add_u64 v[248:249], s[10:11], 0, v[0:1]
	ds_read_b128 v[212:215], v197 offset:32768
	ds_read_b128 v[216:219], v197 offset:33792
	ds_read_b128 v[220:223], v197 offset:34816
	ds_read_b128 v[224:227], v197 offset:35840
	ds_read_b128 v[228:231], v197 offset:36864
	ds_read_b128 v[232:235], v197 offset:37888
	ds_read_b128 v[236:239], v197 offset:38912
	ds_read_b128 v[240:243], v197 offset:39936
	global_load_lds_dwordx4 v[248:249], off
	v_lshl_add_u64 v[248:249], s[10:11], 0, v[148:149]
	s_mov_b32 m0, s77
	s_nop 0
	global_load_lds_dwordx4 v[248:249], off
	s_waitcnt vmcnt(8)
	s_waitcnt lgkmcnt(0)
	s_barrier
	s_setprio 1
	s_waitcnt lgkmcnt(0)
	v_mfma_f32_16x16x32_bf16 v[16:19], v[136:139], v[212:215], v[16:19]
	v_mfma_f32_16x16x32_bf16 v[16:19], v[140:143], v[216:219], v[16:19]
	v_mfma_f32_16x16x32_bf16 v[12:15], v[144:147], v[212:215], v[12:15]
	v_mfma_f32_16x16x32_bf16 v[12:15], v[172:175], v[216:219], v[12:15]
	v_mfma_f32_16x16x32_bf16 v[56:59], v[136:139], v[220:223], v[56:59]
	v_mfma_f32_16x16x32_bf16 v[56:59], v[140:143], v[224:227], v[56:59]
	v_mfma_f32_16x16x32_bf16 v[52:55], v[144:147], v[220:223], v[52:55]
	v_mfma_f32_16x16x32_bf16 v[52:55], v[172:175], v[224:227], v[52:55]
	v_mfma_f32_16x16x32_bf16 v[88:91], v[136:139], v[228:231], v[88:91]
	v_mfma_f32_16x16x32_bf16 v[88:91], v[140:143], v[232:235], v[88:91]
	v_mfma_f32_16x16x32_bf16 v[76:79], v[144:147], v[228:231], v[76:79]
	v_mfma_f32_16x16x32_bf16 v[76:79], v[172:175], v[232:235], v[76:79]
	v_mfma_f32_16x16x32_bf16 v[112:115], v[136:139], v[236:239], v[112:115]
	v_mfma_f32_16x16x32_bf16 v[112:115], v[140:143], v[240:243], v[112:115]
	v_mfma_f32_16x16x32_bf16 v[108:111], v[144:147], v[236:239], v[108:111]
	v_mfma_f32_16x16x32_bf16 v[108:111], v[172:175], v[240:243], v[108:111]
	s_setprio 0
	s_setprio 1
	v_mfma_f32_16x16x32_bf16 v[8:11], v[176:179], v[212:215], v[8:11]
	v_mfma_f32_16x16x32_bf16 v[8:11], v[180:183], v[216:219], v[8:11]
	v_mfma_f32_16x16x32_bf16 v[4:7], v[184:187], v[212:215], v[4:7]
	v_mfma_f32_16x16x32_bf16 v[4:7], v[208:211], v[216:219], v[4:7]
	v_mfma_f32_16x16x32_bf16 v[40:43], v[176:179], v[220:223], v[40:43]
	v_mfma_f32_16x16x32_bf16 v[40:43], v[180:183], v[224:227], v[40:43]
	v_mfma_f32_16x16x32_bf16 v[36:39], v[184:187], v[220:223], v[36:39]
	v_mfma_f32_16x16x32_bf16 v[36:39], v[208:211], v[224:227], v[36:39]
	v_mfma_f32_16x16x32_bf16 v[64:67], v[176:179], v[228:231], v[64:67]
	v_mfma_f32_16x16x32_bf16 v[64:67], v[180:183], v[232:235], v[64:67]
	v_mfma_f32_16x16x32_bf16 v[60:63], v[184:187], v[228:231], v[60:63]
	v_mfma_f32_16x16x32_bf16 v[60:63], v[208:211], v[232:235], v[60:63]
	v_mfma_f32_16x16x32_bf16 v[96:99], v[176:179], v[236:239], v[96:99]
	v_mfma_f32_16x16x32_bf16 v[96:99], v[180:183], v[240:243], v[96:99]
	s_setprio 2
	s_barrier
; #define PG8_STAGE(bufoff, gbase, voff) do { _Pragma("unroll") for (int _i = 0; _i < 2; ++_i) \
;         __builtin_amdgcn_global_load_lds((const unsigned*)((const char*)(gbase) + (voff)[_i]), (LAS unsigned*)(lds + (bufoff) + ldsw + _i * 8192), 16, 0, 0); } while (0)
; #define PG8_LDA(dst, b, h) do { _Pragma("unroll") for (int m = 0; m < 4; ++m) _Pragma("unroll") for (int k = 0; k < 2; ++k) dst[m][k] = *(const LAS bf16x8*)(lds + PG8_SA(b, h) + aoff + m * 2048 + k * 1024); } while (0)
; #define PG8_LDB(dst, b, h) do { _Pragma("unroll") for (int n = 0; n < 2; ++n) _Pragma("unroll") for (int k = 0; k < 2; ++k) dst[n][k] = *(const LAS bf16x8*)(lds + PG8_SB(b, h) + boff + n * 2048 + k * 1024); } while (0)
; #define PG8_WAIT_V(n) asm volatile("s_waitcnt vmcnt(" #n ")" ::: "memory")
; #define PG8_WAIT_L(n) asm volatile("s_waitcnt lgkmcnt(" #n ")" ::: "memory")
; template <class Epi, class Sched, bool ALIGN_EPI = true>
; __device__ __forceinline__ void gemm_phase(LAS unsigned char* lds, const Gemm g, const Sched& S, const Epi& E) {
;     ...
;             const bool last = (t == nt - 2);
;             const char* a1 = cA + (size_t)(t + 1) * kstep;
;             const char* a2 = last ? nA : cA + (size_t)(t + 2) * kstep; const char* b2 = last ? nB : cB + (size_t)(t + 2) * kstep;
;             const char* a3 = a2 + kstep; const char* b3 = b2 + kstep;
;             PG8_LDB(B0, 0, 0); PG8_LDB(B1, 0, 1); PG8_SCHED; PG8_LDA(At, 0, 0); PG8_STAGE(PG8_SA(1, 1), a1 + hA, voffA);
;             PG8_WAIT_V(8); PG8_WAIT_L(0); PG8_BAR; PG8_MMA(0, 0, At, B0); PG8_MMA(0, 1, At, B1); PG8_BAR; PG8_SCHED;
;             PG8_LDA(At, 0, 1); PG8_STAGE(PG8_SB(0, 0), b2, voffB); PG8_STAGE(PG8_SB(0, 1), b2 + hB, voffB); PG8_STAGE(PG8_SA(0, 0), a2, voffA);
;             PG8_WAIT_V(8); PG8_WAIT_L(0); PG8_BAR; PG8_MMA(1, 0, At, B0); PG8_MMA(1, 1, At, B1); PG8_BAR; PG8_SCHED;
;             PG8_LDB(B0, 1, 0); PG8_LDB(B1, 1, 1); PG8_SCHED; PG8_LDA(At, 1, 0); PG8_STAGE(PG8_SA(0, 1), a2 + hA, voffA);
;             PG8_WAIT_V(8); PG8_WAIT_L(0); PG8_BAR; PG8_MMA(0, 0, At, B0); PG8_MMA(0, 1, At, B1); PG8_BAR; PG8_SCHED;
;             PG8_LDA(At, 1, 1); PG8_STAGE(PG8_SB(1, 0), b3, voffB); PG8_STAGE(PG8_SB(1, 1), b3 + hB, voffB); PG8_STAGE(PG8_SA(1, 0), a3, voffA);
;             PG8_WAIT_V(8); PG8_WAIT_L(0); PG8_BAR; PG8_MMA(1, 0, At, B0); PG8_MMA(1, 1, At, B1); PG8_BAR; PG8_SCHED;
	v_mfma_f32_16x16x32_bf16 v[92:95], v[184:187], v[236:239], v[92:95]
	v_mfma_f32_16x16x32_bf16 v[92:95], v[208:211], v[240:243], v[92:95]
	s_setprio 0
	s_add_i32 s10, s19, s66
	v_lshl_add_u64 v[160:161], v[160:161], 0, s[86:87]
	s_mov_b32 m0, s10
	ds_read_b128 v[212:215], v197 offset:49152
	ds_read_b128 v[216:219], v197 offset:50176
	ds_read_b128 v[220:223], v197 offset:51200
	ds_read_b128 v[224:227], v197 offset:52224
	ds_read_b128 v[228:231], v197 offset:53248
	ds_read_b128 v[232:235], v197 offset:54272
	ds_read_b128 v[236:239], v197 offset:55296
	ds_read_b128 v[240:243], v197 offset:56320
	global_load_lds_dwordx4 v[160:161], off
	s_add_i32 m0, s10, 0x2000
	s_add_u32 s10, s62, 0x160080
	v_lshl_add_u64 v[160:161], v[162:163], 0, s[86:87]
	s_addc_u32 s11, s63, 0
	s_add_i32 s19, s24, s66
	global_load_lds_dwordx4 v[160:161], off
	v_lshl_add_u64 v[160:161], s[10:11], 0, v[2:3]
	s_mov_b32 m0, s19
	s_nop 0
	global_load_lds_dwordx4 v[160:161], off
	v_lshl_add_u64 v[160:161], s[10:11], 0, v[150:151]
	s_add_i32 m0, s19, 0x2000
	s_nop 0
	global_load_lds_dwordx4 v[160:161], off
	v_lshl_add_u64 v[160:161], v[244:245], 0, s[86:87]
	s_mov_b32 m0, s80
	s_nop 0
	global_load_lds_dwordx4 v[160:161], off
	v_lshl_add_u64 v[160:161], v[246:247], 0, s[86:87]
	s_mov_b32 m0, s81
	s_nop 0
	global_load_lds_dwordx4 v[160:161], off
	s_waitcnt vmcnt(8)
	s_waitcnt lgkmcnt(0)
	s_barrier
	s_setprio 1
	s_waitcnt lgkmcnt(0)
	v_mfma_f32_16x16x32_bf16 v[128:131], v[136:139], v[212:215], v[128:131]
	v_mfma_f32_16x16x32_bf16 v[128:131], v[140:143], v[216:219], v[128:131]
	v_mfma_f32_16x16x32_bf16 v[124:127], v[144:147], v[212:215], v[124:127]
	v_mfma_f32_16x16x32_bf16 v[124:127], v[172:175], v[216:219], v[124:127]
	v_mfma_f32_16x16x32_bf16 v[104:107], v[136:139], v[220:223], v[104:107]
	v_mfma_f32_16x16x32_bf16 v[104:107], v[140:143], v[224:227], v[104:107]
	v_mfma_f32_16x16x32_bf16 v[100:103], v[144:147], v[220:223], v[100:103]
	v_mfma_f32_16x16x32_bf16 v[100:103], v[172:175], v[224:227], v[100:103]
	v_mfma_f32_16x16x32_bf16 v[72:75], v[136:139], v[228:231], v[72:75]
	v_mfma_f32_16x16x32_bf16 v[72:75], v[140:143], v[232:235], v[72:75]
	v_mfma_f32_16x16x32_bf16 v[68:71], v[144:147], v[228:231], v[68:71]
	v_mfma_f32_16x16x32_bf16 v[68:71], v[172:175], v[232:235], v[68:71]
	v_mfma_f32_16x16x32_bf16 v[32:35], v[136:139], v[236:239], v[32:35]
	v_mfma_f32_16x16x32_bf16 v[32:35], v[140:143], v[240:243], v[32:35]
	v_mfma_f32_16x16x32_bf16 v[28:31], v[144:147], v[236:239], v[28:31]
	v_mfma_f32_16x16x32_bf16 v[28:31], v[172:175], v[240:243], v[28:31]
	s_setprio 0
	s_setprio 1
	v_mfma_f32_16x16x32_bf16 v[120:123], v[176:179], v[212:215], v[120:123]
	v_mfma_f32_16x16x32_bf16 v[120:123], v[180:183], v[216:219], v[120:123]
	v_mfma_f32_16x16x32_bf16 v[116:119], v[184:187], v[212:215], v[116:119]
	v_mfma_f32_16x16x32_bf16 v[116:119], v[208:211], v[216:219], v[116:119]
	v_mfma_f32_16x16x32_bf16 v[84:87], v[176:179], v[220:223], v[84:87]
	v_mfma_f32_16x16x32_bf16 v[84:87], v[180:183], v[224:227], v[84:87]
	v_mfma_f32_16x16x32_bf16 v[80:83], v[184:187], v[220:223], v[80:83]
	v_mfma_f32_16x16x32_bf16 v[80:83], v[208:211], v[224:227], v[80:83]
	v_mfma_f32_16x16x32_bf16 v[48:51], v[176:179], v[228:231], v[48:51]
	v_mfma_f32_16x16x32_bf16 v[48:51], v[180:183], v[232:235], v[48:51]
	v_mfma_f32_16x16x32_bf16 v[44:47], v[184:187], v[228:231], v[44:47]
	v_mfma_f32_16x16x32_bf16 v[44:47], v[208:211], v[232:235], v[44:47]
	v_mfma_f32_16x16x32_bf16 v[24:27], v[176:179], v[236:239], v[24:27]
	v_mfma_f32_16x16x32_bf16 v[24:27], v[180:183], v[240:243], v[24:27]
	s_setprio 2
	s_barrier
	v_mfma_f32_16x16x32_bf16 v[20:23], v[184:187], v[236:239], v[20:23]
	v_mfma_f32_16x16x32_bf16 v[20:23], v[208:211], v[240:243], v[20:23]
	s_setprio 0
	s_add_i32 s18, s18, 2
	s_cmpk_gt_u32 s18, 0x55
	s_mov_b64 s[10:11], vcc
	s_cbranch_scc1 .Lpeel_exit_1111
.LBB0_1111:
	s_add_u32 vcc_lo, s10, 0x100
	s_addc_u32 vcc_hi, s11, 0
	s_add_u32 s19, s16, s10
	s_addc_u32 s24, s17, s11
	s_add_i32 s25, 0, 0x10000
	s_cmpk_eq_i32 s18, 0x54
	s_cselect_b32 s65, s61, s24
	s_cselect_b32 s24, 0, vcc_lo
	s_cselect_b32 s64, s60, s19
	s_cselect_b32 s19, 0, vcc_hi
	s_add_u32 s62, s2, s24
	v_add_u32_e32 v160, s25, v188
	s_addc_u32 s63, s3, s19
	s_add_i32 s19, 0, 0x14000
	ds_read_b128 v[136:139], v160
	ds_read_b128 v[140:143], v160 offset:1024
	ds_read_b128 v[144:147], v160 offset:2048
	ds_read_b128 v[172:175], v160 offset:3072
	v_add_u32_e32 v160, s19, v188
	ds_read_b128 v[176:179], v160
	ds_read_b128 v[180:183], v160 offset:1024
	ds_read_b128 v[184:187], v160 offset:2048
	ds_read_b128 v[208:211], v160 offset:3072
	v_lshl_add_u64 v[160:161], v[132:133], 0, s[10:11]
	s_add_i32 m0, s67, 0xc000
	ds_read_b128 v[212:215], v197
	ds_read_b128 v[216:219], v197 offset:1024
	ds_read_b128 v[220:223], v197 offset:2048
	ds_read_b128 v[224:227], v197 offset:3072
	ds_read_b128 v[228:231], v197 offset:4096
	ds_read_b128 v[232:235], v197 offset:5120
	ds_read_b128 v[236:239], v197 offset:6144
	ds_read_b128 v[240:243], v197 offset:7168
	global_load_lds_dwordx4 v[160:161], off
	v_lshl_add_u64 v[160:161], v[134:135], 0, s[10:11]
	s_add_i32 m0, s67, 0xe000
	s_nop 0
	global_load_lds_dwordx4 v[160:161], off
	s_waitcnt vmcnt(8)
	s_waitcnt lgkmcnt(0)
	s_barrier
; #define PG8_STAGE(bufoff, gbase, voff) do { _Pragma("unroll") for (int _i = 0; _i < 2; ++_i) \
;         __builtin_amdgcn_global_load_lds((const unsigned*)((const char*)(gbase) + (voff)[_i]), (LAS unsigned*)(lds + (bufoff) + ldsw + _i * 8192), 16, 0, 0); } while (0)
; #define PG8_LDA(dst, b, h) do { _Pragma("unroll") for (int m = 0; m < 4; ++m) _Pragma("unroll") for (int k = 0; k < 2; ++k) dst[m][k] = *(const LAS bf16x8*)(lds + PG8_SA(b, h) + aoff + m * 2048 + k * 1024); } while (0)
; #define PG8_MMA(ai, bj, At, Bt) do { __builtin_amdgcn_s_setprio(1); _Pragma("unroll") for (int m = 0; m < 4; ++m) _Pragma("unroll") for (int n = 0; n < 2; ++n) _Pragma("unroll") for (int k = 0; k < 2; ++k) \
;         acc[ai][bj][m][n] = __builtin_amdgcn_mfma_f32_16x16x32_bf16(Bt[n][k], At[m][k], acc[ai][bj][m][n], 0, 0, 0); __builtin_amdgcn_s_setprio(0); } while (0)
; #define PG8_WAIT_V(n) asm volatile("s_waitcnt vmcnt(" #n ")" ::: "memory")
; #define PG8_WAIT_L(n) asm volatile("s_waitcnt lgkmcnt(" #n ")" ::: "memory")
; #define PG8_BAR __builtin_amdgcn_s_barrier()
; #define PG8_SCHED __builtin_amdgcn_sched_barrier(0)
; template <class Epi, class Sched, bool ALIGN_EPI = true>
; __device__ __forceinline__ void gemm_phase(LAS unsigned char* lds, const Gemm g, const Sched& S, const Epi& E) {
;     ...
;             PG8_WAIT_V(8); PG8_WAIT_L(0); PG8_BAR; PG8_MMA(0, 0, At, B0); PG8_MMA(0, 1, At, B1); PG8_BAR; PG8_SCHED;
;             PG8_LDA(At, 0, 1); PG8_STAGE(PG8_SB(0, 0), b2, voffB); PG8_STAGE(PG8_SB(0, 1), b2 + hB, voffB); PG8_STAGE(PG8_SA(0, 0), a2, voffA);
;             PG8_WAIT_V(8); PG8_WAIT_L(0); PG8_BAR; PG8_MMA(1, 0, At, B0); PG8_MMA(1, 1, At, B1); PG8_BAR; PG8_SCHED;
	s_setprio 1
	s_waitcnt lgkmcnt(0)
	v_mfma_f32_16x16x32_bf16 v[16:19], v[136:139], v[212:215], v[16:19]
	v_mfma_f32_16x16x32_bf16 v[16:19], v[140:143], v[216:219], v[16:19]
	v_mfma_f32_16x16x32_bf16 v[12:15], v[144:147], v[212:215], v[12:15]
	v_mfma_f32_16x16x32_bf16 v[12:15], v[172:175], v[216:219], v[12:15]
	v_mfma_f32_16x16x32_bf16 v[56:59], v[136:139], v[220:223], v[56:59]
	v_mfma_f32_16x16x32_bf16 v[56:59], v[140:143], v[224:227], v[56:59]
	v_mfma_f32_16x16x32_bf16 v[52:55], v[144:147], v[220:223], v[52:55]
	v_mfma_f32_16x16x32_bf16 v[52:55], v[172:175], v[224:227], v[52:55]
	v_mfma_f32_16x16x32_bf16 v[88:91], v[136:139], v[228:231], v[88:91]
	v_mfma_f32_16x16x32_bf16 v[88:91], v[140:143], v[232:235], v[88:91]
	v_mfma_f32_16x16x32_bf16 v[76:79], v[144:147], v[228:231], v[76:79]
	v_mfma_f32_16x16x32_bf16 v[76:79], v[172:175], v[232:235], v[76:79]
	v_mfma_f32_16x16x32_bf16 v[112:115], v[136:139], v[236:239], v[112:115]
	v_mfma_f32_16x16x32_bf16 v[112:115], v[140:143], v[240:243], v[112:115]
	v_mfma_f32_16x16x32_bf16 v[108:111], v[144:147], v[236:239], v[108:111]
	v_mfma_f32_16x16x32_bf16 v[108:111], v[172:175], v[240:243], v[108:111]
	s_setprio 0
	s_setprio 1
	v_mfma_f32_16x16x32_bf16 v[8:11], v[176:179], v[212:215], v[8:11]
	v_mfma_f32_16x16x32_bf16 v[8:11], v[180:183], v[216:219], v[8:11]
	v_mfma_f32_16x16x32_bf16 v[4:7], v[184:187], v[212:215], v[4:7]
	v_mfma_f32_16x16x32_bf16 v[4:7], v[208:211], v[216:219], v[4:7]
	v_mfma_f32_16x16x32_bf16 v[40:43], v[176:179], v[220:223], v[40:43]
	v_mfma_f32_16x16x32_bf16 v[40:43], v[180:183], v[224:227], v[40:43]
	v_mfma_f32_16x16x32_bf16 v[36:39], v[184:187], v[220:223], v[36:39]
	v_mfma_f32_16x16x32_bf16 v[36:39], v[208:211], v[224:227], v[36:39]
	v_mfma_f32_16x16x32_bf16 v[64:67], v[176:179], v[228:231], v[64:67]
	v_mfma_f32_16x16x32_bf16 v[64:67], v[180:183], v[232:235], v[64:67]
	v_mfma_f32_16x16x32_bf16 v[60:63], v[184:187], v[228:231], v[60:63]
	v_mfma_f32_16x16x32_bf16 v[60:63], v[208:211], v[232:235], v[60:63]
	v_mfma_f32_16x16x32_bf16 v[96:99], v[176:179], v[236:239], v[96:99]
	v_mfma_f32_16x16x32_bf16 v[96:99], v[180:183], v[240:243], v[96:99]
	s_setprio 2
	s_barrier
	v_mfma_f32_16x16x32_bf16 v[92:95], v[184:187], v[236:239], v[92:95]
	v_mfma_f32_16x16x32_bf16 v[92:95], v[208:211], v[240:243], v[92:95]
	s_setprio 0
	s_add_i32 s10, s25, s66
	v_lshl_add_u64 v[160:161], s[62:63], 0, v[2:3]
	s_mov_b32 m0, s10
	ds_read_b128 v[212:215], v197 offset:16384
	ds_read_b128 v[216:219], v197 offset:17408
	ds_read_b128 v[220:223], v197 offset:18432
	ds_read_b128 v[224:227], v197 offset:19456
	ds_read_b128 v[228:231], v197 offset:20480
	ds_read_b128 v[232:235], v197 offset:21504
	ds_read_b128 v[236:239], v197 offset:22528
	ds_read_b128 v[240:243], v197 offset:23552
	global_load_lds_dwordx4 v[160:161], off
	s_add_i32 m0, s10, 0x2000
	s_add_u32 s10, s62, 0x160000
	v_lshl_add_u64 v[162:163], s[62:63], 0, v[150:151]
	s_addc_u32 s11, s63, 0
	s_add_i32 s19, s19, s66
	global_load_lds_dwordx4 v[162:163], off
	v_lshl_add_u64 v[244:245], s[10:11], 0, v[2:3]
	s_mov_b32 m0, s19
	v_lshl_add_u64 v[246:247], s[64:65], 0, v[148:149]
	global_load_lds_dwordx4 v[244:245], off
	v_lshl_add_u64 v[244:245], s[10:11], 0, v[150:151]
	s_add_i32 m0, s19, 0x2000
	s_nop 0
	global_load_lds_dwordx4 v[244:245], off
	v_lshl_add_u64 v[244:245], s[64:65], 0, v[0:1]
	s_mov_b32 m0, s67
	s_nop 0
	global_load_lds_dwordx4 v[244:245], off
	s_mov_b32 m0, s75
	s_nop 0
	global_load_lds_dwordx4 v[246:247], off
	s_waitcnt vmcnt(8)
	s_waitcnt lgkmcnt(0)
	s_barrier
	s_setprio 1
	s_waitcnt lgkmcnt(0)
	v_mfma_f32_16x16x32_bf16 v[128:131], v[136:139], v[212:215], v[128:131]
	v_mfma_f32_16x16x32_bf16 v[128:131], v[140:143], v[216:219], v[128:131]
	v_mfma_f32_16x16x32_bf16 v[124:127], v[144:147], v[212:215], v[124:127]
	v_mfma_f32_16x16x32_bf16 v[124:127], v[172:175], v[216:219], v[124:127]
	v_mfma_f32_16x16x32_bf16 v[104:107], v[136:139], v[220:223], v[104:107]
	v_mfma_f32_16x16x32_bf16 v[104:107], v[140:143], v[224:227], v[104:107]
	v_mfma_f32_16x16x32_bf16 v[100:103], v[144:147], v[220:223], v[100:103]
	v_mfma_f32_16x16x32_bf16 v[100:103], v[172:175], v[224:227], v[100:103]
	v_mfma_f32_16x16x32_bf16 v[72:75], v[136:139], v[228:231], v[72:75]
	v_mfma_f32_16x16x32_bf16 v[72:75], v[140:143], v[232:235], v[72:75]
	v_mfma_f32_16x16x32_bf16 v[68:71], v[144:147], v[228:231], v[68:71]
	v_mfma_f32_16x16x32_bf16 v[68:71], v[172:175], v[232:235], v[68:71]
	v_mfma_f32_16x16x32_bf16 v[32:35], v[136:139], v[236:239], v[32:35]
	v_mfma_f32_16x16x32_bf16 v[32:35], v[140:143], v[240:243], v[32:35]
	v_mfma_f32_16x16x32_bf16 v[28:31], v[144:147], v[236:239], v[28:31]
	v_mfma_f32_16x16x32_bf16 v[28:31], v[172:175], v[240:243], v[28:31]
	s_setprio 0
	s_setprio 1
	v_mfma_f32_16x16x32_bf16 v[120:123], v[176:179], v[212:215], v[120:123]
	v_mfma_f32_16x16x32_bf16 v[120:123], v[180:183], v[216:219], v[120:123]
	v_mfma_f32_16x16x32_bf16 v[116:119], v[184:187], v[212:215], v[116:119]
	v_mfma_f32_16x16x32_bf16 v[116:119], v[208:211], v[216:219], v[116:119]
	v_mfma_f32_16x16x32_bf16 v[84:87], v[176:179], v[220:223], v[84:87]
	v_mfma_f32_16x16x32_bf16 v[84:87], v[180:183], v[224:227], v[84:87]
	v_mfma_f32_16x16x32_bf16 v[80:83], v[184:187], v[220:223], v[80:83]
	v_mfma_f32_16x16x32_bf16 v[80:83], v[208:211], v[224:227], v[80:83]
	v_mfma_f32_16x16x32_bf16 v[48:51], v[176:179], v[228:231], v[48:51]
	v_mfma_f32_16x16x32_bf16 v[48:51], v[180:183], v[232:235], v[48:51]
	v_mfma_f32_16x16x32_bf16 v[44:47], v[184:187], v[228:231], v[44:47]
	v_mfma_f32_16x16x32_bf16 v[44:47], v[208:211], v[232:235], v[44:47]
	v_mfma_f32_16x16x32_bf16 v[24:27], v[176:179], v[236:239], v[24:27]
	v_mfma_f32_16x16x32_bf16 v[24:27], v[180:183], v[240:243], v[24:27]
	s_setprio 2
	s_barrier
; #define PG8_STAGE(bufoff, gbase, voff) do { _Pragma("unroll") for (int _i = 0; _i < 2; ++_i) \
;         __builtin_amdgcn_global_load_lds((const unsigned*)((const char*)(gbase) + (voff)[_i]), (LAS unsigned*)(lds + (bufoff) + ldsw + _i * 8192), 16, 0, 0); } while (0)
; #define PG8_LDA(dst, b, h) do { _Pragma("unroll") for (int m = 0; m < 4; ++m) _Pragma("unroll") for (int k = 0; k < 2; ++k) dst[m][k] = *(const LAS bf16x8*)(lds + PG8_SA(b, h) + aoff + m * 2048 + k * 1024); } while (0)
; #define PG8_LDB(dst, b, h) do { _Pragma("unroll") for (int n = 0; n < 2; ++n) _Pragma("unroll") for (int k = 0; k < 2; ++k) dst[n][k] = *(const LAS bf16x8*)(lds + PG8_SB(b, h) + boff + n * 2048 + k * 1024); } while (0)
; #define PG8_MMA(ai, bj, At, Bt) do { __builtin_amdgcn_s_setprio(1); _Pragma("unroll") for (int m = 0; m < 4; ++m) _Pragma("unroll") for (int n = 0; n < 2; ++n) _Pragma("unroll") for (int k = 0; k < 2; ++k) \
;         acc[ai][bj][m][n] = __builtin_amdgcn_mfma_f32_16x16x32_bf16(Bt[n][k], At[m][k], acc[ai][bj][m][n], 0, 0, 0); __builtin_amdgcn_s_setprio(0); } while (0)
; #define PG8_WAIT_V(n) asm volatile("s_waitcnt vmcnt(" #n ")" ::: "memory")
; #define PG8_WAIT_L(n) asm volatile("s_waitcnt lgkmcnt(" #n ")" ::: "memory")
; #define PG8_BAR __builtin_amdgcn_s_barrier()
; #define PG8_SCHED __builtin_amdgcn_sched_barrier(0)
; template <class Epi, class Sched, bool ALIGN_EPI = true>
; __device__ __forceinline__ void gemm_phase(LAS unsigned char* lds, const Gemm g, const Sched& S, const Epi& E) {
;     ...
;             PG8_WAIT_V(8); PG8_WAIT_L(0); PG8_BAR; PG8_MMA(1, 0, At, B0); PG8_MMA(1, 1, At, B1); PG8_BAR; PG8_SCHED;
;             PG8_LDB(B0, 1, 0); PG8_LDB(B1, 1, 1); PG8_SCHED; PG8_LDA(At, 1, 0); PG8_STAGE(PG8_SA(0, 1), a2 + hA, voffA);
;             PG8_WAIT_V(8); PG8_WAIT_L(0); PG8_BAR; PG8_MMA(0, 0, At, B0); PG8_MMA(0, 1, At, B1); PG8_BAR; PG8_SCHED;
	v_mfma_f32_16x16x32_bf16 v[20:23], v[184:187], v[236:239], v[20:23]
	v_mfma_f32_16x16x32_bf16 v[20:23], v[208:211], v[240:243], v[20:23]
	s_setprio 0
	s_add_i32 s19, 0, 0x18000
	s_add_i32 s24, 0, 0x1c000
	v_add_u32_e32 v172, s19, v188
	v_add_u32_e32 v207, s24, v188
	ds_read_b128 v[136:139], v172
	ds_read_b128 v[140:143], v172 offset:1024
	ds_read_b128 v[144:147], v172 offset:2048
	ds_read_b128 v[172:175], v172 offset:3072
	ds_read_b128 v[176:179], v207
	ds_read_b128 v[180:183], v207 offset:1024
	ds_read_b128 v[184:187], v207 offset:2048
	ds_read_b128 v[208:211], v207 offset:3072
	s_add_u32 s10, s64, 0x160000
	s_addc_u32 s11, s65, 0
	s_mov_b32 m0, s76
	v_lshl_add_u64 v[248:249], s[10:11], 0, v[0:1]
	ds_read_b128 v[212:215], v197 offset:32768
	ds_read_b128 v[216:219], v197 offset:33792
	ds_read_b128 v[220:223], v197 offset:34816
	ds_read_b128 v[224:227], v197 offset:35840
	ds_read_b128 v[228:231], v197 offset:36864
	ds_read_b128 v[232:235], v197 offset:37888
	ds_read_b128 v[236:239], v197 offset:38912
	ds_read_b128 v[240:243], v197 offset:39936
	global_load_lds_dwordx4 v[248:249], off
	v_lshl_add_u64 v[248:249], s[10:11], 0, v[148:149]
	s_mov_b32 m0, s77
	s_nop 0
	global_load_lds_dwordx4 v[248:249], off
	s_waitcnt vmcnt(8)
	s_waitcnt lgkmcnt(0)
	s_barrier
	s_setprio 1
	s_waitcnt lgkmcnt(0)
	v_mfma_f32_16x16x32_bf16 v[16:19], v[136:139], v[212:215], v[16:19]
	v_mfma_f32_16x16x32_bf16 v[16:19], v[140:143], v[216:219], v[16:19]
	v_mfma_f32_16x16x32_bf16 v[12:15], v[144:147], v[212:215], v[12:15]
	v_mfma_f32_16x16x32_bf16 v[12:15], v[172:175], v[216:219], v[12:15]
	v_mfma_f32_16x16x32_bf16 v[56:59], v[136:139], v[220:223], v[56:59]
	v_mfma_f32_16x16x32_bf16 v[56:59], v[140:143], v[224:227], v[56:59]
	v_mfma_f32_16x16x32_bf16 v[52:55], v[144:147], v[220:223], v[52:55]
	v_mfma_f32_16x16x32_bf16 v[52:55], v[172:175], v[224:227], v[52:55]
	v_mfma_f32_16x16x32_bf16 v[88:91], v[136:139], v[228:231], v[88:91]
	v_mfma_f32_16x16x32_bf16 v[88:91], v[140:143], v[232:235], v[88:91]
	v_mfma_f32_16x16x32_bf16 v[76:79], v[144:147], v[228:231], v[76:79]
	v_mfma_f32_16x16x32_bf16 v[76:79], v[172:175], v[232:235], v[76:79]
	v_mfma_f32_16x16x32_bf16 v[112:115], v[136:139], v[236:239], v[112:115]
	v_mfma_f32_16x16x32_bf16 v[112:115], v[140:143], v[240:243], v[112:115]
	v_mfma_f32_16x16x32_bf16 v[108:111], v[144:147], v[236:239], v[108:111]
	v_mfma_f32_16x16x32_bf16 v[108:111], v[172:175], v[240:243], v[108:111]
	s_setprio 0
	s_setprio 1
	v_mfma_f32_16x16x32_bf16 v[8:11], v[176:179], v[212:215], v[8:11]
	v_mfma_f32_16x16x32_bf16 v[8:11], v[180:183], v[216:219], v[8:11]
	v_mfma_f32_16x16x32_bf16 v[4:7], v[184:187], v[212:215], v[4:7]
	v_mfma_f32_16x16x32_bf16 v[4:7], v[208:211], v[216:219], v[4:7]
	v_mfma_f32_16x16x32_bf16 v[40:43], v[176:179], v[220:223], v[40:43]
	v_mfma_f32_16x16x32_bf16 v[40:43], v[180:183], v[224:227], v[40:43]
	v_mfma_f32_16x16x32_bf16 v[36:39], v[184:187], v[220:223], v[36:39]
	v_mfma_f32_16x16x32_bf16 v[36:39], v[208:211], v[224:227], v[36:39]
	v_mfma_f32_16x16x32_bf16 v[64:67], v[176:179], v[228:231], v[64:67]
	v_mfma_f32_16x16x32_bf16 v[64:67], v[180:183], v[232:235], v[64:67]
	v_mfma_f32_16x16x32_bf16 v[60:63], v[184:187], v[228:231], v[60:63]
	v_mfma_f32_16x16x32_bf16 v[60:63], v[208:211], v[232:235], v[60:63]
	v_mfma_f32_16x16x32_bf16 v[96:99], v[176:179], v[236:239], v[96:99]
	v_mfma_f32_16x16x32_bf16 v[96:99], v[180:183], v[240:243], v[96:99]
	s_setprio 2
	s_barrier
; #define PG8_STAGE(bufoff, gbase, voff) do { _Pragma("unroll") for (int _i = 0; _i < 2; ++_i) \
;         __builtin_amdgcn_global_load_lds((const unsigned*)((const char*)(gbase) + (voff)[_i]), (LAS unsigned*)(lds + (bufoff) + ldsw + _i * 8192), 16, 0, 0); } while (0)
; #define PG8_LDA(dst, b, h) do { _Pragma("unroll") for (int m = 0; m < 4; ++m) _Pragma("unroll") for (int k = 0; k < 2; ++k) dst[m][k] = *(const LAS bf16x8*)(lds + PG8_SA(b, h) + aoff + m * 2048 + k * 1024); } while (0)
; #define PG8_MMA(ai, bj, At, Bt) do { __builtin_amdgcn_s_setprio(1); _Pragma("unroll") for (int m = 0; m < 4; ++m) _Pragma("unroll") for (int n = 0; n < 2; ++n) _Pragma("unroll") for (int k = 0; k < 2; ++k) \
;         acc[ai][bj][m][n] = __builtin_amdgcn_mfma_f32_16x16x32_bf16(Bt[n][k], At[m][k], acc[ai][bj][m][n], 0, 0, 0); __builtin_amdgcn_s_setprio(0); } while (0)
; #define PG8_WAIT_V(n) asm volatile("s_waitcnt vmcnt(" #n ")" ::: "memory")
; #define PG8_WAIT_L(n) asm volatile("s_waitcnt lgkmcnt(" #n ")" ::: "memory")
; #define PG8_BAR __builtin_amdgcn_s_barrier()
; #define PG8_SCHED __builtin_amdgcn_sched_barrier(0)
; template <class Epi, class Sched, bool ALIGN_EPI = true>
; __device__ __forceinline__ void gemm_phase(LAS unsigned char* lds, const Gemm g, const Sched& S, const Epi& E) {
;     ...
;             PG8_WAIT_V(8); PG8_WAIT_L(0); PG8_BAR; PG8_MMA(0, 0, At, B0); PG8_MMA(0, 1, At, B1); PG8_BAR; PG8_SCHED;
;             PG8_LDA(At, 1, 1); PG8_STAGE(PG8_SB(1, 0), b3, voffB); PG8_STAGE(PG8_SB(1, 1), b3 + hB, voffB); PG8_STAGE(PG8_SA(1, 0), a3, voffA);
;             PG8_WAIT_V(8); PG8_WAIT_L(0); PG8_BAR; PG8_MMA(1, 0, At, B0); PG8_MMA(1, 1, At, B1); PG8_BAR; PG8_SCHED;
	v_mfma_f32_16x16x32_bf16 v[92:95], v[184:187], v[236:239], v[92:95]
	v_mfma_f32_16x16x32_bf16 v[92:95], v[208:211], v[240:243], v[92:95]
	s_setprio 0
	s_add_i32 s10, s19, s66
	v_lshl_add_u64 v[160:161], v[160:161], 0, s[86:87]
	s_mov_b32 m0, s10
	ds_read_b128 v[212:215], v197 offset:49152
	ds_read_b128 v[216:219], v197 offset:50176
	ds_read_b128 v[220:223], v197 offset:51200
	ds_read_b128 v[224:227], v197 offset:52224
	ds_read_b128 v[228:231], v197 offset:53248
	ds_read_b128 v[232:235], v197 offset:54272
	ds_read_b128 v[236:239], v197 offset:55296
	ds_read_b128 v[240:243], v197 offset:56320
	global_load_lds_dwordx4 v[160:161], off
	s_add_i32 m0, s10, 0x2000
	s_add_u32 s10, s62, 0x160080
	v_lshl_add_u64 v[160:161], v[162:163], 0, s[86:87]
	s_addc_u32 s11, s63, 0
	s_add_i32 s19, s24, s66
	global_load_lds_dwordx4 v[160:161], off
	v_lshl_add_u64 v[160:161], s[10:11], 0, v[2:3]
	s_mov_b32 m0, s19
	s_nop 0
	global_load_lds_dwordx4 v[160:161], off
	v_lshl_add_u64 v[160:161], s[10:11], 0, v[150:151]
	s_add_i32 m0, s19, 0x2000
	s_nop 0
	global_load_lds_dwordx4 v[160:161], off
	v_lshl_add_u64 v[160:161], v[244:245], 0, s[86:87]
	s_mov_b32 m0, s80
	s_nop 0
	global_load_lds_dwordx4 v[160:161], off
	v_lshl_add_u64 v[160:161], v[246:247], 0, s[86:87]
	s_mov_b32 m0, s81
	s_nop 0
	global_load_lds_dwordx4 v[160:161], off
	s_waitcnt vmcnt(8)
	s_waitcnt lgkmcnt(0)
	s_barrier
	s_setprio 1
	s_waitcnt lgkmcnt(0)
	v_mfma_f32_16x16x32_bf16 v[128:131], v[136:139], v[212:215], v[128:131]
	v_mfma_f32_16x16x32_bf16 v[128:131], v[140:143], v[216:219], v[128:131]
	v_mfma_f32_16x16x32_bf16 v[124:127], v[144:147], v[212:215], v[124:127]
	v_mfma_f32_16x16x32_bf16 v[124:127], v[172:175], v[216:219], v[124:127]
	v_mfma_f32_16x16x32_bf16 v[104:107], v[136:139], v[220:223], v[104:107]
	v_mfma_f32_16x16x32_bf16 v[104:107], v[140:143], v[224:227], v[104:107]
	v_mfma_f32_16x16x32_bf16 v[100:103], v[144:147], v[220:223], v[100:103]
	v_mfma_f32_16x16x32_bf16 v[100:103], v[172:175], v[224:227], v[100:103]
	v_mfma_f32_16x16x32_bf16 v[72:75], v[136:139], v[228:231], v[72:75]
	v_mfma_f32_16x16x32_bf16 v[72:75], v[140:143], v[232:235], v[72:75]
	v_mfma_f32_16x16x32_bf16 v[68:71], v[144:147], v[228:231], v[68:71]
	v_mfma_f32_16x16x32_bf16 v[68:71], v[172:175], v[232:235], v[68:71]
	v_mfma_f32_16x16x32_bf16 v[32:35], v[136:139], v[236:239], v[32:35]
	v_mfma_f32_16x16x32_bf16 v[32:35], v[140:143], v[240:243], v[32:35]
	v_mfma_f32_16x16x32_bf16 v[28:31], v[144:147], v[236:239], v[28:31]
	v_mfma_f32_16x16x32_bf16 v[28:31], v[172:175], v[240:243], v[28:31]
	s_setprio 0
	s_setprio 1
	v_mfma_f32_16x16x32_bf16 v[120:123], v[176:179], v[212:215], v[120:123]
	v_mfma_f32_16x16x32_bf16 v[120:123], v[180:183], v[216:219], v[120:123]
	v_mfma_f32_16x16x32_bf16 v[116:119], v[184:187], v[212:215], v[116:119]
	v_mfma_f32_16x16x32_bf16 v[116:119], v[208:211], v[216:219], v[116:119]
	v_mfma_f32_16x16x32_bf16 v[84:87], v[176:179], v[220:223], v[84:87]
	v_mfma_f32_16x16x32_bf16 v[84:87], v[180:183], v[224:227], v[84:87]
	v_mfma_f32_16x16x32_bf16 v[80:83], v[184:187], v[220:223], v[80:83]
	v_mfma_f32_16x16x32_bf16 v[80:83], v[208:211], v[224:227], v[80:83]
	v_mfma_f32_16x16x32_bf16 v[48:51], v[176:179], v[228:231], v[48:51]
	v_mfma_f32_16x16x32_bf16 v[48:51], v[180:183], v[232:235], v[48:51]
	v_mfma_f32_16x16x32_bf16 v[44:47], v[184:187], v[228:231], v[44:47]
	v_mfma_f32_16x16x32_bf16 v[44:47], v[208:211], v[232:235], v[44:47]
	v_mfma_f32_16x16x32_bf16 v[24:27], v[176:179], v[236:239], v[24:27]
	v_mfma_f32_16x16x32_bf16 v[24:27], v[180:183], v[240:243], v[24:27]
	s_setprio 2
	s_barrier
	v_mfma_f32_16x16x32_bf16 v[20:23], v[184:187], v[236:239], v[20:23]
	v_mfma_f32_16x16x32_bf16 v[20:23], v[208:211], v[240:243], v[20:23]
	s_setprio 0
	s_add_i32 s18, s18, 2
	s_cmpk_gt_u32 s18, 0x55
	s_mov_b64 s[10:11], vcc
	s_cbranch_scc0 .LBB0_1111
